# v43: v37 + G3 and G5 tile loops restructured (next-tile prefetch before epilogue; hand-written gated-residual epilogues with batched loads and 16B stores)
# speedup vs baseline: 1.0589x; 1.0091x over previous
; DI int otid() { int t = threadIdx.x; asm volatile("" : "+v"(t)); return t; }
; DI unsigned pack2(float a, float b) { const hwf32x2 v = {a, b}; const hwbf16x2 r = __builtin_convertvector(v, hwbf16x2); return __builtin_bit_cast(unsigned, r); }
; template <class FL, class FS>
; DI void gemm8_tile(char* shmc, const bf16_t* __restrict__ A, const bf16_t* __restrict__ Bt, const int K, const int brow, const int bcol, FL fl, FS fs) {
;   constexpr int HT = 8192, HALF = 128;
;   bf16_t* shm = (bf16_t*)shmc;
;     ...
;   const int tidx = otid();
;   const int wid = tidx >> 6, lane = tidx & 63, wr = wid >> 2, wc = wid & 3, fr = lane & 15, fq = lane >> 4;
;   f32x4 acc[2][2][4][2];
; #pragma unroll
;   for (int a = 0; a < 2; ++a)
; #pragma unroll
;     for (int b = 0; b < 2; ++b)
; #pragma unroll
;       for (int m = 0; m < 4; ++m)
; #pragma unroll
;         for (int n = 0; n < 2; ++n) acc[a][b][m][n] = (f32x4){0.f, 0.f, 0.f, 0.f};
;   bf16x8 At[4][2], B0[2][2], B1[2][2];
;   const int nt = K / 64;
;   STAGE(SB(0, 0), Bt, bcol, 0); STAGE(SA(0, 0), A, brow, 0);
;   STAGE(SB(0, 1), Bt, bcol + HALF, 0); STAGE(SA(0, 1), A, brow + HALF, 0);
; DI void tile8_order(int L, int nM, int nN, int& pm, int& pn) {
;   const int t = tile_remap(L, nM * nN), nig = 8 * nN, gid = t / nig, fm = gid * 8, gsz = (nM - fm) < 8 ? (nM - fm) : 8;
;   pm = fm + ((t % nig) % gsz); pn = (t % nig) / gsz;
; }
; DI void st_bf4(bf16_t* p, float a, float b, float c, float d) { uint2 v; v.x = pack2(a, b); v.y = pack2(c, d); *(uint2*)p = v; }
; DI void ld_bf4(const bf16_t* p, float& a, float& b, float& c, float& d) {
;   const uint2 v = *(const uint2*)p; a = __uint_as_float(v.x << 16); b = __uint_as_float(v.x & 0xffff0000u); c = __uint_as_float(v.y << 16); d = __uint_as_float(v.y & 0xffff0000u);
; }
; template <class FL, class FS>
; DI void gemm_dispatch(const Sub& s, char* lds_all, const bf16_t* A, const bf16_t* Bt, const int nN256, FL fl, FS fs) {
;   if (!s.samp) {
;     const int nM = 256;
;     for (int L = blockIdx.x; L < nM * nN256; L += gridDim.x) {
;       int pm, pn; tile8_order(L, nM, nN256, pm, pn);
;       gemm8_tile(lds_all, A, Bt, D, pm * 256, pn * 256, fl, fs);
.LBB0_742:
	s_or_b64 exec, exec, s[4:5]
	v_cndmask_b32_e64 v1, 0, 1, s[6:7]
	v_cmp_ne_u32_e64 s[2:3], 1, v1
	s_mov_b32 s33, 0
	s_mov_b32 s0, 0
	s_waitcnt lgkmcnt(0)
	v_mov_b32_e32 v0, v182
	v_writelane_b32 v251, s2, 11
	s_andn2_b64 vcc, exec, s[6:7]
	s_barrier
	v_writelane_b32 v251, s3, 12
	s_cbranch_vccnz .LBB0_751
	s_ashr_i32 s1, s0, 31
	v_readlane_b32 s2, v251, 3
	v_readlane_b32 s3, v251, 4
	s_add_u32 s0, s2, s0
	s_addc_u32 s1, s3, s1
	s_load_dwordx4 s[8:11], s[0:1], 0xf0
	s_load_dwordx4 s[12:15], s[0:1], 0x0
	s_mov_b32 s46, 0x10000
	s_mov_b32 s47, 0x14000
	s_mov_b64 s[16:17], 0x80
	s_waitcnt lgkmcnt(0)
	s_add_u32 s48, s10, 0x1800000
	s_addc_u32 s49, s11, 0
	s_add_u32 s50, s10, 0x600000
	s_addc_u32 s51, s11, 0
	s_add_u32 s6, s10, 0x1080000
	s_addc_u32 s7, s11, 0
	s_mov_b32 s52, 0x18000
	s_mov_b32 s53, 0x1c000
	s_mov_b64 s[18:19], 0x1840080
	s_mov_b64 s[20:21], 0x600100
	s_mov_b64 s[22:23], 0x1800100
	s_mov_b64 s[24:25], 0x640100
	s_mov_b64 s[26:27], 0x1840100
	s_mov_b64 s[28:29], 0x600180
	s_mov_b64 s[30:31], 0x1800180
	s_mov_b64 s[34:35], 0x640180
	s_mov_b64 s[36:37], 0x100
	s_mov_b64 s[38:39], 0x780
	s_movk_i32 s54, 0x100
	s_movk_i32 s55, 0x3000
	s_mov_b64 s[40:41], 0x2000
	v_mov_b32_e32 v142, 1
	v_readlane_b32 s56, v251, 0
	s_mov_b32 s98, 0
	s_branch .LBB0_745
.LBB0_745:
	s_lshl_b32 s0, s56, 7
	s_and_b32 s0, s0, 0x380
	s_ashr_i32 s1, s56, 3
	s_add_i32 s0, s0, s1
	v_mov_b32_e32 v140, v182
	s_ashr_i32 s1, s0, 31
	s_lshr_b32 s1, s1, 27
	v_ashrrev_i32_e32 v200, 31, v140
	v_lshrrev_b32_e32 v200, 26, v200
	s_add_i32 s1, s0, s1
	v_add_u32_e32 v200, v140, v200
	s_and_b32 s2, s1, 0xffe0
	v_ashrrev_i32_e32 v201, 6, v200
	v_bfe_i32 v200, v140, 27, 1
	s_sub_i32 s0, s0, s2
	v_lshlrev_b32_e32 v146, 4, v140
	v_lshrrev_b32_e32 v200, 22, v200
	s_bfe_i32 s2, s0, 0x80000
	v_add_u32_e32 v200, v146, v200
	s_bfe_u32 s2, s2, 0x3000c
	v_and_b32_e32 v200, 0xfffffc00, v200
	s_add_i32 s2, s0, s2
	v_sub_u32_e32 v200, v146, v200
	s_bfe_i32 s3, s2, 0x80000
	s_and_b32 s2, s2, 0xf8
	v_lshrrev_b32_e32 v202, 4, v200
	s_sub_i32 s0, s0, s2
	v_bitop3_b32 v202, v202, v200, 32 bitop3:0x6c
	v_ashrrev_i32_e32 v200, 31, v200
	s_sext_i32_i8 s0, s0
	s_lshl_b32 s1, s1, 6
	v_lshrrev_b32_e32 v200, 26, v200
	s_sext_i32_i16 s3, s3
	s_and_b32 s1, s1, 0xfffff800
	s_lshl_b32 s0, s0, 8
	v_lshlrev_b32_e32 v203, 3, v201
	v_add_u32_e32 v200, v202, v200
	s_add_i32 s44, s0, s1
	s_lshl_b32 s0, s3, 5
	v_and_b32_e32 v203, -16, v203
	v_ashrrev_i32_e32 v204, 6, v200
	s_and_b32 s42, s0, 0xffffff00
	v_add_u32_e32 v200, v204, v203
	v_mul_i32_i24_e32 v203, 64, v204
	s_ashr_i32 s43, s42, 31
	v_lshlrev_b32_e32 v201, 5, v201
	v_sub_u32_e32 v202, v202, v203
	s_lshl_b64 s[0:1], s[42:43], 11
	v_and_b32_e32 v201, 32, v201
	v_ashrrev_i16_sdwa v202, v142, sext(v202) dst_sel:DWORD dst_unused:UNUSED_PAD src0_sel:DWORD src1_sel:BYTE_0
	s_add_u32 s2, s50, s0
	v_add_u32_sdwa v202, v201, sext(v202) dst_sel:DWORD dst_unused:UNUSED_PAD src0_sel:DWORD src1_sel:WORD_0
	v_ashrrev_i32_e32 v201, 31, v200
	s_addc_u32 s3, s51, s1
	v_lshlrev_b64 v[200:201], 11, v[200:201]
	v_ashrrev_i32_e32 v203, 31, v202
	v_lshl_add_u64 v[204:205], s[2:3], 0, v[200:201]
	v_lshlrev_b64 v[202:203], 1, v[202:203]
	v_add_u32_e32 v152, 0x2000, v146
	v_lshl_add_u64 v[208:209], v[204:205], 0, v[202:203]
	v_ashrrev_i32_e32 v204, 31, v152
	v_lshrrev_b32_e32 v204, 22, v204
	v_add_u32_e32 v204, v152, v204
	v_ashrrev_i32_e32 v205, 10, v204
	v_mul_i32_i24_e32 v204, 0x400, v205
	v_sub_u32_e32 v204, v152, v204
	v_lshrrev_b32_e32 v206, 4, v204
	v_bitop3_b32 v206, v206, v204, 32 bitop3:0x6c
	v_ashrrev_i32_e32 v207, 31, v206
	v_lshrrev_b32_e32 v207, 26, v207
	v_add_u32_e32 v207, v206, v207
	v_lshlrev_b32_e32 v204, 3, v205
	v_ashrrev_i32_e32 v210, 6, v207
	v_and_b32_e32 v207, 0xc0, v207
	v_and_b32_e32 v204, -16, v204
	v_lshlrev_b32_e32 v205, 5, v205
	v_sub_u32_e32 v206, v206, v207
	v_add_u32_e32 v204, v210, v204
	v_and_b32_e32 v205, 32, v205
	v_ashrrev_i16_sdwa v206, v142, sext(v206) dst_sel:DWORD dst_unused:UNUSED_PAD src0_sel:DWORD src1_sel:BYTE_0
	v_add_u32_e32 v148, 0x10000, v146
	v_add_u32_sdwa v206, v205, sext(v206) dst_sel:DWORD dst_unused:UNUSED_PAD src0_sel:DWORD src1_sel:WORD_0
	v_ashrrev_i32_e32 v205, 31, v204
	v_readfirstlane_b32 s4, v148
	v_lshlrev_b64 v[204:205], 11, v[204:205]
	v_add_u32_e32 v154, 0x12000, v146
	s_mov_b32 m0, s4
	v_lshl_add_u64 v[210:211], s[2:3], 0, v[204:205]
	v_readfirstlane_b32 s2, v154
	s_ashr_i32 s45, s44, 31
	global_load_lds_dwordx4 v[208:209], off
	s_mov_b32 m0, s2
	s_lshl_b64 s[2:3], s[44:45], 11
	v_ashrrev_i32_e32 v207, 31, v206
	s_add_u32 s4, s48, s2
	v_lshlrev_b64 v[206:207], 1, v[206:207]
	s_addc_u32 s5, s49, s3
	v_lshl_add_u64 v[210:211], v[210:211], 0, v[206:207]
	v_lshl_add_u64 v[212:213], s[4:5], 0, v[200:201]
	v_readfirstlane_b32 s43, v146
	global_load_lds_dwordx4 v[210:211], off
; #define STAGE(P, BASE, br, kt) do { const long _g = (long)(br) * K + (long)(kt) * 64; \
;     _Pragma("unroll") for (int _i = 0; _i < 2; ++_i) { const int _b = tidx * 16 + _i * 8192; int _r, _c; stage_rc8(_b, _r, _c); \
;       __builtin_amdgcn_global_load_lds((const unsigned*)(BASE + _g + (long)_r * K + _c), (LAS unsigned*)((LAS char*)(P) + _b), 16, 0, 0); } } while (0)
; #define LDA(dst, b, h) _Pragma("unroll") for (int m = 0; m < 4; ++m) _Pragma("unroll") for (int k = 0; k < 2; ++k) \
;     dst[m][k] = *reinterpret_cast<const bf16x8*>((const char*)SA(b, h) + lds_byte8(wr * 64 + m * 16 + fr, k * 32 + fq * 8))
; #define LDB(dst, b, h) _Pragma("unroll") for (int n = 0; n < 2; ++n) _Pragma("unroll") for (int k = 0; k < 2; ++k) \
;     dst[n][k] = *reinterpret_cast<const bf16x8*>((const char*)SB(b, h) + lds_byte8(wc * 32 + n * 16 + fr, k * 32 + fq * 8))
; #define MMA(ai, bj, At_, Bt_) do { __builtin_amdgcn_s_setprio(1); \
;     _Pragma("unroll") for (int m = 0; m < 4; ++m) _Pragma("unroll") for (int n = 0; n < 2; ++n) _Pragma("unroll") for (int k = 0; k < 2; ++k) \
;       acc[ai][bj][m][n] = MFMA16(Bt_[n][k], At_[m][k], acc[ai][bj][m][n]); \
;     __builtin_amdgcn_s_setprio(0); } while (0)
; #define WAIT_V(n) asm volatile("s_waitcnt vmcnt(" #n ")" ::: "memory")
; #define WAIT_L(n) asm volatile("s_waitcnt lgkmcnt(" #n ")" ::: "memory")
; #define BAR __builtin_amdgcn_s_barrier()
; #define SCHED __builtin_amdgcn_sched_barrier(0)
; template <class FL, class FS>
; DI void gemm8_tile(char* shmc, const bf16_t* __restrict__ A, const bf16_t* __restrict__ Bt, const int K, const int brow, const int bcol, FL fl, FS fs) {
;     ...
;   STAGE(SB(0, 0), Bt, bcol, 0); STAGE(SA(0, 0), A, brow, 0);
;   STAGE(SB(0, 1), Bt, bcol + HALF, 0); STAGE(SA(0, 1), A, brow + HALF, 0);
;   if (wr == 1) BAR;
;   WAIT_V(4); BAR;
;   STAGE(SB(1, 0), Bt, bcol, 1); STAGE(SA(1, 0), A, brow, 1); STAGE(SB(1, 1), Bt, bcol + HALF, 1);
;   WAIT_V(6); BAR;
;   for (int t = 0; t < nt - 2; t += 2) {
;     LDB(B0, 0, 0); SCHED; LDA(At, 0, 0); STAGE(SA(1, 1), A, brow + HALF, t + 1);
;     WAIT_L(8); BAR; WAIT_L(0); MMA(0, 0, At, B0); BAR; SCHED;
	v_lshl_add_u64 v[212:213], v[212:213], 0, v[202:203]
	s_mov_b32 m0, s43
	v_lshl_add_u64 v[214:215], s[4:5], 0, v[204:205]
	v_readfirstlane_b32 s4, v152
	global_load_lds_dwordx4 v[212:213], off
	s_mov_b32 m0, s4
	s_or_b32 s4, s42, 0x80
	s_ashr_i32 s5, s4, 31
	s_lshl_b64 s[4:5], s[4:5], 11
	s_add_u32 s4, s50, s4
	s_addc_u32 s5, s51, s5
	v_add_u32_e32 v156, 0x14000, v146
	v_lshl_add_u64 v[214:215], v[214:215], 0, v[206:207]
	v_lshl_add_u64 v[216:217], s[4:5], 0, v[200:201]
	v_readfirstlane_b32 s43, v156
	v_add_u32_e32 v157, 0x16000, v146
	global_load_lds_dwordx4 v[214:215], off
	v_lshl_add_u64 v[216:217], v[216:217], 0, v[202:203]
	s_mov_b32 m0, s43
	v_lshl_add_u64 v[218:219], s[4:5], 0, v[204:205]
	v_readfirstlane_b32 s4, v157
	global_load_lds_dwordx4 v[216:217], off
	s_mov_b32 m0, s4
	s_or_b32 s4, s44, 0x80
	s_ashr_i32 s5, s4, 31
	s_lshl_b64 s[4:5], s[4:5], 11
	s_add_u32 s4, s48, s4
	s_addc_u32 s5, s49, s5
	v_add_u32_e32 v158, 0x4000, v146
	v_lshl_add_u64 v[218:219], v[218:219], 0, v[206:207]
	v_lshl_add_u64 v[220:221], s[4:5], 0, v[200:201]
	v_readfirstlane_b32 s43, v158
	v_add_u32_e32 v159, 0x6000, v146
	global_load_lds_dwordx4 v[218:219], off
	v_lshl_add_u64 v[128:129], v[220:221], 0, v[202:203]
	s_mov_b32 m0, s43
	v_lshl_add_u64 v[220:221], s[4:5], 0, v[204:205]
	v_readfirstlane_b32 s4, v159
	global_load_lds_dwordx4 v[128:129], off
	v_lshl_add_u64 v[130:131], v[220:221], 0, v[206:207]
	s_mov_b32 m0, s4
	v_ashrrev_i32_e32 v220, 8, v140
	global_load_lds_dwordx4 v[130:131], off
	v_add_u32_e32 v160, 0x18000, v146
	v_add_u32_e32 v161, 0x1a000, v146
	v_readfirstlane_b32 s4, v160
	v_lshl_add_u64 v[208:209], v[208:209], 0, s[16:17]
	s_mov_b32 m0, s4
	v_readfirstlane_b32 s4, v161
	v_add_u32_e32 v162, 0x8000, v146
	global_load_lds_dwordx4 v[208:209], off
	v_lshl_add_u64 v[208:209], v[210:211], 0, s[16:17]
	s_mov_b32 m0, s4
	v_readfirstlane_b32 s4, v162
	v_add_u32_e32 v163, 0xa000, v146
	global_load_lds_dwordx4 v[208:209], off
	v_lshl_add_u64 v[208:209], v[212:213], 0, s[16:17]
	s_mov_b32 m0, s4
	v_readfirstlane_b32 s4, v163
	v_add_u32_e32 v164, 0x1c000, v146
	global_load_lds_dwordx4 v[208:209], off
	v_lshl_add_u64 v[208:209], v[214:215], 0, s[16:17]
	s_mov_b32 m0, s4
	v_readfirstlane_b32 s4, v164
	v_add_u32_e32 v166, 0x1e000, v146
	global_load_lds_dwordx4 v[208:209], off
	v_lshl_add_u64 v[208:209], v[216:217], 0, s[16:17]
	s_mov_b32 m0, s4
	v_readfirstlane_b32 s4, v166
	global_load_lds_dwordx4 v[208:209], off
	v_lshl_add_u64 v[208:209], v[218:219], 0, s[16:17]
	s_mov_b32 m0, s4
	v_and_b32_e32 v144, 15, v140
	global_load_lds_dwordx4 v[208:209], off
	v_bfe_u32 v143, v140, 4, 2
	v_lshlrev_b32_e32 v212, 2, v140
	v_lshlrev_b32_e32 v208, 4, v143
	v_lshlrev_b32_e32 v209, 6, v144
	v_and_b32_e32 v212, 32, v212
	v_or_b32_e32 v211, v208, v209
	v_bitop3_b32 v213, v208, v212, v209 bitop3:0x36
	v_lshlrev_b32_e32 v209, 6, v140
	v_and_b32_e32 v209, 0x3c0, v209
	v_bitop3_b32 v214, v211, s46, v212 bitop3:0xde
	v_bitop3_b32 v215, v211, s47, v212 bitop3:0xde
	v_bitop3_b32 v216, v211, s52, v212 bitop3:0xde
	v_bitop3_b32 v211, v211, s53, v212 bitop3:0xde
	v_bitop3_b32 v212, v209, v212, v208 bitop3:0x36
	v_lshl_add_u64 v[208:209], s[0:1], 0, v[200:201]
	v_lshl_add_u64 v[200:201], s[2:3], 0, v[200:201]
	v_bfe_u32 v141, v140, 6, 2
	v_lshlrev_b32_e32 v217, 13, v220
	v_lshl_add_u64 v[136:137], v[200:201], 0, v[202:203]
	v_lshl_add_u64 v[200:201], s[2:3], 0, v[204:205]
	v_lshlrev_b32_e32 v210, 12, v141
	v_lshlrev_b32_e32 v145, 6, v220
	v_or_b32_e32 v218, 0x800, v217
	v_or_b32_e32 v219, 0x1000, v217
	v_or_b32_e32 v220, 0x1800, v217
	v_lshl_add_u64 v[132:133], v[208:209], 0, v[202:203]
	v_lshl_add_u64 v[208:209], s[0:1], 0, v[204:205]
	v_lshl_add_u64 v[138:139], v[200:201], 0, v[206:207]
	v_lshl_add_u64 v[134:135], v[208:209], 0, v[206:207]
	v_add_u32_e32 v169, v214, v210
	v_add_u32_e32 v151, v213, v217
	v_add_u32_e32 v150, v212, v218
	v_add_u32_e32 v149, v212, v219
	v_add_u32_e32 v147, v212, v220
	v_add_u32_e32 v168, 0xc000, v146
	v_add_u32_e32 v167, 0xe000, v146
	v_add_u32_e32 v165, v215, v210
	v_add_u32_e32 v155, v216, v210
	v_add_u32_e32 v153, v211, v210
	v_lshl_add_u64 v[222:223], s[10:11], 0, v[136:137]
	v_readfirstlane_b32 s1, v168
	v_lshl_add_u64 v[222:223], v[222:223], 0, s[18:19]
	s_mov_b32 m0, s1
	v_lshl_add_u64 v[224:225], s[10:11], 0, v[138:139]
	v_readfirstlane_b32 s1, v167
	global_load_lds_dwordx4 v[222:223], off
	v_lshl_add_u64 v[224:225], v[224:225], 0, s[18:19]
	s_mov_b32 m0, s1
	s_nop 0
	global_load_lds_dwordx4 v[224:225], off
	s_cmp_eq_u32 s98, 0
	s_cbranch_scc1 .Lg3_first
	s_mov_b32 s101, 0
	s_branch .Lg3_epi
.Lg3_epi_ret0:
	v_lshrrev_b32_e32 v222, 8, v182
	v_cmp_eq_u32_e32 vcc, 1, v222
	s_and_saveexec_b64 s[4:5], vcc
	s_cbranch_execz .Lg3_nba
	s_barrier
.Lg3_nba:
	s_or_b64 exec, exec, s[4:5]
	s_waitcnt vmcnt(28)
	s_barrier
	s_waitcnt vmcnt(24)
	s_branch .Lg3_zero

; #define STAGE(P, BASE, br, kt) do { const long _g = (long)(br) * K + (long)(kt) * 64; \
;     _Pragma("unroll") for (int _i = 0; _i < 2; ++_i) { const int _b = tidx * 16 + _i * 8192; int _r, _c; stage_rc8(_b, _r, _c); \
;       __builtin_amdgcn_global_load_lds((const unsigned*)(BASE + _g + (long)_r * K + _c), (LAS unsigned*)((LAS char*)(P) + _b), 16, 0, 0); } } while (0)
; #define WAIT_V(n) asm volatile("s_waitcnt vmcnt(" #n ")" ::: "memory")
; #define BAR __builtin_amdgcn_s_barrier()
; template <class FL, class FS>
; DI void gemm8_tile(char* shmc, const bf16_t* __restrict__ A, const bf16_t* __restrict__ Bt, const int K, const int brow, const int bcol, FL fl, FS fs) {
;     ...
;   if (wr == 1) BAR;
;   WAIT_V(4); BAR;
;   STAGE(SB(1, 0), Bt, bcol, 1); STAGE(SA(1, 0), A, brow, 1); STAGE(SB(1, 1), Bt, bcol + HALF, 1);
;   WAIT_V(6); BAR;
.Lg3_nbb:
	s_or_b64 exec, exec, s[4:5]
	s_waitcnt vmcnt(12)
	s_barrier
	s_waitcnt vmcnt(8)

; #define STAGE(P, BASE, br, kt) do { const long _g = (long)(br) * K + (long)(kt) * 64; \
;     _Pragma("unroll") for (int _i = 0; _i < 2; ++_i) { const int _b = tidx * 16 + _i * 8192; int _r, _c; stage_rc8(_b, _r, _c); \
;       __builtin_amdgcn_global_load_lds((const unsigned*)(BASE + _g + (long)_r * K + _c), (LAS unsigned*)((LAS char*)(P) + _b), 16, 0, 0); } } while (0)
; #define LDA(dst, b, h) _Pragma("unroll") for (int m = 0; m < 4; ++m) _Pragma("unroll") for (int k = 0; k < 2; ++k) \
;     dst[m][k] = *reinterpret_cast<const bf16x8*>((const char*)SA(b, h) + lds_byte8(wr * 64 + m * 16 + fr, k * 32 + fq * 8))
; #define LDB(dst, b, h) _Pragma("unroll") for (int n = 0; n < 2; ++n) _Pragma("unroll") for (int k = 0; k < 2; ++k) \
;     dst[n][k] = *reinterpret_cast<const bf16x8*>((const char*)SB(b, h) + lds_byte8(wc * 32 + n * 16 + fr, k * 32 + fq * 8))
; #define MMA(ai, bj, At_, Bt_) do { __builtin_amdgcn_s_setprio(1); \
;     _Pragma("unroll") for (int m = 0; m < 4; ++m) _Pragma("unroll") for (int n = 0; n < 2; ++n) _Pragma("unroll") for (int k = 0; k < 2; ++k) \
;       acc[ai][bj][m][n] = MFMA16(Bt_[n][k], At_[m][k], acc[ai][bj][m][n]); \
;     __builtin_amdgcn_s_setprio(0); } while (0)
; #define WAIT_V(n) asm volatile("s_waitcnt vmcnt(" #n ")" ::: "memory")
; #define WAIT_L(n) asm volatile("s_waitcnt lgkmcnt(" #n ")" ::: "memory")
; #define BAR __builtin_amdgcn_s_barrier()
; #define SCHED __builtin_amdgcn_sched_barrier(0)
; template <class FL, class FS>
; DI void gemm8_tile(char* shmc, const bf16_t* __restrict__ A, const bf16_t* __restrict__ Bt, const int K, const int brow, const int bcol, FL fl, FS fs) {
;     ...
;   for (int t = 0; t < nt - 2; t += 2) {
;     LDB(B0, 0, 0); SCHED; LDA(At, 0, 0); STAGE(SA(1, 1), A, brow + HALF, t + 1);
;     WAIT_L(8); BAR; WAIT_L(0); MMA(0, 0, At, B0); BAR; SCHED;
;     LDB(B1, 0, 1); STAGE(SB(0, 0), Bt, bcol, t + 2);
;     BAR; WAIT_L(0); MMA(0, 1, At, B1); BAR;
;     LDA(At, 0, 1); STAGE(SA(0, 0), A, brow, t + 2);
;     BAR; WAIT_L(0); MMA(1, 0, At, B0); BAR; SCHED;
;     STAGE(SB(0, 1), Bt, bcol + HALF, t + 2);
;     WAIT_V(6); BAR; MMA(1, 1, At, B1); BAR;
.LBB0_748:
	ds_read_b128 v[170:173], v169
	ds_read_b128 v[174:177], v169 offset:1024
	ds_read_b128 v[178:181], v169 offset:2048
	ds_read_b128 v[184:187], v169 offset:3072
	v_lshl_add_u64 v[236:237], s[10:11], 0, v[136:137]
	v_readfirstlane_b32 s1, v168
	v_lshl_add_u64 v[220:221], v[236:237], 0, s[18:19]
	s_mov_b32 m0, s1
	v_lshl_add_u64 v[238:239], s[10:11], 0, v[138:139]
	v_readfirstlane_b32 s1, v167
	ds_read_b128 v[188:191], v151
	ds_read_b128 v[192:195], v151 offset:1024
	ds_read_b128 v[196:199], v150
	ds_read_b128 v[200:203], v150 offset:1024
	ds_read_b128 v[204:207], v149
	ds_read_b128 v[208:211], v149 offset:1024
	ds_read_b128 v[212:215], v147
	ds_read_b128 v[216:219], v147 offset:1024
	s_cmp_eq_u32 s0, -2
	s_cbranch_scc1 .Lg3_p1skip
	global_load_lds_dwordx4 v[220:221], off
	v_lshl_add_u64 v[220:221], v[238:239], 0, s[18:19]
	s_mov_b32 m0, s1
	s_nop 0
	global_load_lds_dwordx4 v[220:221], off
.Lg3_p1skip:
	s_waitcnt lgkmcnt(8)
	s_barrier
	s_waitcnt lgkmcnt(0)
	s_setprio 1
	s_waitcnt lgkmcnt(0)
	v_mfma_f32_16x16x32_bf16 v[124:127], v[170:173], v[188:191], v[124:127]
	v_mfma_f32_16x16x32_bf16 v[120:123], v[178:181], v[188:191], v[120:123]
	v_mfma_f32_16x16x32_bf16 v[116:119], v[170:173], v[196:199], v[116:119]
	v_mfma_f32_16x16x32_bf16 v[112:115], v[178:181], v[196:199], v[112:115]
	v_mfma_f32_16x16x32_bf16 v[108:111], v[170:173], v[204:207], v[108:111]
	v_mfma_f32_16x16x32_bf16 v[104:107], v[178:181], v[204:207], v[104:107]
	v_mfma_f32_16x16x32_bf16 v[100:103], v[170:173], v[212:215], v[100:103]
	v_mfma_f32_16x16x32_bf16 v[96:99], v[178:181], v[212:215], v[96:99]
	v_mfma_f32_16x16x32_bf16 v[124:127], v[174:177], v[192:195], v[124:127]
	v_mfma_f32_16x16x32_bf16 v[120:123], v[184:187], v[192:195], v[120:123]
	v_mfma_f32_16x16x32_bf16 v[116:119], v[174:177], v[200:203], v[116:119]
	v_mfma_f32_16x16x32_bf16 v[112:115], v[184:187], v[200:203], v[112:115]
	v_mfma_f32_16x16x32_bf16 v[108:111], v[174:177], v[208:211], v[108:111]
	v_mfma_f32_16x16x32_bf16 v[104:107], v[184:187], v[208:211], v[104:107]
	v_mfma_f32_16x16x32_bf16 v[100:103], v[174:177], v[216:219], v[100:103]
	v_mfma_f32_16x16x32_bf16 v[96:99], v[184:187], v[216:219], v[96:99]
	s_setprio 0
	s_barrier
	v_lshl_add_u64 v[240:241], s[10:11], 0, v[132:133]
	v_readfirstlane_b32 s1, v148
	v_lshl_add_u64 v[242:243], v[240:241], 0, s[20:21]
	s_mov_b32 m0, s1
	ds_read_b128 v[220:223], v165
	ds_read_b128 v[224:227], v165 offset:1024
	ds_read_b128 v[228:231], v165 offset:2048
	ds_read_b128 v[232:235], v165 offset:3072
	global_load_lds_dwordx4 v[242:243], off
	v_lshl_add_u64 v[242:243], s[10:11], 0, v[134:135]
	v_readfirstlane_b32 s1, v154
	v_lshl_add_u64 v[244:245], v[242:243], 0, s[20:21]
	s_mov_b32 m0, s1
	s_nop 0
	global_load_lds_dwordx4 v[244:245], off
	s_barrier
	s_waitcnt lgkmcnt(0)
	s_setprio 1
	s_waitcnt lgkmcnt(0)
	v_mfma_f32_16x16x32_bf16 v[92:95], v[220:223], v[188:191], v[92:95]
	v_mfma_f32_16x16x32_bf16 v[88:91], v[228:231], v[188:191], v[88:91]
	v_mfma_f32_16x16x32_bf16 v[84:87], v[220:223], v[196:199], v[84:87]
	v_mfma_f32_16x16x32_bf16 v[80:83], v[228:231], v[196:199], v[80:83]
	v_mfma_f32_16x16x32_bf16 v[76:79], v[220:223], v[204:207], v[76:79]
	v_mfma_f32_16x16x32_bf16 v[72:75], v[228:231], v[204:207], v[72:75]
	v_mfma_f32_16x16x32_bf16 v[68:71], v[220:223], v[212:215], v[68:71]
	v_mfma_f32_16x16x32_bf16 v[64:67], v[228:231], v[212:215], v[64:67]
	v_mfma_f32_16x16x32_bf16 v[92:95], v[224:227], v[192:195], v[92:95]
	v_mfma_f32_16x16x32_bf16 v[88:91], v[232:235], v[192:195], v[88:91]
	v_mfma_f32_16x16x32_bf16 v[84:87], v[224:227], v[200:203], v[84:87]
	v_mfma_f32_16x16x32_bf16 v[80:83], v[232:235], v[200:203], v[80:83]
	v_mfma_f32_16x16x32_bf16 v[76:79], v[224:227], v[208:211], v[76:79]
	v_mfma_f32_16x16x32_bf16 v[72:75], v[232:235], v[208:211], v[72:75]
	v_mfma_f32_16x16x32_bf16 v[68:71], v[224:227], v[216:219], v[68:71]
	v_mfma_f32_16x16x32_bf16 v[64:67], v[232:235], v[216:219], v[64:67]
	s_setprio 0
	v_readfirstlane_b32 s1, v146
	v_lshl_add_u64 v[244:245], v[236:237], 0, s[22:23]
	s_mov_b32 m0, s1
	v_readfirstlane_b32 s1, v152
	s_barrier
	ds_read_b128 v[188:191], v151 offset:16384
	ds_read_b128 v[192:195], v151 offset:17408
	ds_read_b128 v[196:199], v150 offset:16384
	ds_read_b128 v[200:203], v150 offset:17408
	ds_read_b128 v[204:207], v149 offset:16384
	ds_read_b128 v[208:211], v149 offset:17408
	ds_read_b128 v[212:215], v147 offset:16384
	ds_read_b128 v[216:219], v147 offset:17408
	global_load_lds_dwordx4 v[244:245], off
	v_lshl_add_u64 v[244:245], v[238:239], 0, s[22:23]
	s_mov_b32 m0, s1
	s_nop 0
	global_load_lds_dwordx4 v[244:245], off
	s_barrier
	s_waitcnt lgkmcnt(0)
	s_setprio 1
	s_waitcnt lgkmcnt(0)
	v_mfma_f32_16x16x32_bf16 v[60:63], v[170:173], v[188:191], v[60:63]
	v_mfma_f32_16x16x32_bf16 v[56:59], v[178:181], v[188:191], v[56:59]
	v_mfma_f32_16x16x32_bf16 v[52:55], v[170:173], v[196:199], v[52:55]
	v_mfma_f32_16x16x32_bf16 v[48:51], v[178:181], v[196:199], v[48:51]
	v_mfma_f32_16x16x32_bf16 v[44:47], v[170:173], v[204:207], v[44:47]
	v_mfma_f32_16x16x32_bf16 v[40:43], v[178:181], v[204:207], v[40:43]
	v_mfma_f32_16x16x32_bf16 v[36:39], v[170:173], v[212:215], v[36:39]
	v_mfma_f32_16x16x32_bf16 v[32:35], v[178:181], v[212:215], v[32:35]
	v_mfma_f32_16x16x32_bf16 v[60:63], v[174:177], v[192:195], v[60:63]
	v_mfma_f32_16x16x32_bf16 v[56:59], v[184:187], v[192:195], v[56:59]
	v_mfma_f32_16x16x32_bf16 v[52:55], v[174:177], v[200:203], v[52:55]
	v_mfma_f32_16x16x32_bf16 v[48:51], v[184:187], v[200:203], v[48:51]
	v_mfma_f32_16x16x32_bf16 v[44:47], v[174:177], v[208:211], v[44:47]
	v_mfma_f32_16x16x32_bf16 v[40:43], v[184:187], v[208:211], v[40:43]
	v_mfma_f32_16x16x32_bf16 v[36:39], v[174:177], v[216:219], v[36:39]
	v_mfma_f32_16x16x32_bf16 v[32:35], v[184:187], v[216:219], v[32:35]
	s_setprio 0
	s_barrier
	v_readfirstlane_b32 s1, v156
	v_lshl_add_u64 v[170:171], v[240:241], 0, s[24:25]
	s_mov_b32 m0, s1
	v_readfirstlane_b32 s1, v157
	global_load_lds_dwordx4 v[170:171], off
	v_lshl_add_u64 v[170:171], v[242:243], 0, s[24:25]
	s_mov_b32 m0, s1
	s_nop 0
	global_load_lds_dwordx4 v[170:171], off
	s_cmp_eq_u32 s0, -2
	s_cselect_b32 s101, s98, 0
	s_cmp_lg_u32 s101, 0
	s_cbranch_scc1 .Lg3_w22
	s_waitcnt vmcnt(6)
; #define STAGE(P, BASE, br, kt) do { const long _g = (long)(br) * K + (long)(kt) * 64; \
;     _Pragma("unroll") for (int _i = 0; _i < 2; ++_i) { const int _b = tidx * 16 + _i * 8192; int _r, _c; stage_rc8(_b, _r, _c); \
;       __builtin_amdgcn_global_load_lds((const unsigned*)(BASE + _g + (long)_r * K + _c), (LAS unsigned*)((LAS char*)(P) + _b), 16, 0, 0); } } while (0)
; #define LDA(dst, b, h) _Pragma("unroll") for (int m = 0; m < 4; ++m) _Pragma("unroll") for (int k = 0; k < 2; ++k) \
;     dst[m][k] = *reinterpret_cast<const bf16x8*>((const char*)SA(b, h) + lds_byte8(wr * 64 + m * 16 + fr, k * 32 + fq * 8))
; #define LDB(dst, b, h) _Pragma("unroll") for (int n = 0; n < 2; ++n) _Pragma("unroll") for (int k = 0; k < 2; ++k) \
;     dst[n][k] = *reinterpret_cast<const bf16x8*>((const char*)SB(b, h) + lds_byte8(wc * 32 + n * 16 + fr, k * 32 + fq * 8))
; #define MMA(ai, bj, At_, Bt_) do { __builtin_amdgcn_s_setprio(1); \
;     _Pragma("unroll") for (int m = 0; m < 4; ++m) _Pragma("unroll") for (int n = 0; n < 2; ++n) _Pragma("unroll") for (int k = 0; k < 2; ++k) \
;       acc[ai][bj][m][n] = MFMA16(Bt_[n][k], At_[m][k], acc[ai][bj][m][n]); \
;     __builtin_amdgcn_s_setprio(0); } while (0)
; #define WAIT_V(n) asm volatile("s_waitcnt vmcnt(" #n ")" ::: "memory")
; #define WAIT_L(n) asm volatile("s_waitcnt lgkmcnt(" #n ")" ::: "memory")
; #define BAR __builtin_amdgcn_s_barrier()
; #define SCHED __builtin_amdgcn_sched_barrier(0)
; template <class FL, class FS>
; DI void gemm8_tile(char* shmc, const bf16_t* __restrict__ A, const bf16_t* __restrict__ Bt, const int K, const int brow, const int bcol, FL fl, FS fs) {
;     ...
;     BAR; WAIT_L(0); MMA(1, 0, At, B0); BAR; SCHED;
;     STAGE(SB(0, 1), Bt, bcol + HALF, t + 2);
;     WAIT_V(6); BAR; MMA(1, 1, At, B1); BAR;
;     LDB(B0, 1, 0); SCHED; LDA(At, 1, 0); STAGE(SA(0, 1), A, brow + HALF, t + 2);
;     WAIT_L(8); BAR; WAIT_L(0); MMA(0, 0, At, B0); BAR; SCHED;
;     LDB(B1, 1, 1); STAGE(SB(1, 0), Bt, bcol, t + 3);
;     BAR; WAIT_L(0); MMA(0, 1, At, B1); BAR;
;     LDA(At, 1, 1); STAGE(SA(1, 0), A, brow, t + 3);
;     BAR; WAIT_L(0); MMA(1, 0, At, B0); BAR; SCHED;
;     STAGE(SB(1, 1), Bt, bcol + HALF, t + 3);
;     WAIT_V(6); BAR; MMA(1, 1, At, B1); BAR;
.Lg3_wd:
	s_barrier
	s_setprio 1
	v_mfma_f32_16x16x32_bf16 v[28:31], v[220:223], v[188:191], v[28:31]
	v_mfma_f32_16x16x32_bf16 v[24:27], v[228:231], v[188:191], v[24:27]
	v_mfma_f32_16x16x32_bf16 v[20:23], v[220:223], v[196:199], v[20:23]
	v_mfma_f32_16x16x32_bf16 v[16:19], v[228:231], v[196:199], v[16:19]
	v_mfma_f32_16x16x32_bf16 v[12:15], v[220:223], v[204:207], v[12:15]
	v_mfma_f32_16x16x32_bf16 v[8:11], v[228:231], v[204:207], v[8:11]
	v_mfma_f32_16x16x32_bf16 v[4:7], v[220:223], v[212:215], v[4:7]
	v_mfma_f32_16x16x32_bf16 v[0:3], v[228:231], v[212:215], v[0:3]
	v_mfma_f32_16x16x32_bf16 v[28:31], v[224:227], v[192:195], v[28:31]
	v_mfma_f32_16x16x32_bf16 v[24:27], v[232:235], v[192:195], v[24:27]
	v_mfma_f32_16x16x32_bf16 v[20:23], v[224:227], v[200:203], v[20:23]
	v_mfma_f32_16x16x32_bf16 v[16:19], v[232:235], v[200:203], v[16:19]
	v_mfma_f32_16x16x32_bf16 v[12:15], v[224:227], v[208:211], v[12:15]
	v_mfma_f32_16x16x32_bf16 v[8:11], v[232:235], v[208:211], v[8:11]
	v_mfma_f32_16x16x32_bf16 v[4:7], v[224:227], v[216:219], v[4:7]
	v_mfma_f32_16x16x32_bf16 v[0:3], v[232:235], v[216:219], v[0:3]
	s_setprio 0
	s_barrier
	ds_read_b128 v[170:173], v155
	ds_read_b128 v[174:177], v155 offset:1024
	ds_read_b128 v[178:181], v155 offset:2048
	ds_read_b128 v[184:187], v155 offset:3072
	v_readfirstlane_b32 s1, v158
	v_lshl_add_u64 v[220:221], v[236:237], 0, s[26:27]
	s_mov_b32 m0, s1
	v_readfirstlane_b32 s1, v159
	ds_read_b128 v[188:191], v151 offset:32768
	ds_read_b128 v[192:195], v151 offset:33792
	ds_read_b128 v[196:199], v150 offset:32768
	ds_read_b128 v[200:203], v150 offset:33792
	ds_read_b128 v[204:207], v149 offset:32768
	ds_read_b128 v[208:211], v149 offset:33792
	ds_read_b128 v[212:215], v147 offset:32768
	ds_read_b128 v[216:219], v147 offset:33792
	global_load_lds_dwordx4 v[220:221], off
	v_lshl_add_u64 v[220:221], v[238:239], 0, s[26:27]
	s_mov_b32 m0, s1
	s_nop 0
	global_load_lds_dwordx4 v[220:221], off
	s_waitcnt lgkmcnt(8)
	s_barrier
	s_waitcnt lgkmcnt(0)
	s_setprio 1
	s_waitcnt lgkmcnt(0)
	v_mfma_f32_16x16x32_bf16 v[124:127], v[170:173], v[188:191], v[124:127]
	v_mfma_f32_16x16x32_bf16 v[120:123], v[178:181], v[188:191], v[120:123]
	v_mfma_f32_16x16x32_bf16 v[116:119], v[170:173], v[196:199], v[116:119]
	v_mfma_f32_16x16x32_bf16 v[112:115], v[178:181], v[196:199], v[112:115]
	v_mfma_f32_16x16x32_bf16 v[108:111], v[170:173], v[204:207], v[108:111]
	v_mfma_f32_16x16x32_bf16 v[104:107], v[178:181], v[204:207], v[104:107]
	v_mfma_f32_16x16x32_bf16 v[100:103], v[170:173], v[212:215], v[100:103]
	v_mfma_f32_16x16x32_bf16 v[96:99], v[178:181], v[212:215], v[96:99]
	v_mfma_f32_16x16x32_bf16 v[124:127], v[174:177], v[192:195], v[124:127]
	v_mfma_f32_16x16x32_bf16 v[120:123], v[184:187], v[192:195], v[120:123]
	v_mfma_f32_16x16x32_bf16 v[116:119], v[174:177], v[200:203], v[116:119]
	v_mfma_f32_16x16x32_bf16 v[112:115], v[184:187], v[200:203], v[112:115]
	v_mfma_f32_16x16x32_bf16 v[108:111], v[174:177], v[208:211], v[108:111]
	v_mfma_f32_16x16x32_bf16 v[104:107], v[184:187], v[208:211], v[104:107]
	v_mfma_f32_16x16x32_bf16 v[100:103], v[174:177], v[216:219], v[100:103]
	v_mfma_f32_16x16x32_bf16 v[96:99], v[184:187], v[216:219], v[96:99]
	s_setprio 0
	s_barrier
	v_readfirstlane_b32 s1, v160
	v_lshl_add_u64 v[244:245], v[240:241], 0, s[28:29]
	s_mov_b32 m0, s1
	v_readfirstlane_b32 s1, v161
	ds_read_b128 v[220:223], v153
	ds_read_b128 v[224:227], v153 offset:1024
	ds_read_b128 v[228:231], v153 offset:2048
	ds_read_b128 v[232:235], v153 offset:3072
	global_load_lds_dwordx4 v[244:245], off
	v_lshl_add_u64 v[244:245], v[242:243], 0, s[28:29]
	s_mov_b32 m0, s1
	s_nop 0
	global_load_lds_dwordx4 v[244:245], off
	s_barrier
	s_waitcnt lgkmcnt(0)
	s_setprio 1
	s_waitcnt lgkmcnt(0)
	v_mfma_f32_16x16x32_bf16 v[92:95], v[220:223], v[188:191], v[92:95]
	v_mfma_f32_16x16x32_bf16 v[88:91], v[228:231], v[188:191], v[88:91]
	v_mfma_f32_16x16x32_bf16 v[84:87], v[220:223], v[196:199], v[84:87]
	v_mfma_f32_16x16x32_bf16 v[80:83], v[228:231], v[196:199], v[80:83]
	v_mfma_f32_16x16x32_bf16 v[76:79], v[220:223], v[204:207], v[76:79]
	v_mfma_f32_16x16x32_bf16 v[72:75], v[228:231], v[204:207], v[72:75]
	v_mfma_f32_16x16x32_bf16 v[68:71], v[220:223], v[212:215], v[68:71]
	v_mfma_f32_16x16x32_bf16 v[64:67], v[228:231], v[212:215], v[64:67]
	v_mfma_f32_16x16x32_bf16 v[92:95], v[224:227], v[192:195], v[92:95]
	v_mfma_f32_16x16x32_bf16 v[88:91], v[232:235], v[192:195], v[88:91]
	v_mfma_f32_16x16x32_bf16 v[84:87], v[224:227], v[200:203], v[84:87]
	v_mfma_f32_16x16x32_bf16 v[80:83], v[232:235], v[200:203], v[80:83]
	v_mfma_f32_16x16x32_bf16 v[76:79], v[224:227], v[208:211], v[76:79]
	v_mfma_f32_16x16x32_bf16 v[72:75], v[232:235], v[208:211], v[72:75]
	v_mfma_f32_16x16x32_bf16 v[68:71], v[224:227], v[216:219], v[68:71]
	v_mfma_f32_16x16x32_bf16 v[64:67], v[232:235], v[216:219], v[64:67]
	s_setprio 0
	v_readfirstlane_b32 s1, v162
	v_lshl_add_u64 v[236:237], v[236:237], 0, s[30:31]
	s_mov_b32 m0, s1
	v_readfirstlane_b32 s1, v163
	s_barrier
	ds_read_b128 v[188:191], v151 offset:49152
	ds_read_b128 v[192:195], v151 offset:50176
	ds_read_b128 v[196:199], v150 offset:49152
	ds_read_b128 v[200:203], v150 offset:50176
	ds_read_b128 v[204:207], v149 offset:49152
	ds_read_b128 v[208:211], v149 offset:50176
	ds_read_b128 v[212:215], v147 offset:49152
	ds_read_b128 v[216:219], v147 offset:50176
	global_load_lds_dwordx4 v[236:237], off
	v_lshl_add_u64 v[236:237], v[238:239], 0, s[30:31]
	s_mov_b32 m0, s1
	s_nop 0
	global_load_lds_dwordx4 v[236:237], off
	s_barrier
; #define STAGE(P, BASE, br, kt) do { const long _g = (long)(br) * K + (long)(kt) * 64; \
;     _Pragma("unroll") for (int _i = 0; _i < 2; ++_i) { const int _b = tidx * 16 + _i * 8192; int _r, _c; stage_rc8(_b, _r, _c); \
;       __builtin_amdgcn_global_load_lds((const unsigned*)(BASE + _g + (long)_r * K + _c), (LAS unsigned*)((LAS char*)(P) + _b), 16, 0, 0); } } while (0)
; #define LDA(dst, b, h) _Pragma("unroll") for (int m = 0; m < 4; ++m) _Pragma("unroll") for (int k = 0; k < 2; ++k) \
;     dst[m][k] = *reinterpret_cast<const bf16x8*>((const char*)SA(b, h) + lds_byte8(wr * 64 + m * 16 + fr, k * 32 + fq * 8))
; #define LDB(dst, b, h) _Pragma("unroll") for (int n = 0; n < 2; ++n) _Pragma("unroll") for (int k = 0; k < 2; ++k) \
;     dst[n][k] = *reinterpret_cast<const bf16x8*>((const char*)SB(b, h) + lds_byte8(wc * 32 + n * 16 + fr, k * 32 + fq * 8))
; #define MMA(ai, bj, At_, Bt_) do { __builtin_amdgcn_s_setprio(1); \
;     _Pragma("unroll") for (int m = 0; m < 4; ++m) _Pragma("unroll") for (int n = 0; n < 2; ++n) _Pragma("unroll") for (int k = 0; k < 2; ++k) \
;       acc[ai][bj][m][n] = MFMA16(Bt_[n][k], At_[m][k], acc[ai][bj][m][n]); \
;     __builtin_amdgcn_s_setprio(0); } while (0)
; #define WAIT_V(n) asm volatile("s_waitcnt vmcnt(" #n ")" ::: "memory")
; #define WAIT_L(n) asm volatile("s_waitcnt lgkmcnt(" #n ")" ::: "memory")
; #define BAR __builtin_amdgcn_s_barrier()
; #define SCHED __builtin_amdgcn_sched_barrier(0)
; template <class FL, class FS>
; DI void gemm8_tile(char* shmc, const bf16_t* __restrict__ A, const bf16_t* __restrict__ Bt, const int K, const int brow, const int bcol, FL fl, FS fs) {
;     ...
;     BAR; WAIT_L(0); MMA(1, 0, At, B0); BAR; SCHED;
;     STAGE(SB(1, 1), Bt, bcol + HALF, t + 3);
;     WAIT_V(6); BAR; MMA(1, 1, At, B1); BAR;
;   }
;   { LDB(B0, 0, 0); LDA(At, 0, 0); STAGE(SA(1, 1), A, brow + HALF, nt - 1);
;     BAR; WAIT_L(0); MMA(0, 0, At, B0); BAR;
;     LDB(B1, 0, 1); BAR; WAIT_L(0); MMA(0, 1, At, B1); BAR;
;     LDA(At, 0, 1); WAIT_V(4); BAR; WAIT_L(0); MMA(1, 0, At, B0); MMA(1, 1, At, B1); BAR; }
	s_waitcnt lgkmcnt(0)
	s_setprio 1
	s_waitcnt lgkmcnt(0)
	v_mfma_f32_16x16x32_bf16 v[60:63], v[170:173], v[188:191], v[60:63]
	v_mfma_f32_16x16x32_bf16 v[56:59], v[178:181], v[188:191], v[56:59]
	v_mfma_f32_16x16x32_bf16 v[52:55], v[170:173], v[196:199], v[52:55]
	v_mfma_f32_16x16x32_bf16 v[48:51], v[178:181], v[196:199], v[48:51]
	v_mfma_f32_16x16x32_bf16 v[44:47], v[170:173], v[204:207], v[44:47]
	v_mfma_f32_16x16x32_bf16 v[40:43], v[178:181], v[204:207], v[40:43]
	v_mfma_f32_16x16x32_bf16 v[36:39], v[170:173], v[212:215], v[36:39]
	v_mfma_f32_16x16x32_bf16 v[32:35], v[178:181], v[212:215], v[32:35]
	v_mfma_f32_16x16x32_bf16 v[60:63], v[174:177], v[192:195], v[60:63]
	v_mfma_f32_16x16x32_bf16 v[56:59], v[184:187], v[192:195], v[56:59]
	v_mfma_f32_16x16x32_bf16 v[52:55], v[174:177], v[200:203], v[52:55]
	v_mfma_f32_16x16x32_bf16 v[48:51], v[184:187], v[200:203], v[48:51]
	v_mfma_f32_16x16x32_bf16 v[44:47], v[174:177], v[208:211], v[44:47]
	v_mfma_f32_16x16x32_bf16 v[40:43], v[184:187], v[208:211], v[40:43]
	v_mfma_f32_16x16x32_bf16 v[36:39], v[174:177], v[216:219], v[36:39]
	v_mfma_f32_16x16x32_bf16 v[32:35], v[184:187], v[216:219], v[32:35]
	s_setprio 0
	s_barrier
	v_readfirstlane_b32 s1, v164
	v_lshl_add_u64 v[170:171], v[240:241], 0, s[34:35]
	s_mov_b32 m0, s1
	v_readfirstlane_b32 s1, v166
	global_load_lds_dwordx4 v[170:171], off
	v_lshl_add_u64 v[170:171], v[242:243], 0, s[34:35]
	s_mov_b32 m0, s1
	s_nop 0
	global_load_lds_dwordx4 v[170:171], off
	s_waitcnt vmcnt(6)
	s_barrier
	s_setprio 1
	v_mfma_f32_16x16x32_bf16 v[28:31], v[220:223], v[188:191], v[28:31]
	v_mfma_f32_16x16x32_bf16 v[24:27], v[228:231], v[188:191], v[24:27]
	v_mfma_f32_16x16x32_bf16 v[20:23], v[220:223], v[196:199], v[20:23]
	v_mfma_f32_16x16x32_bf16 v[16:19], v[228:231], v[196:199], v[16:19]
	v_mfma_f32_16x16x32_bf16 v[12:15], v[220:223], v[204:207], v[12:15]
	v_mfma_f32_16x16x32_bf16 v[8:11], v[228:231], v[204:207], v[8:11]
	v_mfma_f32_16x16x32_bf16 v[4:7], v[220:223], v[212:215], v[4:7]
	v_mfma_f32_16x16x32_bf16 v[0:3], v[228:231], v[212:215], v[0:3]
	v_mfma_f32_16x16x32_bf16 v[28:31], v[224:227], v[192:195], v[28:31]
	v_mfma_f32_16x16x32_bf16 v[24:27], v[232:235], v[192:195], v[24:27]
	v_mfma_f32_16x16x32_bf16 v[20:23], v[224:227], v[200:203], v[20:23]
	v_mfma_f32_16x16x32_bf16 v[16:19], v[232:235], v[200:203], v[16:19]
	v_mfma_f32_16x16x32_bf16 v[12:15], v[224:227], v[208:211], v[12:15]
	v_mfma_f32_16x16x32_bf16 v[8:11], v[232:235], v[208:211], v[8:11]
	v_mfma_f32_16x16x32_bf16 v[4:7], v[224:227], v[216:219], v[4:7]
	v_mfma_f32_16x16x32_bf16 v[0:3], v[232:235], v[216:219], v[0:3]
	s_setprio 0
	s_add_i32 s0, s0, 2
	v_lshl_add_u64 v[132:133], v[132:133], 0, s[36:37]
	v_lshl_add_u64 v[134:135], v[134:135], 0, s[36:37]
	v_lshl_add_u64 v[136:137], v[136:137], 0, s[36:37]
	s_cmp_lt_u32 s0, 12
	v_lshl_add_u64 v[138:139], v[138:139], 0, s[36:37]
	s_barrier
	s_cbranch_scc1 .LBB0_748
	v_readfirstlane_b32 s0, v168
	v_lshl_add_u64 v[128:129], v[128:129], 0, s[38:39]
	s_mov_b32 m0, s0
	v_readfirstlane_b32 s0, v167
	ds_read_b128 v[132:135], v169
	ds_read_b128 v[136:139], v169 offset:1024
	ds_read_b128 v[156:159], v169 offset:2048
	ds_read_b128 v[160:163], v169 offset:3072
	ds_read_b128 v[170:173], v151
	ds_read_b128 v[174:177], v151 offset:1024
	ds_read_b128 v[178:181], v150
	ds_read_b128 v[184:187], v150 offset:1024
	ds_read_b128 v[188:191], v149
	ds_read_b128 v[192:195], v149 offset:1024
	ds_read_b128 v[196:199], v147
	ds_read_b128 v[200:203], v147 offset:1024
	global_load_lds_dwordx4 v[128:129], off
	v_lshl_add_u64 v[128:129], v[130:131], 0, s[38:39]
	s_mov_b32 m0, s0
	s_nop 0
	global_load_lds_dwordx4 v[128:129], off
	s_barrier
	s_waitcnt lgkmcnt(0)
	s_setprio 1
	s_waitcnt lgkmcnt(0)
	v_mfma_f32_16x16x32_bf16 v[124:127], v[132:135], v[170:173], v[124:127]
	v_mfma_f32_16x16x32_bf16 v[120:123], v[156:159], v[170:173], v[120:123]
	v_mfma_f32_16x16x32_bf16 v[116:119], v[132:135], v[178:181], v[116:119]
	v_mfma_f32_16x16x32_bf16 v[96:99], v[156:159], v[196:199], v[96:99]
	v_mfma_f32_16x16x32_bf16 v[124:127], v[136:139], v[174:177], v[124:127]
	v_mfma_f32_16x16x32_bf16 v[120:123], v[160:163], v[174:177], v[120:123]
	v_mfma_f32_16x16x32_bf16 v[116:119], v[136:139], v[184:187], v[116:119]
	v_mfma_f32_16x16x32_bf16 v[112:115], v[156:159], v[178:181], v[112:115]
	v_mfma_f32_16x16x32_bf16 v[108:111], v[132:135], v[188:191], v[108:111]
	v_mfma_f32_16x16x32_bf16 v[104:107], v[156:159], v[188:191], v[104:107]
	v_mfma_f32_16x16x32_bf16 v[100:103], v[132:135], v[196:199], v[100:103]
	v_mfma_f32_16x16x32_bf16 v[96:99], v[160:163], v[200:203], v[96:99]
	v_mfma_f32_16x16x32_bf16 v[128:131], v[160:163], v[184:187], v[112:115]
	v_mfma_f32_16x16x32_bf16 v[166:169], v[136:139], v[192:195], v[108:111]
	v_mfma_f32_16x16x32_bf16 v[204:207], v[160:163], v[192:195], v[104:107]
	v_mfma_f32_16x16x32_bf16 v[208:211], v[136:139], v[200:203], v[100:103]
	s_setprio 0
	s_barrier
	ds_read_b128 v[100:103], v165
	ds_read_b128 v[104:107], v165 offset:1024
	ds_read_b128 v[108:111], v165 offset:2048
	ds_read_b128 v[112:115], v165 offset:3072
	s_barrier
; #define STAGE(P, BASE, br, kt) do { const long _g = (long)(br) * K + (long)(kt) * 64; \
;     _Pragma("unroll") for (int _i = 0; _i < 2; ++_i) { const int _b = tidx * 16 + _i * 8192; int _r, _c; stage_rc8(_b, _r, _c); \
;       __builtin_amdgcn_global_load_lds((const unsigned*)(BASE + _g + (long)_r * K + _c), (LAS unsigned*)((LAS char*)(P) + _b), 16, 0, 0); } } while (0)
; #define LDA(dst, b, h) _Pragma("unroll") for (int m = 0; m < 4; ++m) _Pragma("unroll") for (int k = 0; k < 2; ++k) \
;     dst[m][k] = *reinterpret_cast<const bf16x8*>((const char*)SA(b, h) + lds_byte8(wr * 64 + m * 16 + fr, k * 32 + fq * 8))
; #define LDB(dst, b, h) _Pragma("unroll") for (int n = 0; n < 2; ++n) _Pragma("unroll") for (int k = 0; k < 2; ++k) \
;     dst[n][k] = *reinterpret_cast<const bf16x8*>((const char*)SB(b, h) + lds_byte8(wc * 32 + n * 16 + fr, k * 32 + fq * 8))
; #define MMA(ai, bj, At_, Bt_) do { __builtin_amdgcn_s_setprio(1); \
;     _Pragma("unroll") for (int m = 0; m < 4; ++m) _Pragma("unroll") for (int n = 0; n < 2; ++n) _Pragma("unroll") for (int k = 0; k < 2; ++k) \
;       acc[ai][bj][m][n] = MFMA16(Bt_[n][k], At_[m][k], acc[ai][bj][m][n]); \
;     __builtin_amdgcn_s_setprio(0); } while (0)
; #define WAIT_V(n) asm volatile("s_waitcnt vmcnt(" #n ")" ::: "memory")
; #define WAIT_L(n) asm volatile("s_waitcnt lgkmcnt(" #n ")" ::: "memory")
; #define BAR __builtin_amdgcn_s_barrier()
; template <class FL, class FS>
; DI void gemm8_tile(char* shmc, const bf16_t* __restrict__ A, const bf16_t* __restrict__ Bt, const int K, const int brow, const int bcol, FL fl, FS fs) {
;     ...
;   { LDB(B0, 0, 0); LDA(At, 0, 0); STAGE(SA(1, 1), A, brow + HALF, nt - 1);
;     BAR; WAIT_L(0); MMA(0, 0, At, B0); BAR;
;     LDB(B1, 0, 1); BAR; WAIT_L(0); MMA(0, 1, At, B1); BAR;
;     LDA(At, 0, 1); WAIT_V(4); BAR; WAIT_L(0); MMA(1, 0, At, B0); MMA(1, 1, At, B1); BAR; }
;   { LDB(B0, 1, 0); LDA(At, 1, 0); WAIT_V(2); BAR; WAIT_L(0); MMA(0, 0, At, B0); BAR;
;     LDB(B1, 1, 1); WAIT_V(0); BAR; WAIT_L(0); MMA(0, 1, At, B1); BAR;
;     LDA(At, 1, 1); BAR; WAIT_L(0); MMA(1, 0, At, B0); MMA(1, 1, At, B1); BAR; }
	s_waitcnt lgkmcnt(0)
	s_setprio 1
	s_waitcnt lgkmcnt(3)
	v_mfma_f32_16x16x32_bf16 v[92:95], v[100:103], v[170:173], v[92:95]
	s_waitcnt lgkmcnt(1)
	v_mfma_f32_16x16x32_bf16 v[88:91], v[108:111], v[170:173], v[88:91]
	v_mfma_f32_16x16x32_bf16 v[84:87], v[100:103], v[178:181], v[84:87]
	v_mfma_f32_16x16x32_bf16 v[64:67], v[108:111], v[196:199], v[64:67]
	v_mfma_f32_16x16x32_bf16 v[92:95], v[104:107], v[174:177], v[92:95]
	s_waitcnt lgkmcnt(0)
	v_mfma_f32_16x16x32_bf16 v[88:91], v[112:115], v[174:177], v[88:91]
	v_mfma_f32_16x16x32_bf16 v[84:87], v[104:107], v[184:187], v[84:87]
	v_mfma_f32_16x16x32_bf16 v[80:83], v[108:111], v[178:181], v[80:83]
	v_mfma_f32_16x16x32_bf16 v[76:79], v[100:103], v[188:191], v[76:79]
	v_mfma_f32_16x16x32_bf16 v[72:75], v[108:111], v[188:191], v[72:75]
	v_mfma_f32_16x16x32_bf16 v[68:71], v[100:103], v[196:199], v[68:71]
	v_mfma_f32_16x16x32_bf16 v[64:67], v[112:115], v[200:203], v[64:67]
	v_mfma_f32_16x16x32_bf16 v[170:173], v[112:115], v[184:187], v[80:83]
	v_mfma_f32_16x16x32_bf16 v[174:177], v[104:107], v[192:195], v[76:79]
	v_mfma_f32_16x16x32_bf16 v[178:181], v[112:115], v[192:195], v[72:75]
	v_mfma_f32_16x16x32_bf16 v[184:187], v[104:107], v[200:203], v[68:71]
	s_setprio 0
	s_barrier
	s_nop 0
	ds_read_b128 v[68:71], v151 offset:16384
	ds_read_b128 v[72:75], v151 offset:17408
	ds_read_b128 v[76:79], v150 offset:16384
	ds_read_b128 v[80:83], v150 offset:17408
	ds_read_b128 v[188:191], v149 offset:16384
	ds_read_b128 v[192:195], v149 offset:17408
	ds_read_b128 v[196:199], v147 offset:16384
	ds_read_b128 v[200:203], v147 offset:17408
	s_waitcnt vmcnt(4)
	s_barrier
	s_waitcnt lgkmcnt(0)
	s_setprio 1
	s_waitcnt lgkmcnt(7)
	v_mfma_f32_16x16x32_bf16 v[60:63], v[132:135], v[68:71], v[60:63]
	v_mfma_f32_16x16x32_bf16 v[56:59], v[156:159], v[68:71], v[56:59]
	s_waitcnt lgkmcnt(3)
	v_mfma_f32_16x16x32_bf16 v[44:47], v[132:135], v[188:191], v[44:47]
	s_waitcnt lgkmcnt(1)
	v_mfma_f32_16x16x32_bf16 v[32:35], v[156:159], v[196:199], v[32:35]
	v_mfma_f32_16x16x32_bf16 v[60:63], v[136:139], v[72:75], v[60:63]
	v_mfma_f32_16x16x32_bf16 v[56:59], v[160:163], v[72:75], v[56:59]
	v_mfma_f32_16x16x32_bf16 v[52:55], v[132:135], v[76:79], v[52:55]
	v_mfma_f32_16x16x32_bf16 v[48:51], v[156:159], v[76:79], v[48:51]
	v_mfma_f32_16x16x32_bf16 v[44:47], v[136:139], v[192:195], v[44:47]
	v_mfma_f32_16x16x32_bf16 v[40:43], v[156:159], v[188:191], v[40:43]
	v_mfma_f32_16x16x32_bf16 v[36:39], v[132:135], v[196:199], v[36:39]
	s_waitcnt lgkmcnt(0)
	v_mfma_f32_16x16x32_bf16 v[32:35], v[160:163], v[200:203], v[32:35]
	v_mfma_f32_16x16x32_bf16 v[212:215], v[136:139], v[80:83], v[52:55]
	v_mfma_f32_16x16x32_bf16 v[216:219], v[160:163], v[80:83], v[48:51]
	v_mfma_f32_16x16x32_bf16 v[220:223], v[160:163], v[192:195], v[40:43]
	v_mfma_f32_16x16x32_bf16 v[132:135], v[136:139], v[200:203], v[36:39]
	s_setprio 0
	s_setprio 1
	v_mfma_f32_16x16x32_bf16 v[28:31], v[100:103], v[68:71], v[28:31]
	v_mfma_f32_16x16x32_bf16 v[24:27], v[108:111], v[68:71], v[24:27]
	v_mfma_f32_16x16x32_bf16 v[12:15], v[100:103], v[188:191], v[12:15]
	v_mfma_f32_16x16x32_bf16 v[0:3], v[108:111], v[196:199], v[0:3]
	v_mfma_f32_16x16x32_bf16 v[28:31], v[104:107], v[72:75], v[28:31]
	v_mfma_f32_16x16x32_bf16 v[24:27], v[112:115], v[72:75], v[24:27]
	v_mfma_f32_16x16x32_bf16 v[20:23], v[100:103], v[76:79], v[20:23]
	v_mfma_f32_16x16x32_bf16 v[16:19], v[108:111], v[76:79], v[16:19]
	v_mfma_f32_16x16x32_bf16 v[12:15], v[104:107], v[192:195], v[12:15]
	v_mfma_f32_16x16x32_bf16 v[8:11], v[108:111], v[188:191], v[8:11]
	v_mfma_f32_16x16x32_bf16 v[4:7], v[100:103], v[196:199], v[4:7]
	v_mfma_f32_16x16x32_bf16 v[0:3], v[112:115], v[200:203], v[0:3]
	v_mfma_f32_16x16x32_bf16 v[136:139], v[104:107], v[80:83], v[20:23]
	v_mfma_f32_16x16x32_bf16 v[156:159], v[112:115], v[80:83], v[16:19]
	v_mfma_f32_16x16x32_bf16 v[160:163], v[112:115], v[192:195], v[8:11]
	v_mfma_f32_16x16x32_bf16 v[188:191], v[104:107], v[200:203], v[4:7]
	s_setprio 0
	s_barrier
	s_nop 0
	ds_read_b128 v[4:7], v155
	ds_read_b128 v[8:11], v155 offset:1024
	ds_read_b128 v[192:195], v155 offset:2048
	ds_read_b128 v[196:199], v155 offset:3072
	ds_read_b128 v[16:19], v151 offset:32768
	ds_read_b128 v[20:23], v151 offset:33792
	ds_read_b128 v[36:39], v150 offset:32768
	ds_read_b128 v[40:43], v150 offset:33792
	ds_read_b128 v[48:51], v149 offset:32768
	ds_read_b128 v[52:55], v149 offset:33792
	ds_read_b128 v[200:203], v147 offset:32768
	ds_read_b128 v[224:227], v147 offset:33792
	s_waitcnt vmcnt(2)
	s_barrier
	s_waitcnt lgkmcnt(0)
	s_setprio 1
	s_waitcnt lgkmcnt(7)
	v_mfma_f32_16x16x32_bf16 v[68:71], v[4:7], v[16:19], v[124:127]
	s_waitcnt lgkmcnt(6)
	v_mfma_f32_16x16x32_bf16 v[108:111], v[8:11], v[20:23], v[68:71]
	v_mfma_f32_16x16x32_bf16 v[68:71], v[192:195], v[16:19], v[120:123]
	v_mfma_f32_16x16x32_bf16 v[112:115], v[196:199], v[20:23], v[68:71]
	s_waitcnt lgkmcnt(5)
	v_mfma_f32_16x16x32_bf16 v[68:71], v[4:7], v[36:39], v[116:119]
	s_waitcnt lgkmcnt(4)
	v_mfma_f32_16x16x32_bf16 v[104:107], v[8:11], v[40:43], v[68:71]
	v_mfma_f32_16x16x32_bf16 v[68:71], v[192:195], v[36:39], v[128:131]
	v_mfma_f32_16x16x32_bf16 v[100:103], v[196:199], v[40:43], v[68:71]
	s_waitcnt lgkmcnt(3)
	v_mfma_f32_16x16x32_bf16 v[68:71], v[4:7], v[48:51], v[166:169]
	s_waitcnt lgkmcnt(2)
	v_mfma_f32_16x16x32_bf16 v[80:83], v[8:11], v[52:55], v[68:71]
	v_mfma_f32_16x16x32_bf16 v[68:71], v[192:195], v[48:51], v[204:207]
	v_mfma_f32_16x16x32_bf16 v[76:79], v[196:199], v[52:55], v[68:71]
	s_waitcnt lgkmcnt(1)
	v_mfma_f32_16x16x32_bf16 v[68:71], v[4:7], v[200:203], v[208:211]
	s_waitcnt lgkmcnt(0)
	v_mfma_f32_16x16x32_bf16 v[72:75], v[8:11], v[224:227], v[68:71]
	v_mfma_f32_16x16x32_bf16 v[68:71], v[192:195], v[200:203], v[96:99]
	v_mfma_f32_16x16x32_bf16 v[68:71], v[196:199], v[224:227], v[68:71]
	s_setprio 0
	s_barrier
; #define LDA(dst, b, h) _Pragma("unroll") for (int m = 0; m < 4; ++m) _Pragma("unroll") for (int k = 0; k < 2; ++k) \
;     dst[m][k] = *reinterpret_cast<const bf16x8*>((const char*)SA(b, h) + lds_byte8(wr * 64 + m * 16 + fr, k * 32 + fq * 8))
; #define LDB(dst, b, h) _Pragma("unroll") for (int n = 0; n < 2; ++n) _Pragma("unroll") for (int k = 0; k < 2; ++k) \
;     dst[n][k] = *reinterpret_cast<const bf16x8*>((const char*)SB(b, h) + lds_byte8(wc * 32 + n * 16 + fr, k * 32 + fq * 8))
; #define MMA(ai, bj, At_, Bt_) do { __builtin_amdgcn_s_setprio(1); \
;     _Pragma("unroll") for (int m = 0; m < 4; ++m) _Pragma("unroll") for (int n = 0; n < 2; ++n) _Pragma("unroll") for (int k = 0; k < 2; ++k) \
;       acc[ai][bj][m][n] = MFMA16(Bt_[n][k], At_[m][k], acc[ai][bj][m][n]); \
;     __builtin_amdgcn_s_setprio(0); } while (0)
; #define WAIT_V(n) asm volatile("s_waitcnt vmcnt(" #n ")" ::: "memory")
; #define WAIT_L(n) asm volatile("s_waitcnt lgkmcnt(" #n ")" ::: "memory")
; #define BAR __builtin_amdgcn_s_barrier()
; template <class FL, class FS>
; DI void gemm8_tile(char* shmc, const bf16_t* __restrict__ A, const bf16_t* __restrict__ Bt, const int K, const int brow, const int bcol, FL fl, FS fs) {
;     ...
;   { LDB(B0, 1, 0); LDA(At, 1, 0); WAIT_V(2); BAR; WAIT_L(0); MMA(0, 0, At, B0); BAR;
;     LDB(B1, 1, 1); WAIT_V(0); BAR; WAIT_L(0); MMA(0, 1, At, B1); BAR;
;     LDA(At, 1, 1); BAR; WAIT_L(0); MMA(1, 0, At, B0); MMA(1, 1, At, B1); BAR; }
;   if (wr == 0) BAR;
; template <class FL, class FS>
; DI void gemm_dispatch(const Sub& s, char* lds_all, const bf16_t* A, const bf16_t* Bt, const int nN256, FL fl, FS fs) {
;     ...
;     for (int L = blockIdx.x; L < nM * nN256; L += gridDim.x) {
;       int pm, pn; tile8_order(L, nM, nN256, pm, pn);
;       gemm8_tile(lds_all, A, Bt, D, pm * 256, pn * 256, fl, fs);
	ds_read_b128 v[128:131], v153
	ds_read_b128 v[164:167], v153 offset:1024
	ds_read_b128 v[204:207], v153 offset:2048
	ds_read_b128 v[152:155], v153 offset:3072
	s_waitcnt vmcnt(0)
	s_barrier
	s_waitcnt lgkmcnt(0)
	s_setprio 1
	s_waitcnt lgkmcnt(3)
	v_mfma_f32_16x16x32_bf16 v[92:95], v[128:131], v[16:19], v[92:95]
	s_waitcnt lgkmcnt(1)
	v_mfma_f32_16x16x32_bf16 v[16:19], v[204:207], v[16:19], v[88:91]
	s_waitcnt lgkmcnt(0)
	v_mfma_f32_16x16x32_bf16 v[120:123], v[152:155], v[20:23], v[16:19]
	v_mfma_f32_16x16x32_bf16 v[16:19], v[128:131], v[36:39], v[84:87]
	v_mfma_f32_16x16x32_bf16 v[116:119], v[164:167], v[40:43], v[16:19]
	v_mfma_f32_16x16x32_bf16 v[16:19], v[204:207], v[36:39], v[170:173]
	v_mfma_f32_16x16x32_bf16 v[96:99], v[152:155], v[40:43], v[16:19]
	v_mfma_f32_16x16x32_bf16 v[16:19], v[128:131], v[48:51], v[174:177]
	v_mfma_f32_16x16x32_bf16 v[124:127], v[164:167], v[20:23], v[92:95]
	v_mfma_f32_16x16x32_bf16 v[92:95], v[164:167], v[52:55], v[16:19]
	v_mfma_f32_16x16x32_bf16 v[16:19], v[204:207], v[48:51], v[178:181]
	v_mfma_f32_16x16x32_bf16 v[88:91], v[152:155], v[52:55], v[16:19]
	v_mfma_f32_16x16x32_bf16 v[16:19], v[128:131], v[200:203], v[184:187]
	v_mfma_f32_16x16x32_bf16 v[84:87], v[164:167], v[224:227], v[16:19]
	v_mfma_f32_16x16x32_bf16 v[16:19], v[204:207], v[200:203], v[64:67]
	v_mfma_f32_16x16x32_bf16 v[64:67], v[152:155], v[224:227], v[16:19]
	s_setprio 0
	s_barrier
	ds_read_b128 v[168:171], v151 offset:49152
	ds_read_b128 v[172:175], v151 offset:50176
	ds_read_b128 v[176:179], v150 offset:49152
	ds_read_b128 v[184:187], v150 offset:50176
	ds_read_b128 v[200:203], v149 offset:49152
	ds_read_b128 v[148:151], v149 offset:50176
	ds_read_b128 v[208:211], v147 offset:49152
	ds_read_b128 v[224:227], v147 offset:50176
	s_barrier
	s_waitcnt lgkmcnt(0)
	s_setprio 1
	s_waitcnt lgkmcnt(7)
	v_mfma_f32_16x16x32_bf16 v[16:19], v[4:7], v[168:171], v[60:63]
	s_waitcnt lgkmcnt(6)
	v_mfma_f32_16x16x32_bf16 v[52:55], v[8:11], v[172:175], v[16:19]
	v_mfma_f32_16x16x32_bf16 v[16:19], v[192:195], v[168:171], v[56:59]
	v_mfma_f32_16x16x32_bf16 v[48:51], v[196:199], v[172:175], v[16:19]
	s_waitcnt lgkmcnt(5)
	v_mfma_f32_16x16x32_bf16 v[16:19], v[4:7], v[176:179], v[212:215]
	s_waitcnt lgkmcnt(4)
	v_mfma_f32_16x16x32_bf16 v[40:43], v[8:11], v[184:187], v[16:19]
	v_mfma_f32_16x16x32_bf16 v[16:19], v[192:195], v[176:179], v[216:219]
	v_mfma_f32_16x16x32_bf16 v[36:39], v[196:199], v[184:187], v[16:19]
	s_waitcnt lgkmcnt(3)
	v_mfma_f32_16x16x32_bf16 v[16:19], v[4:7], v[200:203], v[44:47]
	s_waitcnt lgkmcnt(1)
	v_mfma_f32_16x16x32_bf16 v[4:7], v[4:7], v[208:211], v[132:135]
	v_mfma_f32_16x16x32_bf16 v[20:23], v[8:11], v[148:151], v[16:19]
	v_mfma_f32_16x16x32_bf16 v[16:19], v[192:195], v[200:203], v[220:223]
	s_waitcnt lgkmcnt(0)
	v_mfma_f32_16x16x32_bf16 v[8:11], v[8:11], v[224:227], v[4:7]
	v_mfma_f32_16x16x32_bf16 v[4:7], v[192:195], v[208:211], v[32:35]
	v_mfma_f32_16x16x32_bf16 v[16:19], v[196:199], v[148:151], v[16:19]
	v_mfma_f32_16x16x32_bf16 v[4:7], v[196:199], v[224:227], v[4:7]
	s_setprio 0
	s_setprio 1
	v_mfma_f32_16x16x32_bf16 v[24:27], v[204:207], v[168:171], v[24:27]
	v_mfma_f32_16x16x32_bf16 v[28:31], v[128:131], v[168:171], v[28:31]
	v_mfma_f32_16x16x32_bf16 v[56:59], v[152:155], v[172:175], v[24:27]
	v_mfma_f32_16x16x32_bf16 v[24:27], v[128:131], v[176:179], v[136:139]
	v_mfma_f32_16x16x32_bf16 v[12:15], v[128:131], v[200:203], v[12:15]
	v_mfma_f32_16x16x32_bf16 v[60:63], v[164:167], v[172:175], v[28:31]
	v_mfma_f32_16x16x32_bf16 v[44:47], v[164:167], v[184:187], v[24:27]
	v_mfma_f32_16x16x32_bf16 v[24:27], v[204:207], v[176:179], v[156:159]
	v_mfma_f32_16x16x32_bf16 v[28:31], v[164:167], v[148:151], v[12:15]
	v_mfma_f32_16x16x32_bf16 v[12:15], v[204:207], v[200:203], v[160:163]
	v_mfma_f32_16x16x32_bf16 v[32:35], v[152:155], v[184:187], v[24:27]
	v_mfma_f32_16x16x32_bf16 v[24:27], v[152:155], v[148:151], v[12:15]
	v_mfma_f32_16x16x32_bf16 v[12:15], v[128:131], v[208:211], v[188:191]
	v_mfma_f32_16x16x32_bf16 v[0:3], v[204:207], v[208:211], v[0:3]
	v_mfma_f32_16x16x32_bf16 v[12:15], v[164:167], v[224:227], v[12:15]
	v_mfma_f32_16x16x32_bf16 v[0:3], v[152:155], v[224:227], v[0:3]
	s_setprio 0
	v_cmp_gt_u32_e32 vcc, s54, v140
	s_barrier
	s_and_saveexec_b64 s[0:1], vcc
	s_cbranch_execz .Lg3_wr0
	s_barrier
.Lg3_wr0:
	s_or_b64 exec, exec, s[0:1]
	s_mov_b32 s99, s44
	s_mov_b32 s100, s42
	s_mov_b32 s98, 1
	v_readlane_b32 s0, v251, 1
	s_add_i32 s56, s56, s0
	s_cmpk_lt_i32 s56, 0x400
	s_cbranch_scc1 .LBB0_745
	s_mov_b32 s101, 1
; DI float4 ldnt4(const float* p) { const f32x4 v = __builtin_nontemporal_load((const f32x4*)p); float4 r; r.x = v[0]; r.y = v[1]; r.z = v[2]; r.w = v[3]; return r; }
; DI void st_bf4(bf16_t* p, float a, float b, float c, float d) { uint2 v; v.x = pack2(a, b); v.y = pack2(c, d); *(uint2*)p = v; }
; template <class FL, class FS>
; DI void gemm8_tile(char* shmc, const bf16_t* __restrict__ A, const bf16_t* __restrict__ Bt, const int K, const int brow, const int bcol, FL fl, FS fs) {
;     ...
; #pragma unroll
;   for (int ai = 0; ai < 2; ++ai)
; #pragma unroll
;     for (int mh = 0; mh < 2; ++mh) {
;       decltype(fl(0, 0)) ld[2][2][2];
; #pragma unroll
;       for (int mm = 0; mm < 2; ++mm)
; #pragma unroll
;         for (int bj = 0; bj < 2; ++bj)
; #pragma unroll
;           for (int n = 0; n < 2; ++n) ld[mm][bj][n] = fl(brow + ai * HALF + wr * 64 + (2 * mh + mm) * 16 + fr, bcol + bj * HALF + wc * 32 + n * 16 + 4 * fq);
; #pragma unroll
;       for (int mm = 0; mm < 2; ++mm)
; #pragma unroll
;         for (int bj = 0; bj < 2; ++bj)
; #pragma unroll
;           for (int n = 0; n < 2; ++n) fs(brow + ai * HALF + wr * 64 + (2 * mh + mm) * 16 + fr, bcol + bj * HALF + wc * 32 + n * 16 + 4 * fq, acc[ai][bj][2 * mh + mm][n], ld[mm][bj][n]);
; DI void phase_gout(const Params& p, const Sub& s, char* lds_all, int layer, const bf16_t* A, const bf16_t* Bt) {
;     ...
;       [&](int row, int col) {
;         const bf16_t* x1b = (const bf16_t*)p.out;
;         float4 x4;
;         if (layer == 0) x4 = ldnt4(xrow(p, row) + col);
;         else ld_bf4(x1b + (size_t)row * D + col, x4.x, x4.y, x4.z, x4.w);
;         Ld2 r; r.a = x4; r.b = *(const float4*)(mod + (size_t)(row_bi(row) * 2 + layer) * 3072 + 2048 + col);
;         return r;
;       },
;       [&](int row, int col, f32x4 v, const Ld2& l2) {
;         const float4 x4 = l2.a, g4 = l2.b;
;         bf16_t* x1b = (bf16_t*)p.out;
;         bf16_t* x2b = (bf16_t*)(p.ws + W_SLOT3);
;         st_bf4((layer == 0 ? x1b : x2b) + (size_t)row * D + col, x4.x + g4.x * v[0], x4.y + g4.y * v[1], x4.z + g4.z * v[2], x4.w + g4.w * v[3]);
.Lg3_epi:
	v_and_b32_e32 v170, 15, v182
	v_bfe_u32 v171, v182, 4, 2
	v_bfe_u32 v180, v182, 6, 2
	v_lshrrev_b32_e32 v181, 8, v182
	v_lshl_add_u32 v248, v181, 6, v170
	v_and_b32_e32 v249, 1, v171
	v_lshrrev_b32_e32 v250, 1, v171
	v_lshlrev_b32_e32 v240, 12, v248
	v_lshl_add_u32 v240, v180, 7, v240
	v_lshl_add_u32 v240, v171, 4, v240
	v_lshlrev_b32_e32 v241, 7, v180
	v_lshl_add_u32 v241, v171, 4, v241
	v_lshlrev_b32_e32 v242, 11, v248
	v_lshl_add_u32 v242, v180, 6, v242
	v_lshl_add_u32 v242, v249, 5, v242
	v_lshl_add_u32 v242, v250, 4, v242
	s_lshr_b32 s0, s99, 13
	s_mul_i32 s0, s0, 0x6000
	s_add_u32 s0, s0, 0x2000
	s_lshl_b32 s1, s100, 2
	s_add_u32 s0, s0, s1
	s_add_u32 s2, s6, s0
	s_addc_u32 s3, s7, 0
	s_lshl_b32 s0, s99, 12
	s_add_u32 s4, s12, s0
	s_addc_u32 s5, s13, 0
	s_lshl_b32 s0, s100, 2
	s_add_u32 s4, s4, s0
	s_addc_u32 s5, s5, 0
	s_lshl_b32 s0, s99, 11
	s_add_u32 s40, s8, s0
	s_addc_u32 s41, s9, 0
	s_lshl_b32 s0, s100, 1
	s_add_u32 s40, s40, s0
	s_addc_u32 s41, s41, 0
	global_load_dwordx4 v[172:175], v241, s[2:3]
	global_load_dwordx4 v[176:179], v241, s[2:3] offset:64
	global_load_dwordx4 v[184:187], v241, s[2:3] offset:512
	global_load_dwordx4 v[188:191], v241, s[2:3] offset:576
	global_load_dwordx4 v[192:195], v240, s[4:5] nt
	global_load_dwordx4 v[196:199], v240, s[4:5] offset:64 nt
	global_load_dwordx4 v[200:203], v240, s[4:5] offset:512 nt
	global_load_dwordx4 v[204:207], v240, s[4:5] offset:576 nt
	s_add_u32 s4, s4, 0x10000
	s_addc_u32 s5, s5, 0
	global_load_dwordx4 v[208:211], v240, s[4:5] nt
	global_load_dwordx4 v[212:215], v240, s[4:5] offset:64 nt
	global_load_dwordx4 v[216:219], v240, s[4:5] offset:512 nt
	global_load_dwordx4 v[220:223], v240, s[4:5] offset:576 nt
	s_add_u32 s4, s4, 0x10000
	s_addc_u32 s5, s5, 0
	global_load_dwordx4 v[224:227], v240, s[4:5] nt
	global_load_dwordx4 v[228:231], v240, s[4:5] offset:64 nt
	global_load_dwordx4 v[232:235], v240, s[4:5] offset:512 nt
	global_load_dwordx4 v[236:239], v240, s[4:5] offset:576 nt
	s_waitcnt vmcnt(8)
	v_pk_fma_f32 v[192:193], v[172:173], v[108:109], v[192:193]
	v_pk_fma_f32 v[194:195], v[174:175], v[110:111], v[194:195]
	v_pk_fma_f32 v[196:197], v[176:177], v[112:113], v[196:197]
	v_pk_fma_f32 v[198:199], v[178:179], v[114:115], v[198:199]
	v_pk_fma_f32 v[200:201], v[184:185], v[124:125], v[200:201]
	v_pk_fma_f32 v[202:203], v[186:187], v[126:127], v[202:203]
	v_pk_fma_f32 v[204:205], v[188:189], v[120:121], v[204:205]
	v_pk_fma_f32 v[206:207], v[190:191], v[122:123], v[206:207]
	v_cvt_pk_bf16_f32 v192, v192, v193
	v_cvt_pk_bf16_f32 v193, v194, v195
	v_cvt_pk_bf16_f32 v194, v196, v197
	v_cvt_pk_bf16_f32 v195, v198, v199
	v_cvt_pk_bf16_f32 v200, v200, v201
	v_cvt_pk_bf16_f32 v201, v202, v203
	v_cvt_pk_bf16_f32 v202, v204, v205
	v_cvt_pk_bf16_f32 v203, v206, v207
	v_permlane16_swap_b32_e32 v192, v194
	v_permlane16_swap_b32_e32 v193, v195
	global_store_dwordx4 v242, v[192:195], s[40:41]
	v_permlane16_swap_b32_e32 v200, v202
	v_permlane16_swap_b32_e32 v201, v203
	global_store_dwordx4 v242, v[200:203], s[40:41] offset:256
	s_nop 1
	s_add_u32 s4, s4, 0x10000
	s_addc_u32 s5, s5, 0
	global_load_dwordx4 v[192:195], v240, s[4:5] nt
	global_load_dwordx4 v[196:199], v240, s[4:5] offset:64 nt
	global_load_dwordx4 v[200:203], v240, s[4:5] offset:512 nt
	global_load_dwordx4 v[204:207], v240, s[4:5] offset:576 nt
	s_waitcnt vmcnt(10)
	v_pk_fma_f32 v[208:209], v[172:173], v[104:105], v[208:209]
	v_pk_fma_f32 v[210:211], v[174:175], v[106:107], v[210:211]
	v_pk_fma_f32 v[212:213], v[176:177], v[100:101], v[212:213]
	v_pk_fma_f32 v[214:215], v[178:179], v[102:103], v[214:215]
	v_pk_fma_f32 v[216:217], v[184:185], v[116:117], v[216:217]
	v_pk_fma_f32 v[218:219], v[186:187], v[118:119], v[218:219]
	v_pk_fma_f32 v[220:221], v[188:189], v[96:97], v[220:221]
	v_pk_fma_f32 v[222:223], v[190:191], v[98:99], v[222:223]
	v_cvt_pk_bf16_f32 v208, v208, v209
	v_cvt_pk_bf16_f32 v209, v210, v211
	v_cvt_pk_bf16_f32 v210, v212, v213
	v_cvt_pk_bf16_f32 v211, v214, v215
	v_cvt_pk_bf16_f32 v216, v216, v217
	v_cvt_pk_bf16_f32 v217, v218, v219
	v_cvt_pk_bf16_f32 v218, v220, v221
	v_cvt_pk_bf16_f32 v219, v222, v223
	s_add_u32 s40, s40, 0x8000
	s_addc_u32 s41, s41, 0
	v_permlane16_swap_b32_e32 v208, v210
	v_permlane16_swap_b32_e32 v209, v211
	global_store_dwordx4 v242, v[208:211], s[40:41]
	v_permlane16_swap_b32_e32 v216, v218
	v_permlane16_swap_b32_e32 v217, v219
	global_store_dwordx4 v242, v[216:219], s[40:41] offset:256
	s_nop 1
	s_add_u32 s4, s4, 0x50000
	s_addc_u32 s5, s5, 0
	global_load_dwordx4 v[208:211], v240, s[4:5] nt
	global_load_dwordx4 v[212:215], v240, s[4:5] offset:64 nt
	global_load_dwordx4 v[216:219], v240, s[4:5] offset:512 nt
	global_load_dwordx4 v[220:223], v240, s[4:5] offset:576 nt
	s_waitcnt vmcnt(12)
	v_pk_fma_f32 v[224:225], v[172:173], v[80:81], v[224:225]
	v_pk_fma_f32 v[226:227], v[174:175], v[82:83], v[226:227]
	v_pk_fma_f32 v[228:229], v[176:177], v[76:77], v[228:229]
	v_pk_fma_f32 v[230:231], v[178:179], v[78:79], v[230:231]
	v_pk_fma_f32 v[232:233], v[184:185], v[92:93], v[232:233]
	v_pk_fma_f32 v[234:235], v[186:187], v[94:95], v[234:235]
	v_pk_fma_f32 v[236:237], v[188:189], v[88:89], v[236:237]
	v_pk_fma_f32 v[238:239], v[190:191], v[90:91], v[238:239]
	v_cvt_pk_bf16_f32 v224, v224, v225
	v_cvt_pk_bf16_f32 v225, v226, v227
	v_cvt_pk_bf16_f32 v226, v228, v229
	v_cvt_pk_bf16_f32 v227, v230, v231
	v_cvt_pk_bf16_f32 v232, v232, v233
	v_cvt_pk_bf16_f32 v233, v234, v235
	v_cvt_pk_bf16_f32 v234, v236, v237
	v_cvt_pk_bf16_f32 v235, v238, v239
	s_add_u32 s40, s40, 0x8000
	s_addc_u32 s41, s41, 0
	v_permlane16_swap_b32_e32 v224, v226
	v_permlane16_swap_b32_e32 v225, v227
	global_store_dwordx4 v242, v[224:227], s[40:41]
	v_permlane16_swap_b32_e32 v232, v234
	v_permlane16_swap_b32_e32 v233, v235
	global_store_dwordx4 v242, v[232:235], s[40:41] offset:256
	s_nop 1
	s_add_u32 s4, s4, 0x10000
	s_addc_u32 s5, s5, 0
	global_load_dwordx4 v[224:227], v240, s[4:5] nt
	global_load_dwordx4 v[228:231], v240, s[4:5] offset:64 nt
	global_load_dwordx4 v[232:235], v240, s[4:5] offset:512 nt
	global_load_dwordx4 v[236:239], v240, s[4:5] offset:576 nt
	s_waitcnt vmcnt(12)
; DI float4 ldnt4(const float* p) { const f32x4 v = __builtin_nontemporal_load((const f32x4*)p); float4 r; r.x = v[0]; r.y = v[1]; r.z = v[2]; r.w = v[3]; return r; }
; DI void st_bf4(bf16_t* p, float a, float b, float c, float d) { uint2 v; v.x = pack2(a, b); v.y = pack2(c, d); *(uint2*)p = v; }
; template <class FL, class FS>
; DI void gemm8_tile(char* shmc, const bf16_t* __restrict__ A, const bf16_t* __restrict__ Bt, const int K, const int brow, const int bcol, FL fl, FS fs) {
;     ...
; #pragma unroll
;   for (int ai = 0; ai < 2; ++ai)
; #pragma unroll
;     for (int mh = 0; mh < 2; ++mh) {
;       decltype(fl(0, 0)) ld[2][2][2];
; #pragma unroll
;       for (int mm = 0; mm < 2; ++mm)
; #pragma unroll
;         for (int bj = 0; bj < 2; ++bj)
; #pragma unroll
;           for (int n = 0; n < 2; ++n) ld[mm][bj][n] = fl(brow + ai * HALF + wr * 64 + (2 * mh + mm) * 16 + fr, bcol + bj * HALF + wc * 32 + n * 16 + 4 * fq);
; #pragma unroll
;       for (int mm = 0; mm < 2; ++mm)
; #pragma unroll
;         for (int bj = 0; bj < 2; ++bj)
; #pragma unroll
;           for (int n = 0; n < 2; ++n) fs(brow + ai * HALF + wr * 64 + (2 * mh + mm) * 16 + fr, bcol + bj * HALF + wc * 32 + n * 16 + 4 * fq, acc[ai][bj][2 * mh + mm][n], ld[mm][bj][n]);
; DI void phase_gout(const Params& p, const Sub& s, char* lds_all, int layer, const bf16_t* A, const bf16_t* Bt) {
;     ...
;       [&](int row, int col) {
;         const bf16_t* x1b = (const bf16_t*)p.out;
;         float4 x4;
;         if (layer == 0) x4 = ldnt4(xrow(p, row) + col);
;         else ld_bf4(x1b + (size_t)row * D + col, x4.x, x4.y, x4.z, x4.w);
;         Ld2 r; r.a = x4; r.b = *(const float4*)(mod + (size_t)(row_bi(row) * 2 + layer) * 3072 + 2048 + col);
;         return r;
;       },
;       [&](int row, int col, f32x4 v, const Ld2& l2) {
;         const float4 x4 = l2.a, g4 = l2.b;
;         bf16_t* x1b = (bf16_t*)p.out;
;         bf16_t* x2b = (bf16_t*)(p.ws + W_SLOT3);
;         st_bf4((layer == 0 ? x1b : x2b) + (size_t)row * D + col, x4.x + g4.x * v[0], x4.y + g4.y * v[1], x4.z + g4.z * v[2], x4.w + g4.w * v[3]);
	v_pk_fma_f32 v[192:193], v[172:173], v[72:73], v[192:193]
	v_pk_fma_f32 v[194:195], v[174:175], v[74:75], v[194:195]
	v_pk_fma_f32 v[196:197], v[176:177], v[68:69], v[196:197]
	v_pk_fma_f32 v[198:199], v[178:179], v[70:71], v[198:199]
	v_pk_fma_f32 v[200:201], v[184:185], v[84:85], v[200:201]
	v_pk_fma_f32 v[202:203], v[186:187], v[86:87], v[202:203]
	v_pk_fma_f32 v[204:205], v[188:189], v[64:65], v[204:205]
	v_pk_fma_f32 v[206:207], v[190:191], v[66:67], v[206:207]
	v_cvt_pk_bf16_f32 v192, v192, v193
	v_cvt_pk_bf16_f32 v193, v194, v195
	v_cvt_pk_bf16_f32 v194, v196, v197
	v_cvt_pk_bf16_f32 v195, v198, v199
	v_cvt_pk_bf16_f32 v200, v200, v201
	v_cvt_pk_bf16_f32 v201, v202, v203
	v_cvt_pk_bf16_f32 v202, v204, v205
	v_cvt_pk_bf16_f32 v203, v206, v207
	s_add_u32 s40, s40, 0x8000
	s_addc_u32 s41, s41, 0
	v_permlane16_swap_b32_e32 v192, v194
	v_permlane16_swap_b32_e32 v193, v195
	global_store_dwordx4 v242, v[192:195], s[40:41]
	v_permlane16_swap_b32_e32 v200, v202
	v_permlane16_swap_b32_e32 v201, v203
	global_store_dwordx4 v242, v[200:203], s[40:41] offset:256
	s_nop 1
	s_add_u32 s4, s4, 0x10000
	s_addc_u32 s5, s5, 0
	global_load_dwordx4 v[192:195], v240, s[4:5] nt
	global_load_dwordx4 v[196:199], v240, s[4:5] offset:64 nt
	global_load_dwordx4 v[200:203], v240, s[4:5] offset:512 nt
	global_load_dwordx4 v[204:207], v240, s[4:5] offset:576 nt
	s_waitcnt vmcnt(12)
	v_pk_fma_f32 v[208:209], v[172:173], v[52:53], v[208:209]
	v_pk_fma_f32 v[210:211], v[174:175], v[54:55], v[210:211]
	v_pk_fma_f32 v[212:213], v[176:177], v[48:49], v[212:213]
	v_pk_fma_f32 v[214:215], v[178:179], v[50:51], v[214:215]
	v_pk_fma_f32 v[216:217], v[184:185], v[60:61], v[216:217]
	v_pk_fma_f32 v[218:219], v[186:187], v[62:63], v[218:219]
	v_pk_fma_f32 v[220:221], v[188:189], v[56:57], v[220:221]
	v_pk_fma_f32 v[222:223], v[190:191], v[58:59], v[222:223]
	v_cvt_pk_bf16_f32 v208, v208, v209
	v_cvt_pk_bf16_f32 v209, v210, v211
	v_cvt_pk_bf16_f32 v210, v212, v213
	v_cvt_pk_bf16_f32 v211, v214, v215
	v_cvt_pk_bf16_f32 v216, v216, v217
	v_cvt_pk_bf16_f32 v217, v218, v219
	v_cvt_pk_bf16_f32 v218, v220, v221
	v_cvt_pk_bf16_f32 v219, v222, v223
	s_add_u32 s40, s40, 0x28000
	s_addc_u32 s41, s41, 0
	v_permlane16_swap_b32_e32 v208, v210
	v_permlane16_swap_b32_e32 v209, v211
	global_store_dwordx4 v242, v[208:211], s[40:41]
	v_permlane16_swap_b32_e32 v216, v218
	v_permlane16_swap_b32_e32 v217, v219
	global_store_dwordx4 v242, v[216:219], s[40:41] offset:256
	s_nop 1
	s_add_u32 s4, s4, 0x10000
	s_addc_u32 s5, s5, 0
	global_load_dwordx4 v[208:211], v240, s[4:5] nt
	global_load_dwordx4 v[212:215], v240, s[4:5] offset:64 nt
	global_load_dwordx4 v[216:219], v240, s[4:5] offset:512 nt
	global_load_dwordx4 v[220:223], v240, s[4:5] offset:576 nt
	s_waitcnt vmcnt(12)
	v_pk_fma_f32 v[224:225], v[172:173], v[40:41], v[224:225]
	v_pk_fma_f32 v[226:227], v[174:175], v[42:43], v[226:227]
	v_pk_fma_f32 v[228:229], v[176:177], v[36:37], v[228:229]
	v_pk_fma_f32 v[230:231], v[178:179], v[38:39], v[230:231]
	v_pk_fma_f32 v[232:233], v[184:185], v[44:45], v[232:233]
	v_pk_fma_f32 v[234:235], v[186:187], v[46:47], v[234:235]
	v_pk_fma_f32 v[236:237], v[188:189], v[32:33], v[236:237]
	v_pk_fma_f32 v[238:239], v[190:191], v[34:35], v[238:239]
	v_cvt_pk_bf16_f32 v224, v224, v225
	v_cvt_pk_bf16_f32 v225, v226, v227
	v_cvt_pk_bf16_f32 v226, v228, v229
	v_cvt_pk_bf16_f32 v227, v230, v231
	v_cvt_pk_bf16_f32 v232, v232, v233
	v_cvt_pk_bf16_f32 v233, v234, v235
	v_cvt_pk_bf16_f32 v234, v236, v237
	v_cvt_pk_bf16_f32 v235, v238, v239
	s_add_u32 s40, s40, 0x8000
	s_addc_u32 s41, s41, 0
	v_permlane16_swap_b32_e32 v224, v226
	v_permlane16_swap_b32_e32 v225, v227
	global_store_dwordx4 v242, v[224:227], s[40:41]
	v_permlane16_swap_b32_e32 v232, v234
	v_permlane16_swap_b32_e32 v233, v235
	global_store_dwordx4 v242, v[232:235], s[40:41] offset:256
	s_waitcnt vmcnt(8)
	v_pk_fma_f32 v[192:193], v[172:173], v[20:21], v[192:193]
	v_pk_fma_f32 v[194:195], v[174:175], v[22:23], v[194:195]
	v_pk_fma_f32 v[196:197], v[176:177], v[16:17], v[196:197]
	v_pk_fma_f32 v[198:199], v[178:179], v[18:19], v[198:199]
	v_pk_fma_f32 v[200:201], v[184:185], v[28:29], v[200:201]
	v_pk_fma_f32 v[202:203], v[186:187], v[30:31], v[202:203]
	v_pk_fma_f32 v[204:205], v[188:189], v[24:25], v[204:205]
	v_pk_fma_f32 v[206:207], v[190:191], v[26:27], v[206:207]
	v_cvt_pk_bf16_f32 v192, v192, v193
	v_cvt_pk_bf16_f32 v193, v194, v195
	v_cvt_pk_bf16_f32 v194, v196, v197
	v_cvt_pk_bf16_f32 v195, v198, v199
	v_cvt_pk_bf16_f32 v200, v200, v201
	v_cvt_pk_bf16_f32 v201, v202, v203
	v_cvt_pk_bf16_f32 v202, v204, v205
	v_cvt_pk_bf16_f32 v203, v206, v207
	s_add_u32 s40, s40, 0x8000
	s_addc_u32 s41, s41, 0
	v_permlane16_swap_b32_e32 v192, v194
	v_permlane16_swap_b32_e32 v193, v195
	global_store_dwordx4 v242, v[192:195], s[40:41]
	v_permlane16_swap_b32_e32 v200, v202
	v_permlane16_swap_b32_e32 v201, v203
	global_store_dwordx4 v242, v[200:203], s[40:41] offset:256
	s_waitcnt vmcnt(4)
	v_pk_fma_f32 v[208:209], v[172:173], v[8:9], v[208:209]
	v_pk_fma_f32 v[210:211], v[174:175], v[10:11], v[210:211]
	v_pk_fma_f32 v[212:213], v[176:177], v[4:5], v[212:213]
	v_pk_fma_f32 v[214:215], v[178:179], v[6:7], v[214:215]
	v_pk_fma_f32 v[216:217], v[184:185], v[12:13], v[216:217]
	v_pk_fma_f32 v[218:219], v[186:187], v[14:15], v[218:219]
	v_pk_fma_f32 v[220:221], v[188:189], v[0:1], v[220:221]
	v_pk_fma_f32 v[222:223], v[190:191], v[2:3], v[222:223]
	v_cvt_pk_bf16_f32 v208, v208, v209
	v_cvt_pk_bf16_f32 v209, v210, v211
	v_cvt_pk_bf16_f32 v210, v212, v213
	v_cvt_pk_bf16_f32 v211, v214, v215
	v_cvt_pk_bf16_f32 v216, v216, v217
	v_cvt_pk_bf16_f32 v217, v218, v219
	v_cvt_pk_bf16_f32 v218, v220, v221
	v_cvt_pk_bf16_f32 v219, v222, v223
	s_add_u32 s40, s40, 0x8000
	s_addc_u32 s41, s41, 0
	v_permlane16_swap_b32_e32 v208, v210
	v_permlane16_swap_b32_e32 v209, v211
	global_store_dwordx4 v242, v[208:211], s[40:41]
	v_permlane16_swap_b32_e32 v216, v218
	v_permlane16_swap_b32_e32 v217, v219
	global_store_dwordx4 v242, v[216:219], s[40:41] offset:256
	s_cmp_eq_u32 s101, 0
	s_cbranch_scc1 .Lg3_epi_ret0
	s_branch .LBB0_751
; DI unsigned xb_ld(unsigned* p) { return __hip_atomic_load(p, __ATOMIC_RELAXED, __HIP_MEMORY_SCOPE_AGENT); }
; DI unsigned xb_add(unsigned* p, unsigned v) { return __hip_atomic_fetch_add(p, v, __ATOMIC_RELAXED, __HIP_MEMORY_SCOPE_AGENT); }
; DI void xcd_barrier_complete(unsigned* bar, unsigned x, unsigned& nloc, unsigned& nx) {
;   const unsigned G = gridDim.x * gridDim.y * gridDim.z;
;   unsigned sum, cnt, mine, sp = 0u;
;   for (;;) {
;     sum = 0u; cnt = 0u; mine = 0u;
; #pragma unroll
;     for (unsigned j = 0; j < 16; ++j) { const unsigned c = xb_ld(&bar[XB_XCNT(j)]); sum += c; cnt += (c > 0u) ? 1u : 0u; mine = (j == x) ? c : mine; }
;     if (sum == G) break;
; DI void xcd_barrier(const XcdBarrier& b) {
;   asm volatile("s_waitcnt vmcnt(0)" ::: "memory");
;   __syncthreads();
;   if (threadIdx.x == 0) {
;     unsigned* bar = b.bar;
;     __builtin_amdgcn_s_waitcnt(0);
;     unsigned nloc = b.st[0], nx = b.st[1];
;     if (nloc == 0u) { xcd_barrier_complete(bar, b.x, nloc, nx); b.st[0] = nloc; b.st[1] = nx; }
;     const unsigned old = xb_add(&bar[XB_XSUB(b.x)], 1u);
.Lg3_w22:
	s_waitcnt vmcnt(22)
	s_branch .Lg3_wd
.LBB0_751:
	s_getreg_b32 s2, hwreg(HW_REG_XCC_ID, 0, 4)
	s_waitcnt vmcnt(0)
	s_barrier
	s_mov_b64 s[6:7], exec
	v_readlane_b32 s0, v251, 5
	v_readlane_b32 s1, v251, 6
	s_and_b64 s[0:1], s[6:7], s[0:1]
	v_readlane_b32 s25, v251, 8
	s_mov_b64 exec, s[0:1]
	s_cbranch_execz .LBB0_803
	s_ashr_i32 s1, s33, 31
	v_readlane_b32 s4, v251, 3
	v_readlane_b32 s5, v251, 4
	s_add_u32 s0, s4, s33
	s_addc_u32 s1, s5, s1
	v_mov_b32_e32 v0, 0x20800
	s_load_dwordx2 s[0:1], s[0:1], 0xf8
	s_waitcnt vmcnt(0) expcnt(0) lgkmcnt(0)
	ds_read_b32 v2, v0
	v_mov_b32_e32 v0, 0x20804
	ds_read_b32 v0, v0
	s_and_b32 s33, s2, 15
	s_waitcnt lgkmcnt(1)
	v_cmp_ne_u32_e32 vcc, 0, v2
	s_cbranch_vccnz .LBB0_767
	s_add_u32 s2, s0, 0x16a4300
	s_addc_u32 s3, s1, 0
	s_add_u32 s4, s0, 0x16a4500
	s_addc_u32 s5, s1, 0
	s_add_u32 s8, s0, 0x16a4600
	s_addc_u32 s9, s1, 0
	s_add_u32 s10, s0, 0x16a4700
	s_addc_u32 s11, s1, 0
	s_add_u32 s12, s0, 0x16a4800
	s_addc_u32 s13, s1, 0
	s_add_u32 s14, s0, 0x16a4900
	s_addc_u32 s15, s1, 0
	s_add_u32 s16, s0, 0x16a4a00
	s_addc_u32 s17, s1, 0
	s_add_u32 s18, s0, 0x16a4b00
	s_addc_u32 s19, s1, 0
	s_add_u32 s20, s0, 0x16a4c00
	s_addc_u32 s21, s1, 0
	s_add_u32 s22, s0, 0x16a4d00
	s_addc_u32 s23, s1, 0
	s_add_u32 s24, s0, 0x16a4e00
	s_addc_u32 s25, s1, 0
	s_add_u32 s26, s0, 0x16a4f00
	s_addc_u32 s27, s1, 0
	s_add_u32 s28, s0, 0x16a5000
	s_addc_u32 s29, s1, 0
	s_add_u32 s30, s0, 0x16a5100
	s_addc_u32 s31, s1, 0
	s_add_u32 s34, s0, 0x16a5200
	s_addc_u32 s35, s1, 0
	s_add_u32 s36, s0, 0x16a5300
	s_addc_u32 s37, s1, 0
	s_add_u32 s38, s0, 0x16a5400
	s_addc_u32 s39, s1, 0
	s_mov_b32 s46, 1
	v_mov_b32_e32 v16, 0
	s_branch .LBB0_755

; DI unsigned pack2(float a, float b) { const hwf32x2 v = {a, b}; const hwbf16x2 r = __builtin_convertvector(v, hwbf16x2); return __builtin_bit_cast(unsigned, r); }
; DI void tile8_order(int L, int nM, int nN, int& pm, int& pn) {
;   const int t = tile_remap(L, nM * nN), nig = 8 * nN, gid = t / nig, fm = gid * 8, gsz = (nM - fm) < 8 ? (nM - fm) : 8;
;   pm = fm + ((t % nig) % gsz); pn = (t % nig) / gsz;
; }
; DI void st_bf4(bf16_t* p, float a, float b, float c, float d) { uint2 v; v.x = pack2(a, b); v.y = pack2(c, d); *(uint2*)p = v; }
; DI void ld_bf4(const bf16_t* p, float& a, float& b, float& c, float& d) {
;   const uint2 v = *(const uint2*)p; a = __uint_as_float(v.x << 16); b = __uint_as_float(v.x & 0xffff0000u); c = __uint_as_float(v.y << 16); d = __uint_as_float(v.y & 0xffff0000u);
; }
; template <class FL, class FS>
; DI void gemm_dispatch(const Sub& s, char* lds_all, const bf16_t* A, const bf16_t* Bt, const int nN256, FL fl, FS fs) {
;   if (!s.samp) {
;     const int nM = 256;
;     for (int L = blockIdx.x; L < nM * nN256; L += gridDim.x) {
;       int pm, pn; tile8_order(L, nM, nN256, pm, pn);
;       gemm8_tile(lds_all, A, Bt, D, pm * 256, pn * 256, fl, fs);
.LBB0_2086:
	s_or_b64 exec, exec, s[6:7]
	v_readlane_b32 s2, v251, 11
	v_readlane_b32 s3, v251, 12
	s_mov_b32 s33, 0
	s_mov_b32 s0, 0
	s_waitcnt lgkmcnt(0)
	v_mov_b32_e32 v0, v182
	s_and_b64 vcc, exec, s[2:3]
	s_barrier
	s_cbranch_vccnz .LBB0_2096
	s_ashr_i32 s1, s0, 31
	v_readlane_b32 s2, v251, 3
	v_readlane_b32 s3, v251, 4
	s_add_u32 s0, s2, s0
	s_addc_u32 s1, s3, s1
	s_load_dwordx4 s[4:7], s[0:1], 0xf0
	s_mov_b32 s44, 0x10000
	s_mov_b32 s45, 0x14000
	s_mov_b64 s[8:9], 0x80
	s_mov_b32 s50, 0x18000
	s_waitcnt lgkmcnt(0)
	s_add_u32 s46, s6, 0x11900000
	s_addc_u32 s47, s7, 0
	s_add_u32 s48, s6, 0xe80000
	s_addc_u32 s49, s7, 0
	s_add_u32 s10, s6, 0x1080000
	s_addc_u32 s11, s7, 0
	s_add_u32 s12, s6, 0x19980000
	s_addc_u32 s13, s7, 0
	s_mov_b32 s51, 0x1c000
	s_mov_b64 s[14:15], 0x11940080
	s_mov_b64 s[16:17], 0xe80100
	s_mov_b64 s[18:19], 0x11900100
	s_mov_b64 s[20:21], 0xec0100
	s_mov_b64 s[22:23], 0x11940100
	s_mov_b64 s[24:25], 0xe80180
	s_mov_b64 s[26:27], 0x11900180
	s_mov_b64 s[28:29], 0xec0180
	s_mov_b64 s[30:31], 0x100
	s_mov_b64 s[34:35], 0x780
	s_movk_i32 s52, 0x100
	s_movk_i32 s53, 0x3000
	s_mov_b64 s[36:37], 0x2000
	v_mov_b32_e32 v144, 1
	v_readlane_b32 s1, v251, 0
	s_mov_b32 s98, 0
	s_branch .LBB0_2089
.LBB0_2089:
	s_lshl_b32 s0, s1, 7
	s_and_b32 s0, s0, 0x380
	s_mov_b32 s56, s1
	s_ashr_i32 s1, s1, 3
	s_add_i32 s0, s0, s1
	v_mov_b32_e32 v140, v182
	s_ashr_i32 s1, s0, 31
	s_lshr_b32 s1, s1, 27
	v_ashrrev_i32_e32 v200, 31, v140
	v_lshrrev_b32_e32 v200, 26, v200
	s_add_i32 s1, s0, s1
	v_add_u32_e32 v200, v140, v200
	s_and_b32 s2, s1, 0xffe0
	v_ashrrev_i32_e32 v201, 6, v200
	v_bfe_i32 v200, v140, 27, 1
	s_sub_i32 s0, s0, s2
	v_lshlrev_b32_e32 v150, 4, v140
	v_lshrrev_b32_e32 v200, 22, v200
	s_bfe_i32 s2, s0, 0x80000
	v_add_u32_e32 v200, v150, v200
	s_bfe_u32 s2, s2, 0x3000c
	v_and_b32_e32 v200, 0xfffffc00, v200
	s_add_i32 s2, s0, s2
	v_sub_u32_e32 v200, v150, v200
	s_bfe_i32 s3, s2, 0x80000
	s_and_b32 s2, s2, 0xf8
	v_lshrrev_b32_e32 v202, 4, v200
	s_sub_i32 s0, s0, s2
	v_bitop3_b32 v202, v202, v200, 32 bitop3:0x6c
	v_ashrrev_i32_e32 v200, 31, v200
	s_sext_i32_i8 s0, s0
	s_lshl_b32 s1, s1, 6
	v_lshrrev_b32_e32 v200, 26, v200
	s_sext_i32_i16 s3, s3
	s_and_b32 s1, s1, 0xfffff800
	s_lshl_b32 s0, s0, 8
	v_lshlrev_b32_e32 v203, 3, v201
	v_add_u32_e32 v200, v202, v200
	s_add_i32 s40, s0, s1
	s_lshl_b32 s0, s3, 5
	v_and_b32_e32 v203, -16, v203
	v_ashrrev_i32_e32 v204, 6, v200
	s_and_b32 s38, s0, 0xffffff00
	v_add_u32_e32 v200, v204, v203
	v_mul_i32_i24_e32 v203, 64, v204
	s_ashr_i32 s39, s38, 31
	v_lshlrev_b32_e32 v201, 5, v201
	v_sub_u32_e32 v202, v202, v203
	s_lshl_b64 s[0:1], s[38:39], 11
	v_and_b32_e32 v201, 32, v201
	v_ashrrev_i16_sdwa v202, v144, sext(v202) dst_sel:DWORD dst_unused:UNUSED_PAD src0_sel:DWORD src1_sel:BYTE_0
	s_add_u32 s2, s48, s0
	v_add_u32_sdwa v202, v201, sext(v202) dst_sel:DWORD dst_unused:UNUSED_PAD src0_sel:DWORD src1_sel:WORD_0
	v_ashrrev_i32_e32 v201, 31, v200
	s_addc_u32 s3, s49, s1
	v_lshlrev_b64 v[200:201], 11, v[200:201]
	v_ashrrev_i32_e32 v203, 31, v202
	v_lshl_add_u64 v[204:205], s[2:3], 0, v[200:201]
	v_lshlrev_b64 v[202:203], 1, v[202:203]
	v_add_u32_e32 v156, 0x2000, v150
	v_lshl_add_u64 v[208:209], v[204:205], 0, v[202:203]
	v_ashrrev_i32_e32 v204, 31, v156
	v_lshrrev_b32_e32 v204, 22, v204
	v_add_u32_e32 v204, v156, v204
	v_ashrrev_i32_e32 v205, 10, v204
	v_mul_i32_i24_e32 v204, 0x400, v205
	v_sub_u32_e32 v204, v156, v204
	v_lshrrev_b32_e32 v206, 4, v204
	v_bitop3_b32 v206, v206, v204, 32 bitop3:0x6c
	v_ashrrev_i32_e32 v207, 31, v206
	v_lshrrev_b32_e32 v207, 26, v207
	v_add_u32_e32 v207, v206, v207
	v_lshlrev_b32_e32 v204, 3, v205
	v_ashrrev_i32_e32 v210, 6, v207
	v_and_b32_e32 v207, 0xc0, v207
	v_and_b32_e32 v204, -16, v204
	v_lshlrev_b32_e32 v205, 5, v205
	v_sub_u32_e32 v206, v206, v207
	v_add_u32_e32 v204, v210, v204
	v_and_b32_e32 v205, 32, v205
	v_ashrrev_i16_sdwa v206, v144, sext(v206) dst_sel:DWORD dst_unused:UNUSED_PAD src0_sel:DWORD src1_sel:BYTE_0
	v_add_u32_e32 v152, 0x10000, v150
	v_add_u32_sdwa v206, v205, sext(v206) dst_sel:DWORD dst_unused:UNUSED_PAD src0_sel:DWORD src1_sel:WORD_0
	v_ashrrev_i32_e32 v205, 31, v204
	v_readfirstlane_b32 s39, v152
	v_lshlrev_b64 v[204:205], 11, v[204:205]
	v_add_u32_e32 v158, 0x12000, v150
	s_mov_b32 m0, s39
	v_lshl_add_u64 v[210:211], s[2:3], 0, v[204:205]
	v_readfirstlane_b32 s2, v158
	s_ashr_i32 s41, s40, 31
	global_load_lds_dwordx4 v[208:209], off
	s_mov_b32 m0, s2
	s_lshl_b64 s[2:3], s[40:41], 11
	s_add_u32 s42, s46, s2
	s_addc_u32 s43, s47, s3
	v_lshl_add_u64 v[212:213], s[42:43], 0, v[200:201]
	v_lshl_add_u64 v[214:215], s[42:43], 0, v[204:205]
	s_or_b32 s42, s38, 0x80
	s_ashr_i32 s43, s42, 31
	s_lshl_b64 s[42:43], s[42:43], 11
	s_add_u32 s42, s48, s42
	v_ashrrev_i32_e32 v207, 31, v206
	s_addc_u32 s43, s49, s43
	v_lshlrev_b64 v[206:207], 1, v[206:207]
	s_waitcnt vmcnt(0)
; #define STAGE(P, BASE, br, kt) do { const long _g = (long)(br) * K + (long)(kt) * 64; \
;     _Pragma("unroll") for (int _i = 0; _i < 2; ++_i) { const int _b = tidx * 16 + _i * 8192; int _r, _c; stage_rc8(_b, _r, _c); \
;       __builtin_amdgcn_global_load_lds((const unsigned*)(BASE + _g + (long)_r * K + _c), (LAS unsigned*)((LAS char*)(P) + _b), 16, 0, 0); } } while (0)
; #define LDA(dst, b, h) _Pragma("unroll") for (int m = 0; m < 4; ++m) _Pragma("unroll") for (int k = 0; k < 2; ++k) \
;     dst[m][k] = *reinterpret_cast<const bf16x8*>((const char*)SA(b, h) + lds_byte8(wr * 64 + m * 16 + fr, k * 32 + fq * 8))
; #define LDB(dst, b, h) _Pragma("unroll") for (int n = 0; n < 2; ++n) _Pragma("unroll") for (int k = 0; k < 2; ++k) \
;     dst[n][k] = *reinterpret_cast<const bf16x8*>((const char*)SB(b, h) + lds_byte8(wc * 32 + n * 16 + fr, k * 32 + fq * 8))
; #define WAIT_V(n) asm volatile("s_waitcnt vmcnt(" #n ")" ::: "memory")
; #define BAR __builtin_amdgcn_s_barrier()
; #define SCHED __builtin_amdgcn_sched_barrier(0)
; template <class FL, class FS>
; DI void gemm8_tile(char* shmc, const bf16_t* __restrict__ A, const bf16_t* __restrict__ Bt, const int K, const int brow, const int bcol, FL fl, FS fs) {
;     ...
;   STAGE(SB(0, 0), Bt, bcol, 0); STAGE(SA(0, 0), A, brow, 0);
;   STAGE(SB(0, 1), Bt, bcol + HALF, 0); STAGE(SA(0, 1), A, brow + HALF, 0);
;   if (wr == 1) BAR;
;   WAIT_V(4); BAR;
;   STAGE(SB(1, 0), Bt, bcol, 1); STAGE(SA(1, 0), A, brow, 1); STAGE(SB(1, 1), Bt, bcol + HALF, 1);
;   WAIT_V(6); BAR;
;   for (int t = 0; t < nt - 2; t += 2) {
;     LDB(B0, 0, 0); SCHED; LDA(At, 0, 0); STAGE(SA(1, 1), A, brow + HALF, t + 1);
	v_lshl_add_u64 v[216:217], s[42:43], 0, v[200:201]
	v_lshl_add_u64 v[218:219], s[42:43], 0, v[204:205]
	s_or_b32 s42, s40, 0x80
	v_lshl_add_u64 v[210:211], v[210:211], 0, v[206:207]
	v_readfirstlane_b32 s39, v150
	s_ashr_i32 s43, s42, 31
	global_load_lds_dwordx4 v[210:211], off
	v_lshl_add_u64 v[212:213], v[212:213], 0, v[202:203]
	s_mov_b32 m0, s39
	v_readfirstlane_b32 s39, v156
	v_add_u32_e32 v160, 0x14000, v150
	s_lshl_b64 s[42:43], s[42:43], 11
	global_load_lds_dwordx4 v[212:213], off
	v_lshl_add_u64 v[214:215], v[214:215], 0, v[206:207]
	s_mov_b32 m0, s39
	v_readfirstlane_b32 s39, v160
	v_add_u32_e32 v161, 0x16000, v150
	s_add_u32 s42, s46, s42
	global_load_lds_dwordx4 v[214:215], off
	v_lshl_add_u64 v[216:217], v[216:217], 0, v[202:203]
	s_mov_b32 m0, s39
	v_readfirstlane_b32 s39, v161
	s_addc_u32 s43, s47, s43
	v_add_u32_e32 v162, 0x4000, v150
	global_load_lds_dwordx4 v[216:217], off
	v_lshl_add_u64 v[218:219], v[218:219], 0, v[206:207]
	s_mov_b32 m0, s39
	v_lshl_add_u64 v[220:221], s[42:43], 0, v[200:201]
	v_readfirstlane_b32 s39, v162
	v_add_u32_e32 v163, 0x6000, v150
	global_load_lds_dwordx4 v[218:219], off
	v_lshl_add_u64 v[128:129], v[220:221], 0, v[202:203]
	s_mov_b32 m0, s39
	v_lshl_add_u64 v[220:221], s[42:43], 0, v[204:205]
	v_readfirstlane_b32 s39, v163
	global_load_lds_dwordx4 v[128:129], off
	v_lshl_add_u64 v[130:131], v[220:221], 0, v[206:207]
	s_mov_b32 m0, s39
	v_ashrrev_i32_e32 v220, 8, v140
	global_load_lds_dwordx4 v[130:131], off
	v_add_u32_e32 v164, 0x18000, v150
	v_add_u32_e32 v165, 0x1a000, v150
	v_readfirstlane_b32 s39, v164
	v_lshl_add_u64 v[208:209], v[208:209], 0, s[8:9]
	s_mov_b32 m0, s39
	v_readfirstlane_b32 s39, v165
	v_add_u32_e32 v166, 0x8000, v150
	global_load_lds_dwordx4 v[208:209], off
	v_lshl_add_u64 v[208:209], v[210:211], 0, s[8:9]
	s_mov_b32 m0, s39
	v_readfirstlane_b32 s39, v166
	v_add_u32_e32 v167, 0xa000, v150
	global_load_lds_dwordx4 v[208:209], off
	v_lshl_add_u64 v[208:209], v[212:213], 0, s[8:9]
	s_mov_b32 m0, s39
	v_readfirstlane_b32 s39, v167
	v_add_u32_e32 v168, 0x1c000, v150
	global_load_lds_dwordx4 v[208:209], off
	v_lshl_add_u64 v[208:209], v[214:215], 0, s[8:9]
	s_mov_b32 m0, s39
	v_readfirstlane_b32 s39, v168
	v_add_u32_e32 v170, 0x1e000, v150
	global_load_lds_dwordx4 v[208:209], off
	v_lshl_add_u64 v[208:209], v[216:217], 0, s[8:9]
	s_mov_b32 m0, s39
	v_readfirstlane_b32 s39, v170
	global_load_lds_dwordx4 v[208:209], off
	v_lshl_add_u64 v[208:209], v[218:219], 0, s[8:9]
	s_mov_b32 m0, s39
	v_and_b32_e32 v143, 15, v140
	global_load_lds_dwordx4 v[208:209], off
	v_bfe_u32 v142, v140, 4, 2
	v_lshlrev_b32_e32 v212, 2, v140
	v_lshlrev_b32_e32 v208, 4, v142
	v_lshlrev_b32_e32 v209, 6, v143
	v_and_b32_e32 v212, 32, v212
	v_or_b32_e32 v211, v208, v209
	v_bitop3_b32 v213, v208, v212, v209 bitop3:0x36
	v_lshlrev_b32_e32 v209, 6, v140
	v_and_b32_e32 v209, 0x3c0, v209
	v_bitop3_b32 v214, v211, s44, v212 bitop3:0xde
	v_bitop3_b32 v215, v211, s45, v212 bitop3:0xde
	v_bitop3_b32 v216, v211, s50, v212 bitop3:0xde
	v_bitop3_b32 v211, v211, s51, v212 bitop3:0xde
	v_bitop3_b32 v212, v209, v212, v208 bitop3:0x36
	v_lshl_add_u64 v[208:209], s[0:1], 0, v[200:201]
	v_lshl_add_u64 v[200:201], s[2:3], 0, v[200:201]
	v_bfe_u32 v141, v140, 6, 2
	v_lshlrev_b32_e32 v217, 13, v220
	v_lshl_add_u64 v[136:137], v[200:201], 0, v[202:203]
	v_lshl_add_u64 v[200:201], s[2:3], 0, v[204:205]
	v_lshlrev_b32_e32 v210, 12, v141
	v_lshlrev_b32_e32 v145, 6, v220
	v_or_b32_e32 v218, 0x800, v217
	v_or_b32_e32 v219, 0x1000, v217
	v_or_b32_e32 v220, 0x1800, v217
	v_lshl_add_u64 v[132:133], v[208:209], 0, v[202:203]
	v_lshl_add_u64 v[208:209], s[0:1], 0, v[204:205]
	v_lshl_add_u64 v[138:139], v[200:201], 0, v[206:207]
	v_lshl_add_u64 v[134:135], v[208:209], 0, v[206:207]
	v_add_u32_e32 v173, v214, v210
	v_add_u32_e32 v155, v213, v217
	v_add_u32_e32 v154, v212, v218
	v_add_u32_e32 v153, v212, v219
	v_add_u32_e32 v151, v212, v220
	v_add_u32_e32 v172, 0xc000, v150
	v_add_u32_e32 v171, 0xe000, v150
	v_add_u32_e32 v169, v215, v210
	v_add_u32_e32 v159, v216, v210
	v_add_u32_e32 v157, v211, v210
	v_lshl_add_u64 v[222:223], s[6:7], 0, v[136:137]
	v_readfirstlane_b32 s1, v172
	v_lshl_add_u64 v[222:223], v[222:223], 0, s[14:15]
	s_mov_b32 m0, s1
	v_lshl_add_u64 v[224:225], s[6:7], 0, v[138:139]
	v_readfirstlane_b32 s1, v171
	global_load_lds_dwordx4 v[222:223], off
	v_lshl_add_u64 v[224:225], v[224:225], 0, s[14:15]
	s_mov_b32 m0, s1
	s_nop 0
	global_load_lds_dwordx4 v[224:225], off
	s_cmp_eq_u32 s98, 0
	s_cbranch_scc1 .Lg5_first
	s_mov_b32 s101, 0
	s_branch .Lg5_epi
.Lg5_epi_ret0:
	v_lshrrev_b32_e32 v222, 8, v182
	v_cmp_eq_u32_e32 vcc, 1, v222
	s_and_saveexec_b64 s[42:43], vcc
	s_cbranch_execz .Lg5_nba
	s_barrier
.Lg5_nba:
	s_or_b64 exec, exec, s[42:43]
	s_waitcnt vmcnt(28)
	s_barrier
	s_waitcnt vmcnt(24)
	s_branch .Lg5_zero

; #define STAGE(P, BASE, br, kt) do { const long _g = (long)(br) * K + (long)(kt) * 64; \
;     _Pragma("unroll") for (int _i = 0; _i < 2; ++_i) { const int _b = tidx * 16 + _i * 8192; int _r, _c; stage_rc8(_b, _r, _c); \
;       __builtin_amdgcn_global_load_lds((const unsigned*)(BASE + _g + (long)_r * K + _c), (LAS unsigned*)((LAS char*)(P) + _b), 16, 0, 0); } } while (0)
; #define WAIT_V(n) asm volatile("s_waitcnt vmcnt(" #n ")" ::: "memory")
; #define BAR __builtin_amdgcn_s_barrier()
; template <class FL, class FS>
; DI void gemm8_tile(char* shmc, const bf16_t* __restrict__ A, const bf16_t* __restrict__ Bt, const int K, const int brow, const int bcol, FL fl, FS fs) {
;     ...
;   if (wr == 1) BAR;
;   WAIT_V(4); BAR;
;   STAGE(SB(1, 0), Bt, bcol, 1); STAGE(SA(1, 0), A, brow, 1); STAGE(SB(1, 1), Bt, bcol + HALF, 1);
;   WAIT_V(6); BAR;
.Lg5_nbb:
	s_or_b64 exec, exec, s[42:43]
	s_waitcnt vmcnt(12)
	s_barrier
	s_waitcnt vmcnt(8)

; #define STAGE(P, BASE, br, kt) do { const long _g = (long)(br) * K + (long)(kt) * 64; \
;     _Pragma("unroll") for (int _i = 0; _i < 2; ++_i) { const int _b = tidx * 16 + _i * 8192; int _r, _c; stage_rc8(_b, _r, _c); \
;       __builtin_amdgcn_global_load_lds((const unsigned*)(BASE + _g + (long)_r * K + _c), (LAS unsigned*)((LAS char*)(P) + _b), 16, 0, 0); } } while (0)
; #define LDA(dst, b, h) _Pragma("unroll") for (int m = 0; m < 4; ++m) _Pragma("unroll") for (int k = 0; k < 2; ++k) \
;     dst[m][k] = *reinterpret_cast<const bf16x8*>((const char*)SA(b, h) + lds_byte8(wr * 64 + m * 16 + fr, k * 32 + fq * 8))
; #define LDB(dst, b, h) _Pragma("unroll") for (int n = 0; n < 2; ++n) _Pragma("unroll") for (int k = 0; k < 2; ++k) \
;     dst[n][k] = *reinterpret_cast<const bf16x8*>((const char*)SB(b, h) + lds_byte8(wc * 32 + n * 16 + fr, k * 32 + fq * 8))
; #define MMA(ai, bj, At_, Bt_) do { __builtin_amdgcn_s_setprio(1); \
;     _Pragma("unroll") for (int m = 0; m < 4; ++m) _Pragma("unroll") for (int n = 0; n < 2; ++n) _Pragma("unroll") for (int k = 0; k < 2; ++k) \
;       acc[ai][bj][m][n] = MFMA16(Bt_[n][k], At_[m][k], acc[ai][bj][m][n]); \
;     __builtin_amdgcn_s_setprio(0); } while (0)
; #define WAIT_V(n) asm volatile("s_waitcnt vmcnt(" #n ")" ::: "memory")
; #define WAIT_L(n) asm volatile("s_waitcnt lgkmcnt(" #n ")" ::: "memory")
; #define BAR __builtin_amdgcn_s_barrier()
; #define SCHED __builtin_amdgcn_sched_barrier(0)
; template <class FL, class FS>
; DI void gemm8_tile(char* shmc, const bf16_t* __restrict__ A, const bf16_t* __restrict__ Bt, const int K, const int brow, const int bcol, FL fl, FS fs) {
;     ...
;   for (int t = 0; t < nt - 2; t += 2) {
;     LDB(B0, 0, 0); SCHED; LDA(At, 0, 0); STAGE(SA(1, 1), A, brow + HALF, t + 1);
;     WAIT_L(8); BAR; WAIT_L(0); MMA(0, 0, At, B0); BAR; SCHED;
;     LDB(B1, 0, 1); STAGE(SB(0, 0), Bt, bcol, t + 2);
;     BAR; WAIT_L(0); MMA(0, 1, At, B1); BAR;
;     LDA(At, 0, 1); STAGE(SA(0, 0), A, brow, t + 2);
;     BAR; WAIT_L(0); MMA(1, 0, At, B0); BAR; SCHED;
;     STAGE(SB(0, 1), Bt, bcol + HALF, t + 2);
;     WAIT_V(6); BAR; MMA(1, 1, At, B1); BAR;
.LBB0_2092:
	ds_read_b128 v[174:177], v173
	ds_read_b128 v[178:181], v173 offset:1024
	ds_read_b128 v[184:187], v173 offset:2048
	ds_read_b128 v[188:191], v173 offset:3072
	v_lshl_add_u64 v[240:241], s[6:7], 0, v[136:137]
	v_readfirstlane_b32 s1, v172
	v_lshl_add_u64 v[224:225], v[240:241], 0, s[14:15]
	s_mov_b32 m0, s1
	v_lshl_add_u64 v[242:243], s[6:7], 0, v[138:139]
	v_readfirstlane_b32 s1, v171
	ds_read_b128 v[192:195], v155
	ds_read_b128 v[196:199], v155 offset:1024
	ds_read_b128 v[200:203], v154
	ds_read_b128 v[204:207], v154 offset:1024
	ds_read_b128 v[208:211], v153
	ds_read_b128 v[212:215], v153 offset:1024
	ds_read_b128 v[216:219], v151
	ds_read_b128 v[220:223], v151 offset:1024
	s_cmp_eq_u32 s0, -2
	s_cbranch_scc1 .Lg5_p1skip
	global_load_lds_dwordx4 v[224:225], off
	v_lshl_add_u64 v[224:225], v[242:243], 0, s[14:15]
	s_mov_b32 m0, s1
	s_nop 0
	global_load_lds_dwordx4 v[224:225], off
.Lg5_p1skip:
	s_waitcnt lgkmcnt(8)
	s_barrier
	s_waitcnt lgkmcnt(0)
	s_setprio 1
	s_waitcnt lgkmcnt(0)
	v_mfma_f32_16x16x32_bf16 v[124:127], v[174:177], v[192:195], v[124:127]
	v_mfma_f32_16x16x32_bf16 v[120:123], v[184:187], v[192:195], v[120:123]
	v_mfma_f32_16x16x32_bf16 v[116:119], v[174:177], v[200:203], v[116:119]
	v_mfma_f32_16x16x32_bf16 v[112:115], v[184:187], v[200:203], v[112:115]
	v_mfma_f32_16x16x32_bf16 v[108:111], v[174:177], v[208:211], v[108:111]
	v_mfma_f32_16x16x32_bf16 v[104:107], v[184:187], v[208:211], v[104:107]
	v_mfma_f32_16x16x32_bf16 v[100:103], v[174:177], v[216:219], v[100:103]
	v_mfma_f32_16x16x32_bf16 v[96:99], v[184:187], v[216:219], v[96:99]
	v_mfma_f32_16x16x32_bf16 v[124:127], v[178:181], v[196:199], v[124:127]
	v_mfma_f32_16x16x32_bf16 v[120:123], v[188:191], v[196:199], v[120:123]
	v_mfma_f32_16x16x32_bf16 v[116:119], v[178:181], v[204:207], v[116:119]
	v_mfma_f32_16x16x32_bf16 v[112:115], v[188:191], v[204:207], v[112:115]
	v_mfma_f32_16x16x32_bf16 v[108:111], v[178:181], v[212:215], v[108:111]
	v_mfma_f32_16x16x32_bf16 v[104:107], v[188:191], v[212:215], v[104:107]
	v_mfma_f32_16x16x32_bf16 v[100:103], v[178:181], v[220:223], v[100:103]
	v_mfma_f32_16x16x32_bf16 v[96:99], v[188:191], v[220:223], v[96:99]
	s_setprio 0
	s_barrier
	v_lshl_add_u64 v[244:245], s[6:7], 0, v[132:133]
	v_readfirstlane_b32 s1, v152
	v_lshl_add_u64 v[246:247], v[244:245], 0, s[16:17]
	s_mov_b32 m0, s1
	ds_read_b128 v[224:227], v169
	ds_read_b128 v[228:231], v169 offset:1024
	ds_read_b128 v[232:235], v169 offset:2048
	ds_read_b128 v[236:239], v169 offset:3072
	global_load_lds_dwordx4 v[246:247], off
	v_lshl_add_u64 v[246:247], s[6:7], 0, v[134:135]
	v_readfirstlane_b32 s1, v158
	v_lshl_add_u64 v[248:249], v[246:247], 0, s[16:17]
	s_mov_b32 m0, s1
	s_nop 0
	global_load_lds_dwordx4 v[248:249], off
	s_barrier
	s_waitcnt lgkmcnt(0)
	s_setprio 1
	s_waitcnt lgkmcnt(0)
	v_mfma_f32_16x16x32_bf16 v[92:95], v[224:227], v[192:195], v[92:95]
	v_mfma_f32_16x16x32_bf16 v[88:91], v[232:235], v[192:195], v[88:91]
	v_mfma_f32_16x16x32_bf16 v[84:87], v[224:227], v[200:203], v[84:87]
	v_mfma_f32_16x16x32_bf16 v[80:83], v[232:235], v[200:203], v[80:83]
	v_mfma_f32_16x16x32_bf16 v[76:79], v[224:227], v[208:211], v[76:79]
	v_mfma_f32_16x16x32_bf16 v[72:75], v[232:235], v[208:211], v[72:75]
	v_mfma_f32_16x16x32_bf16 v[68:71], v[224:227], v[216:219], v[68:71]
	v_mfma_f32_16x16x32_bf16 v[64:67], v[232:235], v[216:219], v[64:67]
	v_mfma_f32_16x16x32_bf16 v[92:95], v[228:231], v[196:199], v[92:95]
	v_mfma_f32_16x16x32_bf16 v[88:91], v[236:239], v[196:199], v[88:91]
	v_mfma_f32_16x16x32_bf16 v[84:87], v[228:231], v[204:207], v[84:87]
	v_mfma_f32_16x16x32_bf16 v[80:83], v[236:239], v[204:207], v[80:83]
	v_mfma_f32_16x16x32_bf16 v[76:79], v[228:231], v[212:215], v[76:79]
	v_mfma_f32_16x16x32_bf16 v[72:75], v[236:239], v[212:215], v[72:75]
	v_mfma_f32_16x16x32_bf16 v[68:71], v[228:231], v[220:223], v[68:71]
	v_mfma_f32_16x16x32_bf16 v[64:67], v[236:239], v[220:223], v[64:67]
	s_setprio 0
	v_readfirstlane_b32 s1, v150
	v_lshl_add_u64 v[248:249], v[240:241], 0, s[18:19]
	s_mov_b32 m0, s1
	v_readfirstlane_b32 s1, v156
	s_barrier
	ds_read_b128 v[192:195], v155 offset:16384
	ds_read_b128 v[196:199], v155 offset:17408
	ds_read_b128 v[200:203], v154 offset:16384
	ds_read_b128 v[204:207], v154 offset:17408
	ds_read_b128 v[208:211], v153 offset:16384
	ds_read_b128 v[212:215], v153 offset:17408
	ds_read_b128 v[216:219], v151 offset:16384
	ds_read_b128 v[220:223], v151 offset:17408
	global_load_lds_dwordx4 v[248:249], off
	v_lshl_add_u64 v[248:249], v[242:243], 0, s[18:19]
	s_mov_b32 m0, s1
	s_nop 0
	global_load_lds_dwordx4 v[248:249], off
	s_barrier
	s_waitcnt lgkmcnt(0)
	s_setprio 1
	s_waitcnt lgkmcnt(0)
	v_mfma_f32_16x16x32_bf16 v[60:63], v[174:177], v[192:195], v[60:63]
	v_mfma_f32_16x16x32_bf16 v[56:59], v[184:187], v[192:195], v[56:59]
	v_mfma_f32_16x16x32_bf16 v[52:55], v[174:177], v[200:203], v[52:55]
	v_mfma_f32_16x16x32_bf16 v[48:51], v[184:187], v[200:203], v[48:51]
	v_mfma_f32_16x16x32_bf16 v[44:47], v[174:177], v[208:211], v[44:47]
	v_mfma_f32_16x16x32_bf16 v[40:43], v[184:187], v[208:211], v[40:43]
	v_mfma_f32_16x16x32_bf16 v[36:39], v[174:177], v[216:219], v[36:39]
	v_mfma_f32_16x16x32_bf16 v[32:35], v[184:187], v[216:219], v[32:35]
	v_mfma_f32_16x16x32_bf16 v[60:63], v[178:181], v[196:199], v[60:63]
	v_mfma_f32_16x16x32_bf16 v[56:59], v[188:191], v[196:199], v[56:59]
	v_mfma_f32_16x16x32_bf16 v[52:55], v[178:181], v[204:207], v[52:55]
	v_mfma_f32_16x16x32_bf16 v[48:51], v[188:191], v[204:207], v[48:51]
	v_mfma_f32_16x16x32_bf16 v[44:47], v[178:181], v[212:215], v[44:47]
	v_mfma_f32_16x16x32_bf16 v[40:43], v[188:191], v[212:215], v[40:43]
	v_mfma_f32_16x16x32_bf16 v[36:39], v[178:181], v[220:223], v[36:39]
	v_mfma_f32_16x16x32_bf16 v[32:35], v[188:191], v[220:223], v[32:35]
	s_setprio 0
	s_barrier
	v_readfirstlane_b32 s1, v160
	v_lshl_add_u64 v[174:175], v[244:245], 0, s[20:21]
	s_mov_b32 m0, s1
	v_readfirstlane_b32 s1, v161
	global_load_lds_dwordx4 v[174:175], off
	v_lshl_add_u64 v[174:175], v[246:247], 0, s[20:21]
	s_mov_b32 m0, s1
	s_nop 0
	global_load_lds_dwordx4 v[174:175], off
	s_cmp_eq_u32 s0, -2
	s_cselect_b32 s101, s98, 0
	s_cmp_lg_u32 s101, 0
	s_cbranch_scc1 .Lg5_w22
	s_waitcnt vmcnt(6)
; #define STAGE(P, BASE, br, kt) do { const long _g = (long)(br) * K + (long)(kt) * 64; \
;     _Pragma("unroll") for (int _i = 0; _i < 2; ++_i) { const int _b = tidx * 16 + _i * 8192; int _r, _c; stage_rc8(_b, _r, _c); \
;       __builtin_amdgcn_global_load_lds((const unsigned*)(BASE + _g + (long)_r * K + _c), (LAS unsigned*)((LAS char*)(P) + _b), 16, 0, 0); } } while (0)
; #define LDA(dst, b, h) _Pragma("unroll") for (int m = 0; m < 4; ++m) _Pragma("unroll") for (int k = 0; k < 2; ++k) \
;     dst[m][k] = *reinterpret_cast<const bf16x8*>((const char*)SA(b, h) + lds_byte8(wr * 64 + m * 16 + fr, k * 32 + fq * 8))
; #define LDB(dst, b, h) _Pragma("unroll") for (int n = 0; n < 2; ++n) _Pragma("unroll") for (int k = 0; k < 2; ++k) \
;     dst[n][k] = *reinterpret_cast<const bf16x8*>((const char*)SB(b, h) + lds_byte8(wc * 32 + n * 16 + fr, k * 32 + fq * 8))
; #define MMA(ai, bj, At_, Bt_) do { __builtin_amdgcn_s_setprio(1); \
;     _Pragma("unroll") for (int m = 0; m < 4; ++m) _Pragma("unroll") for (int n = 0; n < 2; ++n) _Pragma("unroll") for (int k = 0; k < 2; ++k) \
;       acc[ai][bj][m][n] = MFMA16(Bt_[n][k], At_[m][k], acc[ai][bj][m][n]); \
;     __builtin_amdgcn_s_setprio(0); } while (0)
; #define WAIT_V(n) asm volatile("s_waitcnt vmcnt(" #n ")" ::: "memory")
; #define WAIT_L(n) asm volatile("s_waitcnt lgkmcnt(" #n ")" ::: "memory")
; #define BAR __builtin_amdgcn_s_barrier()
; #define SCHED __builtin_amdgcn_sched_barrier(0)
; template <class FL, class FS>
; DI void gemm8_tile(char* shmc, const bf16_t* __restrict__ A, const bf16_t* __restrict__ Bt, const int K, const int brow, const int bcol, FL fl, FS fs) {
;     ...
;     WAIT_V(6); BAR; MMA(1, 1, At, B1); BAR;
;     LDB(B0, 1, 0); SCHED; LDA(At, 1, 0); STAGE(SA(0, 1), A, brow + HALF, t + 2);
;     WAIT_L(8); BAR; WAIT_L(0); MMA(0, 0, At, B0); BAR; SCHED;
;     LDB(B1, 1, 1); STAGE(SB(1, 0), Bt, bcol, t + 3);
;     BAR; WAIT_L(0); MMA(0, 1, At, B1); BAR;
;     LDA(At, 1, 1); STAGE(SA(1, 0), A, brow, t + 3);
;     BAR; WAIT_L(0); MMA(1, 0, At, B0); BAR; SCHED;
.Lg5_wd:
	s_barrier
	s_setprio 1
	v_mfma_f32_16x16x32_bf16 v[28:31], v[224:227], v[192:195], v[28:31]
	v_mfma_f32_16x16x32_bf16 v[24:27], v[232:235], v[192:195], v[24:27]
	v_mfma_f32_16x16x32_bf16 v[20:23], v[224:227], v[200:203], v[20:23]
	v_mfma_f32_16x16x32_bf16 v[16:19], v[232:235], v[200:203], v[16:19]
	v_mfma_f32_16x16x32_bf16 v[12:15], v[224:227], v[208:211], v[12:15]
	v_mfma_f32_16x16x32_bf16 v[8:11], v[232:235], v[208:211], v[8:11]
	v_mfma_f32_16x16x32_bf16 v[4:7], v[224:227], v[216:219], v[4:7]
	v_mfma_f32_16x16x32_bf16 v[0:3], v[232:235], v[216:219], v[0:3]
	v_mfma_f32_16x16x32_bf16 v[28:31], v[228:231], v[196:199], v[28:31]
	v_mfma_f32_16x16x32_bf16 v[24:27], v[236:239], v[196:199], v[24:27]
	v_mfma_f32_16x16x32_bf16 v[20:23], v[228:231], v[204:207], v[20:23]
	v_mfma_f32_16x16x32_bf16 v[16:19], v[236:239], v[204:207], v[16:19]
	v_mfma_f32_16x16x32_bf16 v[12:15], v[228:231], v[212:215], v[12:15]
	v_mfma_f32_16x16x32_bf16 v[8:11], v[236:239], v[212:215], v[8:11]
	v_mfma_f32_16x16x32_bf16 v[4:7], v[228:231], v[220:223], v[4:7]
	v_mfma_f32_16x16x32_bf16 v[0:3], v[236:239], v[220:223], v[0:3]
	s_setprio 0
	s_barrier
	ds_read_b128 v[174:177], v159
	ds_read_b128 v[178:181], v159 offset:1024
	ds_read_b128 v[184:187], v159 offset:2048
	ds_read_b128 v[188:191], v159 offset:3072
	v_readfirstlane_b32 s1, v162
	v_lshl_add_u64 v[224:225], v[240:241], 0, s[22:23]
	s_mov_b32 m0, s1
	v_readfirstlane_b32 s1, v163
	ds_read_b128 v[192:195], v155 offset:32768
	ds_read_b128 v[196:199], v155 offset:33792
	ds_read_b128 v[200:203], v154 offset:32768
	ds_read_b128 v[204:207], v154 offset:33792
	ds_read_b128 v[208:211], v153 offset:32768
	ds_read_b128 v[212:215], v153 offset:33792
	ds_read_b128 v[216:219], v151 offset:32768
	ds_read_b128 v[220:223], v151 offset:33792
	global_load_lds_dwordx4 v[224:225], off
	v_lshl_add_u64 v[224:225], v[242:243], 0, s[22:23]
	s_mov_b32 m0, s1
	s_nop 0
	global_load_lds_dwordx4 v[224:225], off
	s_waitcnt lgkmcnt(8)
	s_barrier
	s_waitcnt lgkmcnt(0)
	s_setprio 1
	s_waitcnt lgkmcnt(0)
	v_mfma_f32_16x16x32_bf16 v[124:127], v[174:177], v[192:195], v[124:127]
	v_mfma_f32_16x16x32_bf16 v[120:123], v[184:187], v[192:195], v[120:123]
	v_mfma_f32_16x16x32_bf16 v[116:119], v[174:177], v[200:203], v[116:119]
	v_mfma_f32_16x16x32_bf16 v[112:115], v[184:187], v[200:203], v[112:115]
	v_mfma_f32_16x16x32_bf16 v[108:111], v[174:177], v[208:211], v[108:111]
	v_mfma_f32_16x16x32_bf16 v[104:107], v[184:187], v[208:211], v[104:107]
	v_mfma_f32_16x16x32_bf16 v[100:103], v[174:177], v[216:219], v[100:103]
	v_mfma_f32_16x16x32_bf16 v[96:99], v[184:187], v[216:219], v[96:99]
	v_mfma_f32_16x16x32_bf16 v[124:127], v[178:181], v[196:199], v[124:127]
	v_mfma_f32_16x16x32_bf16 v[120:123], v[188:191], v[196:199], v[120:123]
	v_mfma_f32_16x16x32_bf16 v[116:119], v[178:181], v[204:207], v[116:119]
	v_mfma_f32_16x16x32_bf16 v[112:115], v[188:191], v[204:207], v[112:115]
	v_mfma_f32_16x16x32_bf16 v[108:111], v[178:181], v[212:215], v[108:111]
	v_mfma_f32_16x16x32_bf16 v[104:107], v[188:191], v[212:215], v[104:107]
	v_mfma_f32_16x16x32_bf16 v[100:103], v[178:181], v[220:223], v[100:103]
	v_mfma_f32_16x16x32_bf16 v[96:99], v[188:191], v[220:223], v[96:99]
	s_setprio 0
	s_barrier
	v_readfirstlane_b32 s1, v164
	v_lshl_add_u64 v[248:249], v[244:245], 0, s[24:25]
	s_mov_b32 m0, s1
	v_readfirstlane_b32 s1, v165
	ds_read_b128 v[224:227], v157
	ds_read_b128 v[228:231], v157 offset:1024
	ds_read_b128 v[232:235], v157 offset:2048
	ds_read_b128 v[236:239], v157 offset:3072
	global_load_lds_dwordx4 v[248:249], off
	v_lshl_add_u64 v[248:249], v[246:247], 0, s[24:25]
	s_mov_b32 m0, s1
	s_nop 0
	global_load_lds_dwordx4 v[248:249], off
	s_barrier
	s_waitcnt lgkmcnt(0)
	s_setprio 1
	s_waitcnt lgkmcnt(0)
	v_mfma_f32_16x16x32_bf16 v[92:95], v[224:227], v[192:195], v[92:95]
	v_mfma_f32_16x16x32_bf16 v[88:91], v[232:235], v[192:195], v[88:91]
	v_mfma_f32_16x16x32_bf16 v[84:87], v[224:227], v[200:203], v[84:87]
	v_mfma_f32_16x16x32_bf16 v[80:83], v[232:235], v[200:203], v[80:83]
	v_mfma_f32_16x16x32_bf16 v[76:79], v[224:227], v[208:211], v[76:79]
	v_mfma_f32_16x16x32_bf16 v[72:75], v[232:235], v[208:211], v[72:75]
	v_mfma_f32_16x16x32_bf16 v[68:71], v[224:227], v[216:219], v[68:71]
	v_mfma_f32_16x16x32_bf16 v[64:67], v[232:235], v[216:219], v[64:67]
	v_mfma_f32_16x16x32_bf16 v[92:95], v[228:231], v[196:199], v[92:95]
	v_mfma_f32_16x16x32_bf16 v[88:91], v[236:239], v[196:199], v[88:91]
	v_mfma_f32_16x16x32_bf16 v[84:87], v[228:231], v[204:207], v[84:87]
	v_mfma_f32_16x16x32_bf16 v[80:83], v[236:239], v[204:207], v[80:83]
	v_mfma_f32_16x16x32_bf16 v[76:79], v[228:231], v[212:215], v[76:79]
	v_mfma_f32_16x16x32_bf16 v[72:75], v[236:239], v[212:215], v[72:75]
	v_mfma_f32_16x16x32_bf16 v[68:71], v[228:231], v[220:223], v[68:71]
	v_mfma_f32_16x16x32_bf16 v[64:67], v[236:239], v[220:223], v[64:67]
	s_setprio 0
	v_readfirstlane_b32 s1, v166
	v_lshl_add_u64 v[240:241], v[240:241], 0, s[26:27]
	s_mov_b32 m0, s1
	v_readfirstlane_b32 s1, v167
	s_barrier
	ds_read_b128 v[192:195], v155 offset:49152
	ds_read_b128 v[196:199], v155 offset:50176
	ds_read_b128 v[200:203], v154 offset:49152
	ds_read_b128 v[204:207], v154 offset:50176
	ds_read_b128 v[208:211], v153 offset:49152
	ds_read_b128 v[212:215], v153 offset:50176
	ds_read_b128 v[216:219], v151 offset:49152
	ds_read_b128 v[220:223], v151 offset:50176
	global_load_lds_dwordx4 v[240:241], off
	v_lshl_add_u64 v[240:241], v[242:243], 0, s[26:27]
	s_mov_b32 m0, s1
	s_nop 0
	global_load_lds_dwordx4 v[240:241], off
	s_barrier
; #define STAGE(P, BASE, br, kt) do { const long _g = (long)(br) * K + (long)(kt) * 64; \
;     _Pragma("unroll") for (int _i = 0; _i < 2; ++_i) { const int _b = tidx * 16 + _i * 8192; int _r, _c; stage_rc8(_b, _r, _c); \
;       __builtin_amdgcn_global_load_lds((const unsigned*)(BASE + _g + (long)_r * K + _c), (LAS unsigned*)((LAS char*)(P) + _b), 16, 0, 0); } } while (0)
; #define LDA(dst, b, h) _Pragma("unroll") for (int m = 0; m < 4; ++m) _Pragma("unroll") for (int k = 0; k < 2; ++k) \
;     dst[m][k] = *reinterpret_cast<const bf16x8*>((const char*)SA(b, h) + lds_byte8(wr * 64 + m * 16 + fr, k * 32 + fq * 8))
; #define LDB(dst, b, h) _Pragma("unroll") for (int n = 0; n < 2; ++n) _Pragma("unroll") for (int k = 0; k < 2; ++k) \
;     dst[n][k] = *reinterpret_cast<const bf16x8*>((const char*)SB(b, h) + lds_byte8(wc * 32 + n * 16 + fr, k * 32 + fq * 8))
; #define MMA(ai, bj, At_, Bt_) do { __builtin_amdgcn_s_setprio(1); \
;     _Pragma("unroll") for (int m = 0; m < 4; ++m) _Pragma("unroll") for (int n = 0; n < 2; ++n) _Pragma("unroll") for (int k = 0; k < 2; ++k) \
;       acc[ai][bj][m][n] = MFMA16(Bt_[n][k], At_[m][k], acc[ai][bj][m][n]); \
;     __builtin_amdgcn_s_setprio(0); } while (0)
; #define WAIT_V(n) asm volatile("s_waitcnt vmcnt(" #n ")" ::: "memory")
; #define WAIT_L(n) asm volatile("s_waitcnt lgkmcnt(" #n ")" ::: "memory")
; #define BAR __builtin_amdgcn_s_barrier()
; #define SCHED __builtin_amdgcn_sched_barrier(0)
; template <class FL, class FS>
; DI void gemm8_tile(char* shmc, const bf16_t* __restrict__ A, const bf16_t* __restrict__ Bt, const int K, const int brow, const int bcol, FL fl, FS fs) {
;     ...
;     BAR; WAIT_L(0); MMA(1, 0, At, B0); BAR; SCHED;
;     STAGE(SB(1, 1), Bt, bcol + HALF, t + 3);
;     WAIT_V(6); BAR; MMA(1, 1, At, B1); BAR;
;   }
;   { LDB(B0, 0, 0); LDA(At, 0, 0); STAGE(SA(1, 1), A, brow + HALF, nt - 1);
;     BAR; WAIT_L(0); MMA(0, 0, At, B0); BAR;
;     LDB(B1, 0, 1); BAR; WAIT_L(0); MMA(0, 1, At, B1); BAR;
	s_waitcnt lgkmcnt(0)
	s_setprio 1
	s_waitcnt lgkmcnt(0)
	v_mfma_f32_16x16x32_bf16 v[60:63], v[174:177], v[192:195], v[60:63]
	v_mfma_f32_16x16x32_bf16 v[56:59], v[184:187], v[192:195], v[56:59]
	v_mfma_f32_16x16x32_bf16 v[52:55], v[174:177], v[200:203], v[52:55]
	v_mfma_f32_16x16x32_bf16 v[48:51], v[184:187], v[200:203], v[48:51]
	v_mfma_f32_16x16x32_bf16 v[44:47], v[174:177], v[208:211], v[44:47]
	v_mfma_f32_16x16x32_bf16 v[40:43], v[184:187], v[208:211], v[40:43]
	v_mfma_f32_16x16x32_bf16 v[36:39], v[174:177], v[216:219], v[36:39]
	v_mfma_f32_16x16x32_bf16 v[32:35], v[184:187], v[216:219], v[32:35]
	v_mfma_f32_16x16x32_bf16 v[60:63], v[178:181], v[196:199], v[60:63]
	v_mfma_f32_16x16x32_bf16 v[56:59], v[188:191], v[196:199], v[56:59]
	v_mfma_f32_16x16x32_bf16 v[52:55], v[178:181], v[204:207], v[52:55]
	v_mfma_f32_16x16x32_bf16 v[48:51], v[188:191], v[204:207], v[48:51]
	v_mfma_f32_16x16x32_bf16 v[44:47], v[178:181], v[212:215], v[44:47]
	v_mfma_f32_16x16x32_bf16 v[40:43], v[188:191], v[212:215], v[40:43]
	v_mfma_f32_16x16x32_bf16 v[36:39], v[178:181], v[220:223], v[36:39]
	v_mfma_f32_16x16x32_bf16 v[32:35], v[188:191], v[220:223], v[32:35]
	s_setprio 0
	s_barrier
	v_readfirstlane_b32 s1, v168
	v_lshl_add_u64 v[174:175], v[244:245], 0, s[28:29]
	s_mov_b32 m0, s1
	v_readfirstlane_b32 s1, v170
	global_load_lds_dwordx4 v[174:175], off
	v_lshl_add_u64 v[174:175], v[246:247], 0, s[28:29]
	s_mov_b32 m0, s1
	s_nop 0
	global_load_lds_dwordx4 v[174:175], off
	s_waitcnt vmcnt(6)
	s_barrier
	s_setprio 1
	v_mfma_f32_16x16x32_bf16 v[28:31], v[224:227], v[192:195], v[28:31]
	v_mfma_f32_16x16x32_bf16 v[24:27], v[232:235], v[192:195], v[24:27]
	v_mfma_f32_16x16x32_bf16 v[20:23], v[224:227], v[200:203], v[20:23]
	v_mfma_f32_16x16x32_bf16 v[16:19], v[232:235], v[200:203], v[16:19]
	v_mfma_f32_16x16x32_bf16 v[12:15], v[224:227], v[208:211], v[12:15]
	v_mfma_f32_16x16x32_bf16 v[8:11], v[232:235], v[208:211], v[8:11]
	v_mfma_f32_16x16x32_bf16 v[4:7], v[224:227], v[216:219], v[4:7]
	v_mfma_f32_16x16x32_bf16 v[0:3], v[232:235], v[216:219], v[0:3]
	v_mfma_f32_16x16x32_bf16 v[28:31], v[228:231], v[196:199], v[28:31]
	v_mfma_f32_16x16x32_bf16 v[24:27], v[236:239], v[196:199], v[24:27]
	v_mfma_f32_16x16x32_bf16 v[20:23], v[228:231], v[204:207], v[20:23]
	v_mfma_f32_16x16x32_bf16 v[16:19], v[236:239], v[204:207], v[16:19]
	v_mfma_f32_16x16x32_bf16 v[12:15], v[228:231], v[212:215], v[12:15]
	v_mfma_f32_16x16x32_bf16 v[8:11], v[236:239], v[212:215], v[8:11]
	v_mfma_f32_16x16x32_bf16 v[4:7], v[228:231], v[220:223], v[4:7]
	v_mfma_f32_16x16x32_bf16 v[0:3], v[236:239], v[220:223], v[0:3]
	s_setprio 0
	s_add_i32 s0, s0, 2
	v_lshl_add_u64 v[132:133], v[132:133], 0, s[30:31]
	v_lshl_add_u64 v[134:135], v[134:135], 0, s[30:31]
	v_lshl_add_u64 v[136:137], v[136:137], 0, s[30:31]
	s_cmp_lt_u32 s0, 12
	v_lshl_add_u64 v[138:139], v[138:139], 0, s[30:31]
	s_barrier
	s_cbranch_scc1 .LBB0_2092
	v_readfirstlane_b32 s0, v172
	v_lshl_add_u64 v[128:129], v[128:129], 0, s[34:35]
	s_mov_b32 m0, s0
	v_readfirstlane_b32 s0, v171
	ds_read_b128 v[132:135], v173
	ds_read_b128 v[136:139], v173 offset:1024
	ds_read_b128 v[160:163], v173 offset:2048
	ds_read_b128 v[164:167], v173 offset:3072
	ds_read_b128 v[174:177], v155
	ds_read_b128 v[178:181], v155 offset:1024
	ds_read_b128 v[184:187], v154
	ds_read_b128 v[188:191], v154 offset:1024
	ds_read_b128 v[192:195], v153
	ds_read_b128 v[196:199], v153 offset:1024
	ds_read_b128 v[200:203], v151
	ds_read_b128 v[204:207], v151 offset:1024
	global_load_lds_dwordx4 v[128:129], off
	v_lshl_add_u64 v[128:129], v[130:131], 0, s[34:35]
	s_mov_b32 m0, s0
	s_nop 0
	global_load_lds_dwordx4 v[128:129], off
	s_barrier
	s_waitcnt lgkmcnt(0)
	s_setprio 1
	s_waitcnt lgkmcnt(0)
	v_mfma_f32_16x16x32_bf16 v[124:127], v[132:135], v[174:177], v[124:127]
	v_mfma_f32_16x16x32_bf16 v[120:123], v[160:163], v[174:177], v[120:123]
	v_mfma_f32_16x16x32_bf16 v[116:119], v[132:135], v[184:187], v[116:119]
	v_mfma_f32_16x16x32_bf16 v[96:99], v[160:163], v[200:203], v[96:99]
	v_mfma_f32_16x16x32_bf16 v[124:127], v[136:139], v[178:181], v[124:127]
	v_mfma_f32_16x16x32_bf16 v[120:123], v[164:167], v[178:181], v[120:123]
	v_mfma_f32_16x16x32_bf16 v[116:119], v[136:139], v[188:191], v[116:119]
	v_mfma_f32_16x16x32_bf16 v[112:115], v[160:163], v[184:187], v[112:115]
	v_mfma_f32_16x16x32_bf16 v[108:111], v[132:135], v[192:195], v[108:111]
	v_mfma_f32_16x16x32_bf16 v[104:107], v[160:163], v[192:195], v[104:107]
	v_mfma_f32_16x16x32_bf16 v[100:103], v[132:135], v[200:203], v[100:103]
	v_mfma_f32_16x16x32_bf16 v[96:99], v[164:167], v[204:207], v[96:99]
	v_mfma_f32_16x16x32_bf16 v[128:131], v[164:167], v[188:191], v[112:115]
	v_mfma_f32_16x16x32_bf16 v[170:173], v[136:139], v[196:199], v[108:111]
	v_mfma_f32_16x16x32_bf16 v[208:211], v[164:167], v[196:199], v[104:107]
	v_mfma_f32_16x16x32_bf16 v[212:215], v[136:139], v[204:207], v[100:103]
	s_setprio 0
	s_barrier
	ds_read_b128 v[100:103], v169
	ds_read_b128 v[104:107], v169 offset:1024
	ds_read_b128 v[108:111], v169 offset:2048
	ds_read_b128 v[112:115], v169 offset:3072
	s_barrier
; #define LDA(dst, b, h) _Pragma("unroll") for (int m = 0; m < 4; ++m) _Pragma("unroll") for (int k = 0; k < 2; ++k) \
;     dst[m][k] = *reinterpret_cast<const bf16x8*>((const char*)SA(b, h) + lds_byte8(wr * 64 + m * 16 + fr, k * 32 + fq * 8))
; #define LDB(dst, b, h) _Pragma("unroll") for (int n = 0; n < 2; ++n) _Pragma("unroll") for (int k = 0; k < 2; ++k) \
;     dst[n][k] = *reinterpret_cast<const bf16x8*>((const char*)SB(b, h) + lds_byte8(wc * 32 + n * 16 + fr, k * 32 + fq * 8))
; #define MMA(ai, bj, At_, Bt_) do { __builtin_amdgcn_s_setprio(1); \
;     _Pragma("unroll") for (int m = 0; m < 4; ++m) _Pragma("unroll") for (int n = 0; n < 2; ++n) _Pragma("unroll") for (int k = 0; k < 2; ++k) \
;       acc[ai][bj][m][n] = MFMA16(Bt_[n][k], At_[m][k], acc[ai][bj][m][n]); \
;     __builtin_amdgcn_s_setprio(0); } while (0)
; #define WAIT_V(n) asm volatile("s_waitcnt vmcnt(" #n ")" ::: "memory")
; #define WAIT_L(n) asm volatile("s_waitcnt lgkmcnt(" #n ")" ::: "memory")
; #define BAR __builtin_amdgcn_s_barrier()
; template <class FL, class FS>
; DI void gemm8_tile(char* shmc, const bf16_t* __restrict__ A, const bf16_t* __restrict__ Bt, const int K, const int brow, const int bcol, FL fl, FS fs) {
;     ...
;     LDB(B1, 0, 1); BAR; WAIT_L(0); MMA(0, 1, At, B1); BAR;
;     LDA(At, 0, 1); WAIT_V(4); BAR; WAIT_L(0); MMA(1, 0, At, B0); MMA(1, 1, At, B1); BAR; }
;   { LDB(B0, 1, 0); LDA(At, 1, 0); WAIT_V(2); BAR; WAIT_L(0); MMA(0, 0, At, B0); BAR;
;     LDB(B1, 1, 1); WAIT_V(0); BAR; WAIT_L(0); MMA(0, 1, At, B1); BAR;
	s_waitcnt lgkmcnt(0)
	s_setprio 1
	s_waitcnt lgkmcnt(3)
	v_mfma_f32_16x16x32_bf16 v[92:95], v[100:103], v[174:177], v[92:95]
	s_waitcnt lgkmcnt(1)
	v_mfma_f32_16x16x32_bf16 v[88:91], v[108:111], v[174:177], v[88:91]
	v_mfma_f32_16x16x32_bf16 v[84:87], v[100:103], v[184:187], v[84:87]
	v_mfma_f32_16x16x32_bf16 v[64:67], v[108:111], v[200:203], v[64:67]
	v_mfma_f32_16x16x32_bf16 v[92:95], v[104:107], v[178:181], v[92:95]
	s_waitcnt lgkmcnt(0)
	v_mfma_f32_16x16x32_bf16 v[88:91], v[112:115], v[178:181], v[88:91]
	v_mfma_f32_16x16x32_bf16 v[84:87], v[104:107], v[188:191], v[84:87]
	v_mfma_f32_16x16x32_bf16 v[80:83], v[108:111], v[184:187], v[80:83]
	v_mfma_f32_16x16x32_bf16 v[76:79], v[100:103], v[192:195], v[76:79]
	v_mfma_f32_16x16x32_bf16 v[72:75], v[108:111], v[192:195], v[72:75]
	v_mfma_f32_16x16x32_bf16 v[68:71], v[100:103], v[200:203], v[68:71]
	v_mfma_f32_16x16x32_bf16 v[64:67], v[112:115], v[204:207], v[64:67]
	v_mfma_f32_16x16x32_bf16 v[174:177], v[112:115], v[188:191], v[80:83]
	v_mfma_f32_16x16x32_bf16 v[178:181], v[104:107], v[196:199], v[76:79]
	v_mfma_f32_16x16x32_bf16 v[184:187], v[112:115], v[196:199], v[72:75]
	v_mfma_f32_16x16x32_bf16 v[188:191], v[104:107], v[204:207], v[68:71]
	s_setprio 0
	s_barrier
	s_nop 0
	ds_read_b128 v[68:71], v155 offset:16384
	ds_read_b128 v[72:75], v155 offset:17408
	ds_read_b128 v[76:79], v154 offset:16384
	ds_read_b128 v[80:83], v154 offset:17408
	ds_read_b128 v[192:195], v153 offset:16384
	ds_read_b128 v[196:199], v153 offset:17408
	ds_read_b128 v[200:203], v151 offset:16384
	ds_read_b128 v[204:207], v151 offset:17408
	s_waitcnt vmcnt(4)
	s_barrier
	s_waitcnt lgkmcnt(0)
	s_setprio 1
	s_waitcnt lgkmcnt(7)
	v_mfma_f32_16x16x32_bf16 v[60:63], v[132:135], v[68:71], v[60:63]
	v_mfma_f32_16x16x32_bf16 v[56:59], v[160:163], v[68:71], v[56:59]
	s_waitcnt lgkmcnt(3)
	v_mfma_f32_16x16x32_bf16 v[44:47], v[132:135], v[192:195], v[44:47]
	s_waitcnt lgkmcnt(1)
	v_mfma_f32_16x16x32_bf16 v[32:35], v[160:163], v[200:203], v[32:35]
	v_mfma_f32_16x16x32_bf16 v[60:63], v[136:139], v[72:75], v[60:63]
	v_mfma_f32_16x16x32_bf16 v[56:59], v[164:167], v[72:75], v[56:59]
	v_mfma_f32_16x16x32_bf16 v[52:55], v[132:135], v[76:79], v[52:55]
	v_mfma_f32_16x16x32_bf16 v[48:51], v[160:163], v[76:79], v[48:51]
	v_mfma_f32_16x16x32_bf16 v[44:47], v[136:139], v[196:199], v[44:47]
	v_mfma_f32_16x16x32_bf16 v[40:43], v[160:163], v[192:195], v[40:43]
	v_mfma_f32_16x16x32_bf16 v[36:39], v[132:135], v[200:203], v[36:39]
	s_waitcnt lgkmcnt(0)
	v_mfma_f32_16x16x32_bf16 v[32:35], v[164:167], v[204:207], v[32:35]
	v_mfma_f32_16x16x32_bf16 v[216:219], v[136:139], v[80:83], v[52:55]
	v_mfma_f32_16x16x32_bf16 v[220:223], v[164:167], v[80:83], v[48:51]
	v_mfma_f32_16x16x32_bf16 v[224:227], v[164:167], v[196:199], v[40:43]
	v_mfma_f32_16x16x32_bf16 v[132:135], v[136:139], v[204:207], v[36:39]
	s_setprio 0
	s_setprio 1
	v_mfma_f32_16x16x32_bf16 v[28:31], v[100:103], v[68:71], v[28:31]
	v_mfma_f32_16x16x32_bf16 v[24:27], v[108:111], v[68:71], v[24:27]
	v_mfma_f32_16x16x32_bf16 v[12:15], v[100:103], v[192:195], v[12:15]
	v_mfma_f32_16x16x32_bf16 v[0:3], v[108:111], v[200:203], v[0:3]
	v_mfma_f32_16x16x32_bf16 v[28:31], v[104:107], v[72:75], v[28:31]
	v_mfma_f32_16x16x32_bf16 v[24:27], v[112:115], v[72:75], v[24:27]
	v_mfma_f32_16x16x32_bf16 v[20:23], v[100:103], v[76:79], v[20:23]
	v_mfma_f32_16x16x32_bf16 v[16:19], v[108:111], v[76:79], v[16:19]
	v_mfma_f32_16x16x32_bf16 v[12:15], v[104:107], v[196:199], v[12:15]
	v_mfma_f32_16x16x32_bf16 v[8:11], v[108:111], v[192:195], v[8:11]
	v_mfma_f32_16x16x32_bf16 v[4:7], v[100:103], v[200:203], v[4:7]
	v_mfma_f32_16x16x32_bf16 v[0:3], v[112:115], v[204:207], v[0:3]
	v_mfma_f32_16x16x32_bf16 v[136:139], v[104:107], v[80:83], v[20:23]
	v_mfma_f32_16x16x32_bf16 v[160:163], v[112:115], v[80:83], v[16:19]
	v_mfma_f32_16x16x32_bf16 v[164:167], v[112:115], v[196:199], v[8:11]
	v_mfma_f32_16x16x32_bf16 v[192:195], v[104:107], v[204:207], v[4:7]
	s_setprio 0
	s_barrier
	s_nop 0
	ds_read_b128 v[4:7], v159
	ds_read_b128 v[8:11], v159 offset:1024
	ds_read_b128 v[196:199], v159 offset:2048
	ds_read_b128 v[200:203], v159 offset:3072
	ds_read_b128 v[16:19], v155 offset:32768
	ds_read_b128 v[20:23], v155 offset:33792
	ds_read_b128 v[36:39], v154 offset:32768
	ds_read_b128 v[40:43], v154 offset:33792
	ds_read_b128 v[48:51], v153 offset:32768
	ds_read_b128 v[52:55], v153 offset:33792
	ds_read_b128 v[204:207], v151 offset:32768
	ds_read_b128 v[228:231], v151 offset:33792
	s_waitcnt vmcnt(2)
	s_barrier
	s_waitcnt lgkmcnt(0)
	s_setprio 1
	s_waitcnt lgkmcnt(7)
	v_mfma_f32_16x16x32_bf16 v[68:71], v[4:7], v[16:19], v[124:127]
	s_waitcnt lgkmcnt(6)
	v_mfma_f32_16x16x32_bf16 v[112:115], v[8:11], v[20:23], v[68:71]
	v_mfma_f32_16x16x32_bf16 v[68:71], v[196:199], v[16:19], v[120:123]
	v_mfma_f32_16x16x32_bf16 v[108:111], v[200:203], v[20:23], v[68:71]
	s_waitcnt lgkmcnt(5)
	v_mfma_f32_16x16x32_bf16 v[68:71], v[4:7], v[36:39], v[116:119]
	s_waitcnt lgkmcnt(4)
	v_mfma_f32_16x16x32_bf16 v[104:107], v[8:11], v[40:43], v[68:71]
	v_mfma_f32_16x16x32_bf16 v[68:71], v[196:199], v[36:39], v[128:131]
	v_mfma_f32_16x16x32_bf16 v[100:103], v[200:203], v[40:43], v[68:71]
	s_waitcnt lgkmcnt(3)
	v_mfma_f32_16x16x32_bf16 v[68:71], v[4:7], v[48:51], v[170:173]
	s_waitcnt lgkmcnt(2)
	v_mfma_f32_16x16x32_bf16 v[80:83], v[8:11], v[52:55], v[68:71]
	v_mfma_f32_16x16x32_bf16 v[68:71], v[196:199], v[48:51], v[208:211]
	v_mfma_f32_16x16x32_bf16 v[76:79], v[200:203], v[52:55], v[68:71]
	s_waitcnt lgkmcnt(1)
	v_mfma_f32_16x16x32_bf16 v[68:71], v[4:7], v[204:207], v[212:215]
	s_waitcnt lgkmcnt(0)
	v_mfma_f32_16x16x32_bf16 v[72:75], v[8:11], v[228:231], v[68:71]
	v_mfma_f32_16x16x32_bf16 v[68:71], v[196:199], v[204:207], v[96:99]
	v_mfma_f32_16x16x32_bf16 v[68:71], v[200:203], v[228:231], v[68:71]
	s_setprio 0
	s_barrier
; #define LDA(dst, b, h) _Pragma("unroll") for (int m = 0; m < 4; ++m) _Pragma("unroll") for (int k = 0; k < 2; ++k) \
;     dst[m][k] = *reinterpret_cast<const bf16x8*>((const char*)SA(b, h) + lds_byte8(wr * 64 + m * 16 + fr, k * 32 + fq * 8))
; #define LDB(dst, b, h) _Pragma("unroll") for (int n = 0; n < 2; ++n) _Pragma("unroll") for (int k = 0; k < 2; ++k) \
;     dst[n][k] = *reinterpret_cast<const bf16x8*>((const char*)SB(b, h) + lds_byte8(wc * 32 + n * 16 + fr, k * 32 + fq * 8))
; #define MMA(ai, bj, At_, Bt_) do { __builtin_amdgcn_s_setprio(1); \
;     _Pragma("unroll") for (int m = 0; m < 4; ++m) _Pragma("unroll") for (int n = 0; n < 2; ++n) _Pragma("unroll") for (int k = 0; k < 2; ++k) \
;       acc[ai][bj][m][n] = MFMA16(Bt_[n][k], At_[m][k], acc[ai][bj][m][n]); \
;     __builtin_amdgcn_s_setprio(0); } while (0)
; #define WAIT_V(n) asm volatile("s_waitcnt vmcnt(" #n ")" ::: "memory")
; #define WAIT_L(n) asm volatile("s_waitcnt lgkmcnt(" #n ")" ::: "memory")
; #define BAR __builtin_amdgcn_s_barrier()
; template <class FL, class FS>
; DI void gemm8_tile(char* shmc, const bf16_t* __restrict__ A, const bf16_t* __restrict__ Bt, const int K, const int brow, const int bcol, FL fl, FS fs) {
;     ...
;     LDB(B1, 1, 1); WAIT_V(0); BAR; WAIT_L(0); MMA(0, 1, At, B1); BAR;
;     LDA(At, 1, 1); BAR; WAIT_L(0); MMA(1, 0, At, B0); MMA(1, 1, At, B1); BAR; }
;   if (wr == 0) BAR;
; template <class FL, class FS>
; DI void gemm_dispatch(const Sub& s, char* lds_all, const bf16_t* A, const bf16_t* Bt, const int nN256, FL fl, FS fs) {
;     ...
;     for (int L = blockIdx.x; L < nM * nN256; L += gridDim.x) {
;       int pm, pn; tile8_order(L, nM, nN256, pm, pn);
;       gemm8_tile(lds_all, A, Bt, D, pm * 256, pn * 256, fl, fs);
	ds_read_b128 v[128:131], v157
	ds_read_b128 v[168:171], v157 offset:1024
	ds_read_b128 v[208:211], v157 offset:2048
	ds_read_b128 v[156:159], v157 offset:3072
	s_waitcnt vmcnt(0)
	s_barrier
	s_waitcnt lgkmcnt(0)
	s_setprio 1
	s_waitcnt lgkmcnt(3)
	v_mfma_f32_16x16x32_bf16 v[92:95], v[128:131], v[16:19], v[92:95]
	s_waitcnt lgkmcnt(1)
	v_mfma_f32_16x16x32_bf16 v[16:19], v[208:211], v[16:19], v[88:91]
	s_waitcnt lgkmcnt(0)
	v_mfma_f32_16x16x32_bf16 v[120:123], v[156:159], v[20:23], v[16:19]
	v_mfma_f32_16x16x32_bf16 v[16:19], v[128:131], v[36:39], v[84:87]
	v_mfma_f32_16x16x32_bf16 v[116:119], v[168:171], v[40:43], v[16:19]
	v_mfma_f32_16x16x32_bf16 v[16:19], v[208:211], v[36:39], v[174:177]
	v_mfma_f32_16x16x32_bf16 v[96:99], v[156:159], v[40:43], v[16:19]
	v_mfma_f32_16x16x32_bf16 v[16:19], v[128:131], v[48:51], v[178:181]
	v_mfma_f32_16x16x32_bf16 v[124:127], v[168:171], v[20:23], v[92:95]
	v_mfma_f32_16x16x32_bf16 v[92:95], v[168:171], v[52:55], v[16:19]
	v_mfma_f32_16x16x32_bf16 v[16:19], v[208:211], v[48:51], v[184:187]
	v_mfma_f32_16x16x32_bf16 v[88:91], v[156:159], v[52:55], v[16:19]
	v_mfma_f32_16x16x32_bf16 v[16:19], v[128:131], v[204:207], v[188:191]
	v_mfma_f32_16x16x32_bf16 v[84:87], v[168:171], v[228:231], v[16:19]
	v_mfma_f32_16x16x32_bf16 v[16:19], v[208:211], v[204:207], v[64:67]
	v_mfma_f32_16x16x32_bf16 v[64:67], v[156:159], v[228:231], v[16:19]
	s_setprio 0
	s_barrier
	ds_read_b128 v[172:175], v155 offset:49152
	ds_read_b128 v[176:179], v155 offset:50176
	ds_read_b128 v[184:187], v154 offset:49152
	ds_read_b128 v[188:191], v154 offset:50176
	ds_read_b128 v[204:207], v153 offset:49152
	ds_read_b128 v[152:155], v153 offset:50176
	ds_read_b128 v[212:215], v151 offset:49152
	ds_read_b128 v[228:231], v151 offset:50176
	s_barrier
	s_waitcnt lgkmcnt(0)
	s_setprio 1
	s_waitcnt lgkmcnt(7)
	v_mfma_f32_16x16x32_bf16 v[16:19], v[4:7], v[172:175], v[60:63]
	s_waitcnt lgkmcnt(6)
	v_mfma_f32_16x16x32_bf16 v[52:55], v[8:11], v[176:179], v[16:19]
	v_mfma_f32_16x16x32_bf16 v[16:19], v[196:199], v[172:175], v[56:59]
	v_mfma_f32_16x16x32_bf16 v[48:51], v[200:203], v[176:179], v[16:19]
	s_waitcnt lgkmcnt(5)
	v_mfma_f32_16x16x32_bf16 v[16:19], v[4:7], v[184:187], v[216:219]
	s_waitcnt lgkmcnt(4)
	v_mfma_f32_16x16x32_bf16 v[40:43], v[8:11], v[188:191], v[16:19]
	v_mfma_f32_16x16x32_bf16 v[16:19], v[196:199], v[184:187], v[220:223]
	v_mfma_f32_16x16x32_bf16 v[36:39], v[200:203], v[188:191], v[16:19]
	s_waitcnt lgkmcnt(3)
	v_mfma_f32_16x16x32_bf16 v[16:19], v[4:7], v[204:207], v[44:47]
	s_waitcnt lgkmcnt(1)
	v_mfma_f32_16x16x32_bf16 v[4:7], v[4:7], v[212:215], v[132:135]
	v_mfma_f32_16x16x32_bf16 v[20:23], v[8:11], v[152:155], v[16:19]
	v_mfma_f32_16x16x32_bf16 v[16:19], v[196:199], v[204:207], v[224:227]
	s_waitcnt lgkmcnt(0)
	v_mfma_f32_16x16x32_bf16 v[8:11], v[8:11], v[228:231], v[4:7]
	v_mfma_f32_16x16x32_bf16 v[4:7], v[196:199], v[212:215], v[32:35]
	v_mfma_f32_16x16x32_bf16 v[16:19], v[200:203], v[152:155], v[16:19]
	v_mfma_f32_16x16x32_bf16 v[4:7], v[200:203], v[228:231], v[4:7]
	s_setprio 0
	s_setprio 1
	v_mfma_f32_16x16x32_bf16 v[24:27], v[208:211], v[172:175], v[24:27]
	v_mfma_f32_16x16x32_bf16 v[28:31], v[128:131], v[172:175], v[28:31]
	v_mfma_f32_16x16x32_bf16 v[56:59], v[156:159], v[176:179], v[24:27]
	v_mfma_f32_16x16x32_bf16 v[24:27], v[128:131], v[184:187], v[136:139]
	v_mfma_f32_16x16x32_bf16 v[12:15], v[128:131], v[204:207], v[12:15]
	v_mfma_f32_16x16x32_bf16 v[60:63], v[168:171], v[176:179], v[28:31]
	v_mfma_f32_16x16x32_bf16 v[44:47], v[168:171], v[188:191], v[24:27]
	v_mfma_f32_16x16x32_bf16 v[24:27], v[208:211], v[184:187], v[160:163]
	v_mfma_f32_16x16x32_bf16 v[28:31], v[168:171], v[152:155], v[12:15]
	v_mfma_f32_16x16x32_bf16 v[12:15], v[208:211], v[204:207], v[164:167]
	v_mfma_f32_16x16x32_bf16 v[32:35], v[156:159], v[188:191], v[24:27]
	v_mfma_f32_16x16x32_bf16 v[24:27], v[156:159], v[152:155], v[12:15]
	v_mfma_f32_16x16x32_bf16 v[12:15], v[128:131], v[212:215], v[192:195]
	v_mfma_f32_16x16x32_bf16 v[0:3], v[208:211], v[212:215], v[0:3]
	v_mfma_f32_16x16x32_bf16 v[12:15], v[168:171], v[228:231], v[12:15]
	v_mfma_f32_16x16x32_bf16 v[0:3], v[156:159], v[228:231], v[0:3]
	s_setprio 0
	v_cmp_gt_u32_e32 vcc, s52, v140
	s_barrier
	s_and_saveexec_b64 s[0:1], vcc
	s_cbranch_execz .Lg5_wr0
	s_barrier
.Lg5_wr0:
	s_or_b64 exec, exec, s[0:1]
	s_mov_b32 s99, s40
	s_mov_b32 s100, s38
	s_mov_b32 s98, 1
	v_readlane_b32 s2, v251, 1
	s_add_i32 s1, s56, s2
	s_cmpk_lt_i32 s1, 0x400
	s_cbranch_scc1 .LBB0_2089
	s_mov_b32 s101, 1
; DI float4 ldnt4(const float* p) { const f32x4 v = __builtin_nontemporal_load((const f32x4*)p); float4 r; r.x = v[0]; r.y = v[1]; r.z = v[2]; r.w = v[3]; return r; }
; DI void st_bf4(bf16_t* p, float a, float b, float c, float d) { uint2 v; v.x = pack2(a, b); v.y = pack2(c, d); *(uint2*)p = v; }
; template <class FL, class FS>
; DI void gemm8_tile(char* shmc, const bf16_t* __restrict__ A, const bf16_t* __restrict__ Bt, const int K, const int brow, const int bcol, FL fl, FS fs) {
;     ...
; #pragma unroll
;   for (int ai = 0; ai < 2; ++ai)
; #pragma unroll
;     for (int mh = 0; mh < 2; ++mh) {
;       decltype(fl(0, 0)) ld[2][2][2];
; #pragma unroll
;       for (int mm = 0; mm < 2; ++mm)
; #pragma unroll
;         for (int bj = 0; bj < 2; ++bj)
; #pragma unroll
;           for (int n = 0; n < 2; ++n) ld[mm][bj][n] = fl(brow + ai * HALF + wr * 64 + (2 * mh + mm) * 16 + fr, bcol + bj * HALF + wc * 32 + n * 16 + 4 * fq);
; #pragma unroll
;       for (int mm = 0; mm < 2; ++mm)
; #pragma unroll
;         for (int bj = 0; bj < 2; ++bj)
; #pragma unroll
;           for (int n = 0; n < 2; ++n) fs(brow + ai * HALF + wr * 64 + (2 * mh + mm) * 16 + fr, bcol + bj * HALF + wc * 32 + n * 16 + 4 * fq, acc[ai][bj][2 * mh + mm][n], ld[mm][bj][n]);
; DI void phase_gout(const Params& p, const Sub& s, char* lds_all, int layer, const bf16_t* A, const bf16_t* Bt) {
;     ...
;       [&](int row, int col) {
;         const bf16_t* x1b = (const bf16_t*)p.out;
;         float4 x4;
;         if (layer == 0) x4 = ldnt4(xrow(p, row) + col);
;         else ld_bf4(x1b + (size_t)row * D + col, x4.x, x4.y, x4.z, x4.w);
;         Ld2 r; r.a = x4; r.b = *(const float4*)(mod + (size_t)(row_bi(row) * 2 + layer) * 3072 + 2048 + col);
;         return r;
;       },
;       [&](int row, int col, f32x4 v, const Ld2& l2) {
;         const float4 x4 = l2.a, g4 = l2.b;
;         bf16_t* x1b = (bf16_t*)p.out;
;         bf16_t* x2b = (bf16_t*)(p.ws + W_SLOT3);
;         st_bf4((layer == 0 ? x1b : x2b) + (size_t)row * D + col, x4.x + g4.x * v[0], x4.y + g4.y * v[1], x4.z + g4.z * v[2], x4.w + g4.w * v[3]);
.Lg5_epi:
	v_and_b32_e32 v174, 15, v182
	v_bfe_u32 v175, v182, 4, 2
	v_bfe_u32 v180, v182, 6, 2
	v_lshrrev_b32_e32 v181, 8, v182
	v_lshl_add_u32 v248, v181, 6, v174
	v_and_b32_e32 v249, 1, v175
	v_lshrrev_b32_e32 v250, 1, v175
	v_lshlrev_b32_e32 v228, 11, v248
	v_lshl_add_u32 v228, v180, 6, v228
	v_lshl_add_u32 v228, v175, 3, v228
	v_lshlrev_b32_e32 v229, 7, v180
	v_lshl_add_u32 v229, v175, 4, v229
	v_lshlrev_b32_e32 v230, 11, v248
	v_lshl_add_u32 v230, v180, 6, v230
	v_lshl_add_u32 v230, v249, 5, v230
	v_lshl_add_u32 v230, v250, 4, v230
	s_lshr_b32 s0, s99, 13
	s_mul_i32 s0, s0, 0x6000
	s_add_u32 s0, s0, 0x5000
	s_lshl_b32 s2, s100, 2
	s_add_u32 s0, s0, s2
	s_add_u32 s36, s10, s0
	s_addc_u32 s37, s11, 0
	s_lshl_b32 s0, s99, 11
	s_add_u32 s42, s4, s0
	s_addc_u32 s43, s5, 0
	s_lshl_b32 s0, s100, 1
	s_add_u32 s42, s42, s0
	s_addc_u32 s43, s43, 0
	s_lshl_b32 s0, s99, 11
	s_add_u32 s54, s12, s0
	s_addc_u32 s55, s13, 0
	s_lshl_b32 s0, s100, 1
	s_add_u32 s54, s54, s0
	s_addc_u32 s55, s55, 0
	global_load_dwordx4 v[176:179], v229, s[36:37]
	global_load_dwordx4 v[184:187], v229, s[36:37] offset:64
	global_load_dwordx4 v[188:191], v229, s[36:37] offset:512
	global_load_dwordx4 v[192:195], v229, s[36:37] offset:576
	global_load_dwordx2 v[196:197], v228, s[42:43]
	global_load_dwordx2 v[200:201], v228, s[42:43] offset:32
	global_load_dwordx2 v[204:205], v228, s[42:43] offset:256
	global_load_dwordx2 v[208:209], v228, s[42:43] offset:288
	s_add_u32 s42, s42, 0x8000
	s_addc_u32 s43, s43, 0
	global_load_dwordx2 v[212:213], v228, s[42:43]
	global_load_dwordx2 v[216:217], v228, s[42:43] offset:32
	global_load_dwordx2 v[220:221], v228, s[42:43] offset:256
	global_load_dwordx2 v[224:225], v228, s[42:43] offset:288
	s_waitcnt vmcnt(4)
	v_and_b32_e32 v199, 0xffff0000, v197
	v_lshlrev_b32_e32 v198, 16, v197
	v_and_b32_e32 v197, 0xffff0000, v196
	v_lshlrev_b32_e32 v196, 16, v196
	v_pk_fma_f32 v[196:197], v[176:177], v[112:113], v[196:197]
	v_pk_fma_f32 v[198:199], v[178:179], v[114:115], v[198:199]
	v_and_b32_e32 v203, 0xffff0000, v201
	v_lshlrev_b32_e32 v202, 16, v201
	v_and_b32_e32 v201, 0xffff0000, v200
	v_lshlrev_b32_e32 v200, 16, v200
	v_pk_fma_f32 v[200:201], v[184:185], v[108:109], v[200:201]
	v_pk_fma_f32 v[202:203], v[186:187], v[110:111], v[202:203]
	v_and_b32_e32 v207, 0xffff0000, v205
	v_lshlrev_b32_e32 v206, 16, v205
	v_and_b32_e32 v205, 0xffff0000, v204
	v_lshlrev_b32_e32 v204, 16, v204
	v_pk_fma_f32 v[204:205], v[188:189], v[124:125], v[204:205]
	v_pk_fma_f32 v[206:207], v[190:191], v[126:127], v[206:207]
	v_and_b32_e32 v211, 0xffff0000, v209
	v_lshlrev_b32_e32 v210, 16, v209
	v_and_b32_e32 v209, 0xffff0000, v208
	v_lshlrev_b32_e32 v208, 16, v208
	v_pk_fma_f32 v[208:209], v[192:193], v[120:121], v[208:209]
	v_pk_fma_f32 v[210:211], v[194:195], v[122:123], v[210:211]
	v_cvt_pk_bf16_f32 v196, v196, v197
	v_cvt_pk_bf16_f32 v197, v198, v199
	v_cvt_pk_bf16_f32 v198, v200, v201
	v_cvt_pk_bf16_f32 v199, v202, v203
	v_cvt_pk_bf16_f32 v204, v204, v205
	v_cvt_pk_bf16_f32 v205, v206, v207
	v_cvt_pk_bf16_f32 v206, v208, v209
	v_cvt_pk_bf16_f32 v207, v210, v211
	v_permlane16_swap_b32_e32 v196, v198
	v_permlane16_swap_b32_e32 v197, v199
	global_store_dwordx4 v230, v[196:199], s[54:55]
	v_permlane16_swap_b32_e32 v204, v206
	v_permlane16_swap_b32_e32 v205, v207
	global_store_dwordx4 v230, v[204:207], s[54:55] offset:256
	s_nop 1
	s_add_u32 s42, s42, 0x8000
	s_addc_u32 s43, s43, 0
	global_load_dwordx2 v[196:197], v228, s[42:43]
	global_load_dwordx2 v[200:201], v228, s[42:43] offset:32
	global_load_dwordx2 v[204:205], v228, s[42:43] offset:256
	global_load_dwordx2 v[208:209], v228, s[42:43] offset:288
	s_waitcnt vmcnt(6)
	v_and_b32_e32 v215, 0xffff0000, v213
	v_lshlrev_b32_e32 v214, 16, v213
	v_and_b32_e32 v213, 0xffff0000, v212
	v_lshlrev_b32_e32 v212, 16, v212
	v_pk_fma_f32 v[212:213], v[176:177], v[104:105], v[212:213]
	v_pk_fma_f32 v[214:215], v[178:179], v[106:107], v[214:215]
	v_and_b32_e32 v219, 0xffff0000, v217
	v_lshlrev_b32_e32 v218, 16, v217
	v_and_b32_e32 v217, 0xffff0000, v216
	v_lshlrev_b32_e32 v216, 16, v216
	v_pk_fma_f32 v[216:217], v[184:185], v[100:101], v[216:217]
	v_pk_fma_f32 v[218:219], v[186:187], v[102:103], v[218:219]
	v_and_b32_e32 v223, 0xffff0000, v221
	v_lshlrev_b32_e32 v222, 16, v221
	v_and_b32_e32 v221, 0xffff0000, v220
	v_lshlrev_b32_e32 v220, 16, v220
	v_pk_fma_f32 v[220:221], v[188:189], v[116:117], v[220:221]
	v_pk_fma_f32 v[222:223], v[190:191], v[118:119], v[222:223]
	v_and_b32_e32 v227, 0xffff0000, v225
	v_lshlrev_b32_e32 v226, 16, v225
	v_and_b32_e32 v225, 0xffff0000, v224
	v_lshlrev_b32_e32 v224, 16, v224
	v_pk_fma_f32 v[224:225], v[192:193], v[96:97], v[224:225]
	v_pk_fma_f32 v[226:227], v[194:195], v[98:99], v[226:227]
	v_cvt_pk_bf16_f32 v212, v212, v213
	v_cvt_pk_bf16_f32 v213, v214, v215
	v_cvt_pk_bf16_f32 v214, v216, v217
	v_cvt_pk_bf16_f32 v215, v218, v219
	v_cvt_pk_bf16_f32 v220, v220, v221
	v_cvt_pk_bf16_f32 v221, v222, v223
	v_cvt_pk_bf16_f32 v222, v224, v225
	v_cvt_pk_bf16_f32 v223, v226, v227
	s_add_u32 s54, s54, 0x8000
	s_addc_u32 s55, s55, 0
	v_permlane16_swap_b32_e32 v212, v214
	v_permlane16_swap_b32_e32 v213, v215
	global_store_dwordx4 v230, v[212:215], s[54:55]
	v_permlane16_swap_b32_e32 v220, v222
	v_permlane16_swap_b32_e32 v221, v223
	global_store_dwordx4 v230, v[220:223], s[54:55] offset:256
	s_nop 1
	s_add_u32 s42, s42, 0x8000
	s_addc_u32 s43, s43, 0
	global_load_dwordx2 v[212:213], v228, s[42:43]
	global_load_dwordx2 v[216:217], v228, s[42:43] offset:32
	global_load_dwordx2 v[220:221], v228, s[42:43] offset:256
	global_load_dwordx2 v[224:225], v228, s[42:43] offset:288
	s_waitcnt vmcnt(6)
; DI float4 ldnt4(const float* p) { const f32x4 v = __builtin_nontemporal_load((const f32x4*)p); float4 r; r.x = v[0]; r.y = v[1]; r.z = v[2]; r.w = v[3]; return r; }
; DI void st_bf4(bf16_t* p, float a, float b, float c, float d) { uint2 v; v.x = pack2(a, b); v.y = pack2(c, d); *(uint2*)p = v; }
; template <class FL, class FS>
; DI void gemm8_tile(char* shmc, const bf16_t* __restrict__ A, const bf16_t* __restrict__ Bt, const int K, const int brow, const int bcol, FL fl, FS fs) {
;     ...
; #pragma unroll
;   for (int ai = 0; ai < 2; ++ai)
; #pragma unroll
;     for (int mh = 0; mh < 2; ++mh) {
;       decltype(fl(0, 0)) ld[2][2][2];
; #pragma unroll
;       for (int mm = 0; mm < 2; ++mm)
; #pragma unroll
;         for (int bj = 0; bj < 2; ++bj)
; #pragma unroll
;           for (int n = 0; n < 2; ++n) ld[mm][bj][n] = fl(brow + ai * HALF + wr * 64 + (2 * mh + mm) * 16 + fr, bcol + bj * HALF + wc * 32 + n * 16 + 4 * fq);
; #pragma unroll
;       for (int mm = 0; mm < 2; ++mm)
; #pragma unroll
;         for (int bj = 0; bj < 2; ++bj)
; #pragma unroll
;           for (int n = 0; n < 2; ++n) fs(brow + ai * HALF + wr * 64 + (2 * mh + mm) * 16 + fr, bcol + bj * HALF + wc * 32 + n * 16 + 4 * fq, acc[ai][bj][2 * mh + mm][n], ld[mm][bj][n]);
; DI void phase_gout(const Params& p, const Sub& s, char* lds_all, int layer, const bf16_t* A, const bf16_t* Bt) {
;     ...
;       [&](int row, int col) {
;         const bf16_t* x1b = (const bf16_t*)p.out;
;         float4 x4;
;         if (layer == 0) x4 = ldnt4(xrow(p, row) + col);
;         else ld_bf4(x1b + (size_t)row * D + col, x4.x, x4.y, x4.z, x4.w);
;         Ld2 r; r.a = x4; r.b = *(const float4*)(mod + (size_t)(row_bi(row) * 2 + layer) * 3072 + 2048 + col);
;         return r;
;       },
;       [&](int row, int col, f32x4 v, const Ld2& l2) {
;         const float4 x4 = l2.a, g4 = l2.b;
;         bf16_t* x1b = (bf16_t*)p.out;
;         bf16_t* x2b = (bf16_t*)(p.ws + W_SLOT3);
;         st_bf4((layer == 0 ? x1b : x2b) + (size_t)row * D + col, x4.x + g4.x * v[0], x4.y + g4.y * v[1], x4.z + g4.z * v[2], x4.w + g4.w * v[3]);
	v_and_b32_e32 v199, 0xffff0000, v197
	v_lshlrev_b32_e32 v198, 16, v197
	v_and_b32_e32 v197, 0xffff0000, v196
	v_lshlrev_b32_e32 v196, 16, v196
	v_pk_fma_f32 v[196:197], v[176:177], v[80:81], v[196:197]
	v_pk_fma_f32 v[198:199], v[178:179], v[82:83], v[198:199]
	v_and_b32_e32 v203, 0xffff0000, v201
	v_lshlrev_b32_e32 v202, 16, v201
	v_and_b32_e32 v201, 0xffff0000, v200
	v_lshlrev_b32_e32 v200, 16, v200
	v_pk_fma_f32 v[200:201], v[184:185], v[76:77], v[200:201]
	v_pk_fma_f32 v[202:203], v[186:187], v[78:79], v[202:203]
	v_and_b32_e32 v207, 0xffff0000, v205
	v_lshlrev_b32_e32 v206, 16, v205
	v_and_b32_e32 v205, 0xffff0000, v204
	v_lshlrev_b32_e32 v204, 16, v204
	v_pk_fma_f32 v[204:205], v[188:189], v[92:93], v[204:205]
	v_pk_fma_f32 v[206:207], v[190:191], v[94:95], v[206:207]
	v_and_b32_e32 v211, 0xffff0000, v209
	v_lshlrev_b32_e32 v210, 16, v209
	v_and_b32_e32 v209, 0xffff0000, v208
	v_lshlrev_b32_e32 v208, 16, v208
	v_pk_fma_f32 v[208:209], v[192:193], v[88:89], v[208:209]
	v_pk_fma_f32 v[210:211], v[194:195], v[90:91], v[210:211]
	v_cvt_pk_bf16_f32 v196, v196, v197
	v_cvt_pk_bf16_f32 v197, v198, v199
	v_cvt_pk_bf16_f32 v198, v200, v201
	v_cvt_pk_bf16_f32 v199, v202, v203
	v_cvt_pk_bf16_f32 v204, v204, v205
	v_cvt_pk_bf16_f32 v205, v206, v207
	v_cvt_pk_bf16_f32 v206, v208, v209
	v_cvt_pk_bf16_f32 v207, v210, v211
	s_add_u32 s54, s54, 0x8000
	s_addc_u32 s55, s55, 0
	v_permlane16_swap_b32_e32 v196, v198
	v_permlane16_swap_b32_e32 v197, v199
	global_store_dwordx4 v230, v[196:199], s[54:55]
	v_permlane16_swap_b32_e32 v204, v206
	v_permlane16_swap_b32_e32 v205, v207
	global_store_dwordx4 v230, v[204:207], s[54:55] offset:256
	s_nop 1
	s_add_u32 s42, s42, 0x28000
	s_addc_u32 s43, s43, 0
	global_load_dwordx2 v[196:197], v228, s[42:43]
	global_load_dwordx2 v[200:201], v228, s[42:43] offset:32
	global_load_dwordx2 v[204:205], v228, s[42:43] offset:256
	global_load_dwordx2 v[208:209], v228, s[42:43] offset:288
	s_waitcnt vmcnt(6)
	v_and_b32_e32 v215, 0xffff0000, v213
	v_lshlrev_b32_e32 v214, 16, v213
	v_and_b32_e32 v213, 0xffff0000, v212
	v_lshlrev_b32_e32 v212, 16, v212
	v_pk_fma_f32 v[212:213], v[176:177], v[72:73], v[212:213]
	v_pk_fma_f32 v[214:215], v[178:179], v[74:75], v[214:215]
	v_and_b32_e32 v219, 0xffff0000, v217
	v_lshlrev_b32_e32 v218, 16, v217
	v_and_b32_e32 v217, 0xffff0000, v216
	v_lshlrev_b32_e32 v216, 16, v216
	v_pk_fma_f32 v[216:217], v[184:185], v[68:69], v[216:217]
	v_pk_fma_f32 v[218:219], v[186:187], v[70:71], v[218:219]
	v_and_b32_e32 v223, 0xffff0000, v221
	v_lshlrev_b32_e32 v222, 16, v221
	v_and_b32_e32 v221, 0xffff0000, v220
	v_lshlrev_b32_e32 v220, 16, v220
	v_pk_fma_f32 v[220:221], v[188:189], v[84:85], v[220:221]
	v_pk_fma_f32 v[222:223], v[190:191], v[86:87], v[222:223]
	v_and_b32_e32 v227, 0xffff0000, v225
	v_lshlrev_b32_e32 v226, 16, v225
	v_and_b32_e32 v225, 0xffff0000, v224
	v_lshlrev_b32_e32 v224, 16, v224
	v_pk_fma_f32 v[224:225], v[192:193], v[64:65], v[224:225]
	v_pk_fma_f32 v[226:227], v[194:195], v[66:67], v[226:227]
	v_cvt_pk_bf16_f32 v212, v212, v213
	v_cvt_pk_bf16_f32 v213, v214, v215
	v_cvt_pk_bf16_f32 v214, v216, v217
	v_cvt_pk_bf16_f32 v215, v218, v219
	v_cvt_pk_bf16_f32 v220, v220, v221
	v_cvt_pk_bf16_f32 v221, v222, v223
	v_cvt_pk_bf16_f32 v222, v224, v225
	v_cvt_pk_bf16_f32 v223, v226, v227
	s_add_u32 s54, s54, 0x8000
	s_addc_u32 s55, s55, 0
	v_permlane16_swap_b32_e32 v212, v214
	v_permlane16_swap_b32_e32 v213, v215
	global_store_dwordx4 v230, v[212:215], s[54:55]
	v_permlane16_swap_b32_e32 v220, v222
	v_permlane16_swap_b32_e32 v221, v223
	global_store_dwordx4 v230, v[220:223], s[54:55] offset:256
	s_nop 1
	s_add_u32 s42, s42, 0x8000
	s_addc_u32 s43, s43, 0
	global_load_dwordx2 v[212:213], v228, s[42:43]
	global_load_dwordx2 v[216:217], v228, s[42:43] offset:32
	global_load_dwordx2 v[220:221], v228, s[42:43] offset:256
	global_load_dwordx2 v[224:225], v228, s[42:43] offset:288
	s_waitcnt vmcnt(6)
	v_and_b32_e32 v199, 0xffff0000, v197
	v_lshlrev_b32_e32 v198, 16, v197
	v_and_b32_e32 v197, 0xffff0000, v196
	v_lshlrev_b32_e32 v196, 16, v196
	v_pk_fma_f32 v[196:197], v[176:177], v[52:53], v[196:197]
	v_pk_fma_f32 v[198:199], v[178:179], v[54:55], v[198:199]
	v_and_b32_e32 v203, 0xffff0000, v201
	v_lshlrev_b32_e32 v202, 16, v201
	v_and_b32_e32 v201, 0xffff0000, v200
	v_lshlrev_b32_e32 v200, 16, v200
	v_pk_fma_f32 v[200:201], v[184:185], v[48:49], v[200:201]
	v_pk_fma_f32 v[202:203], v[186:187], v[50:51], v[202:203]
	v_and_b32_e32 v207, 0xffff0000, v205
	v_lshlrev_b32_e32 v206, 16, v205
	v_and_b32_e32 v205, 0xffff0000, v204
	v_lshlrev_b32_e32 v204, 16, v204
	v_pk_fma_f32 v[204:205], v[188:189], v[60:61], v[204:205]
	v_pk_fma_f32 v[206:207], v[190:191], v[62:63], v[206:207]
	v_and_b32_e32 v211, 0xffff0000, v209
	v_lshlrev_b32_e32 v210, 16, v209
	v_and_b32_e32 v209, 0xffff0000, v208
	v_lshlrev_b32_e32 v208, 16, v208
	v_pk_fma_f32 v[208:209], v[192:193], v[56:57], v[208:209]
	v_pk_fma_f32 v[210:211], v[194:195], v[58:59], v[210:211]
	v_cvt_pk_bf16_f32 v196, v196, v197
	v_cvt_pk_bf16_f32 v197, v198, v199
	v_cvt_pk_bf16_f32 v198, v200, v201
	v_cvt_pk_bf16_f32 v199, v202, v203
	v_cvt_pk_bf16_f32 v204, v204, v205
	v_cvt_pk_bf16_f32 v205, v206, v207
	v_cvt_pk_bf16_f32 v206, v208, v209
	v_cvt_pk_bf16_f32 v207, v210, v211
	s_add_u32 s54, s54, 0x28000
	s_addc_u32 s55, s55, 0
	v_permlane16_swap_b32_e32 v196, v198
	v_permlane16_swap_b32_e32 v197, v199
	global_store_dwordx4 v230, v[196:199], s[54:55]
	v_permlane16_swap_b32_e32 v204, v206
	v_permlane16_swap_b32_e32 v205, v207
	global_store_dwordx4 v230, v[204:207], s[54:55] offset:256
	s_nop 1
	s_add_u32 s42, s42, 0x8000
	s_addc_u32 s43, s43, 0
	global_load_dwordx2 v[196:197], v228, s[42:43]
	global_load_dwordx2 v[200:201], v228, s[42:43] offset:32
	global_load_dwordx2 v[204:205], v228, s[42:43] offset:256
	global_load_dwordx2 v[208:209], v228, s[42:43] offset:288
	s_waitcnt vmcnt(6)
; DI float4 ldnt4(const float* p) { const f32x4 v = __builtin_nontemporal_load((const f32x4*)p); float4 r; r.x = v[0]; r.y = v[1]; r.z = v[2]; r.w = v[3]; return r; }
; DI void st_bf4(bf16_t* p, float a, float b, float c, float d) { uint2 v; v.x = pack2(a, b); v.y = pack2(c, d); *(uint2*)p = v; }
; template <class FL, class FS>
; DI void gemm8_tile(char* shmc, const bf16_t* __restrict__ A, const bf16_t* __restrict__ Bt, const int K, const int brow, const int bcol, FL fl, FS fs) {
;     ...
; #pragma unroll
;   for (int ai = 0; ai < 2; ++ai)
; #pragma unroll
;     for (int mh = 0; mh < 2; ++mh) {
;       decltype(fl(0, 0)) ld[2][2][2];
; #pragma unroll
;       for (int mm = 0; mm < 2; ++mm)
; #pragma unroll
;         for (int bj = 0; bj < 2; ++bj)
; #pragma unroll
;           for (int n = 0; n < 2; ++n) ld[mm][bj][n] = fl(brow + ai * HALF + wr * 64 + (2 * mh + mm) * 16 + fr, bcol + bj * HALF + wc * 32 + n * 16 + 4 * fq);
; #pragma unroll
;       for (int mm = 0; mm < 2; ++mm)
; #pragma unroll
;         for (int bj = 0; bj < 2; ++bj)
; #pragma unroll
;           for (int n = 0; n < 2; ++n) fs(brow + ai * HALF + wr * 64 + (2 * mh + mm) * 16 + fr, bcol + bj * HALF + wc * 32 + n * 16 + 4 * fq, acc[ai][bj][2 * mh + mm][n], ld[mm][bj][n]);
; DI void phase_gout(const Params& p, const Sub& s, char* lds_all, int layer, const bf16_t* A, const bf16_t* Bt) {
;     ...
;       [&](int row, int col) {
;         const bf16_t* x1b = (const bf16_t*)p.out;
;         float4 x4;
;         if (layer == 0) x4 = ldnt4(xrow(p, row) + col);
;         else ld_bf4(x1b + (size_t)row * D + col, x4.x, x4.y, x4.z, x4.w);
;         Ld2 r; r.a = x4; r.b = *(const float4*)(mod + (size_t)(row_bi(row) * 2 + layer) * 3072 + 2048 + col);
;         return r;
;       },
;       [&](int row, int col, f32x4 v, const Ld2& l2) {
;         const float4 x4 = l2.a, g4 = l2.b;
;         bf16_t* x1b = (bf16_t*)p.out;
;         bf16_t* x2b = (bf16_t*)(p.ws + W_SLOT3);
;         st_bf4((layer == 0 ? x1b : x2b) + (size_t)row * D + col, x4.x + g4.x * v[0], x4.y + g4.y * v[1], x4.z + g4.z * v[2], x4.w + g4.w * v[3]);
	v_and_b32_e32 v215, 0xffff0000, v213
	v_lshlrev_b32_e32 v214, 16, v213
	v_and_b32_e32 v213, 0xffff0000, v212
	v_lshlrev_b32_e32 v212, 16, v212
	v_pk_fma_f32 v[212:213], v[176:177], v[40:41], v[212:213]
	v_pk_fma_f32 v[214:215], v[178:179], v[42:43], v[214:215]
	v_and_b32_e32 v219, 0xffff0000, v217
	v_lshlrev_b32_e32 v218, 16, v217
	v_and_b32_e32 v217, 0xffff0000, v216
	v_lshlrev_b32_e32 v216, 16, v216
	v_pk_fma_f32 v[216:217], v[184:185], v[36:37], v[216:217]
	v_pk_fma_f32 v[218:219], v[186:187], v[38:39], v[218:219]
	v_and_b32_e32 v223, 0xffff0000, v221
	v_lshlrev_b32_e32 v222, 16, v221
	v_and_b32_e32 v221, 0xffff0000, v220
	v_lshlrev_b32_e32 v220, 16, v220
	v_pk_fma_f32 v[220:221], v[188:189], v[44:45], v[220:221]
	v_pk_fma_f32 v[222:223], v[190:191], v[46:47], v[222:223]
	v_and_b32_e32 v227, 0xffff0000, v225
	v_lshlrev_b32_e32 v226, 16, v225
	v_and_b32_e32 v225, 0xffff0000, v224
	v_lshlrev_b32_e32 v224, 16, v224
	v_pk_fma_f32 v[224:225], v[192:193], v[32:33], v[224:225]
	v_pk_fma_f32 v[226:227], v[194:195], v[34:35], v[226:227]
	v_cvt_pk_bf16_f32 v212, v212, v213
	v_cvt_pk_bf16_f32 v213, v214, v215
	v_cvt_pk_bf16_f32 v214, v216, v217
	v_cvt_pk_bf16_f32 v215, v218, v219
	v_cvt_pk_bf16_f32 v220, v220, v221
	v_cvt_pk_bf16_f32 v221, v222, v223
	v_cvt_pk_bf16_f32 v222, v224, v225
	v_cvt_pk_bf16_f32 v223, v226, v227
	s_add_u32 s54, s54, 0x8000
	s_addc_u32 s55, s55, 0
	v_permlane16_swap_b32_e32 v212, v214
	v_permlane16_swap_b32_e32 v213, v215
	global_store_dwordx4 v230, v[212:215], s[54:55]
	v_permlane16_swap_b32_e32 v220, v222
	v_permlane16_swap_b32_e32 v221, v223
	global_store_dwordx4 v230, v[220:223], s[54:55] offset:256
	s_nop 1
	s_add_u32 s42, s42, 0x8000
	s_addc_u32 s43, s43, 0
	global_load_dwordx2 v[212:213], v228, s[42:43]
	global_load_dwordx2 v[216:217], v228, s[42:43] offset:32
	global_load_dwordx2 v[220:221], v228, s[42:43] offset:256
	global_load_dwordx2 v[224:225], v228, s[42:43] offset:288
	s_waitcnt vmcnt(6)
	v_and_b32_e32 v199, 0xffff0000, v197
	v_lshlrev_b32_e32 v198, 16, v197
	v_and_b32_e32 v197, 0xffff0000, v196
	v_lshlrev_b32_e32 v196, 16, v196
	v_pk_fma_f32 v[196:197], v[176:177], v[20:21], v[196:197]
	v_pk_fma_f32 v[198:199], v[178:179], v[22:23], v[198:199]
	v_and_b32_e32 v203, 0xffff0000, v201
	v_lshlrev_b32_e32 v202, 16, v201
	v_and_b32_e32 v201, 0xffff0000, v200
	v_lshlrev_b32_e32 v200, 16, v200
	v_pk_fma_f32 v[200:201], v[184:185], v[16:17], v[200:201]
	v_pk_fma_f32 v[202:203], v[186:187], v[18:19], v[202:203]
	v_and_b32_e32 v207, 0xffff0000, v205
	v_lshlrev_b32_e32 v206, 16, v205
	v_and_b32_e32 v205, 0xffff0000, v204
	v_lshlrev_b32_e32 v204, 16, v204
	v_pk_fma_f32 v[204:205], v[188:189], v[28:29], v[204:205]
	v_pk_fma_f32 v[206:207], v[190:191], v[30:31], v[206:207]
	v_and_b32_e32 v211, 0xffff0000, v209
	v_lshlrev_b32_e32 v210, 16, v209
	v_and_b32_e32 v209, 0xffff0000, v208
	v_lshlrev_b32_e32 v208, 16, v208
	v_pk_fma_f32 v[208:209], v[192:193], v[24:25], v[208:209]
	v_pk_fma_f32 v[210:211], v[194:195], v[26:27], v[210:211]
	v_cvt_pk_bf16_f32 v196, v196, v197
	v_cvt_pk_bf16_f32 v197, v198, v199
	v_cvt_pk_bf16_f32 v198, v200, v201
	v_cvt_pk_bf16_f32 v199, v202, v203
	v_cvt_pk_bf16_f32 v204, v204, v205
	v_cvt_pk_bf16_f32 v205, v206, v207
	v_cvt_pk_bf16_f32 v206, v208, v209
	v_cvt_pk_bf16_f32 v207, v210, v211
	s_add_u32 s54, s54, 0x8000
	s_addc_u32 s55, s55, 0
	v_permlane16_swap_b32_e32 v196, v198
	v_permlane16_swap_b32_e32 v197, v199
	global_store_dwordx4 v230, v[196:199], s[54:55]
	v_permlane16_swap_b32_e32 v204, v206
	v_permlane16_swap_b32_e32 v205, v207
	global_store_dwordx4 v230, v[204:207], s[54:55] offset:256
	s_waitcnt vmcnt(2)
	v_and_b32_e32 v215, 0xffff0000, v213
	v_lshlrev_b32_e32 v214, 16, v213
	v_and_b32_e32 v213, 0xffff0000, v212
	v_lshlrev_b32_e32 v212, 16, v212
	v_pk_fma_f32 v[212:213], v[176:177], v[8:9], v[212:213]
	v_pk_fma_f32 v[214:215], v[178:179], v[10:11], v[214:215]
	v_and_b32_e32 v219, 0xffff0000, v217
	v_lshlrev_b32_e32 v218, 16, v217
	v_and_b32_e32 v217, 0xffff0000, v216
	v_lshlrev_b32_e32 v216, 16, v216
	v_pk_fma_f32 v[216:217], v[184:185], v[4:5], v[216:217]
	v_pk_fma_f32 v[218:219], v[186:187], v[6:7], v[218:219]
	v_and_b32_e32 v223, 0xffff0000, v221
	v_lshlrev_b32_e32 v222, 16, v221
	v_and_b32_e32 v221, 0xffff0000, v220
	v_lshlrev_b32_e32 v220, 16, v220
	v_pk_fma_f32 v[220:221], v[188:189], v[12:13], v[220:221]
	v_pk_fma_f32 v[222:223], v[190:191], v[14:15], v[222:223]
	v_and_b32_e32 v227, 0xffff0000, v225
	v_lshlrev_b32_e32 v226, 16, v225
	v_and_b32_e32 v225, 0xffff0000, v224
	v_lshlrev_b32_e32 v224, 16, v224
	v_pk_fma_f32 v[224:225], v[192:193], v[0:1], v[224:225]
	v_pk_fma_f32 v[226:227], v[194:195], v[2:3], v[226:227]
	v_cvt_pk_bf16_f32 v212, v212, v213
	v_cvt_pk_bf16_f32 v213, v214, v215
	v_cvt_pk_bf16_f32 v214, v216, v217
	v_cvt_pk_bf16_f32 v215, v218, v219
	v_cvt_pk_bf16_f32 v220, v220, v221
	v_cvt_pk_bf16_f32 v221, v222, v223
	v_cvt_pk_bf16_f32 v222, v224, v225
	v_cvt_pk_bf16_f32 v223, v226, v227
	s_add_u32 s54, s54, 0x8000
	s_addc_u32 s55, s55, 0
	v_permlane16_swap_b32_e32 v212, v214
	v_permlane16_swap_b32_e32 v213, v215
	global_store_dwordx4 v230, v[212:215], s[54:55]
	v_permlane16_swap_b32_e32 v220, v222
	v_permlane16_swap_b32_e32 v221, v223
	global_store_dwordx4 v230, v[220:223], s[54:55] offset:256
	s_cmp_eq_u32 s101, 0
	s_cbranch_scc1 .Lg5_epi_ret0
	s_branch .LBB0_2095
.Lg5_w22:
	s_waitcnt vmcnt(22)
	s_branch .Lg5_wd
.LBB0_2095:
	v_readlane_b32 s25, v251, 8
